# relax pass extended to asm-marked blocks; out-proj epilogue g_post and residual rows preloaded
# speedup vs baseline: 1.0308x; 1.0150x over previous
.LBB0_316:
	v_mov_b32_e32 v21, v185
	s_ashr_i32 s11, s10, 31
	s_lshl_b64 s[14:15], s[10:11], 11
	v_and_b32_e32 v86, 63, v21
	v_lshlrev_b32_e32 v0, 4, v21
	v_lshlrev_b32_e32 v192, 4, v86
	v_ashrrev_i32_e32 v24, 3, v21
	s_add_u32 s14, s12, s14
	v_and_b32_e32 v20, 0x70, v0
	v_lshl_add_u64 v[72:73], s[0:1], 0, v[192:193]
	s_addc_u32 s15, s13, s15
	v_lshl_or_b32 v192, v24, 11, v20
	v_lshl_add_u64 v[76:77], s[14:15], 0, v[192:193]
	v_add_co_u32_e32 v78, vcc, s17, v76
	s_waitcnt lgkmcnt(0)
	s_nop 0
	v_addc_co_u32_e32 v79, vcc, 0, v77, vcc
	v_add_co_u32_e32 v80, vcc, s18, v76
	s_barrier
	global_load_dwordx4 v[0:3], v[76:77], off
	global_load_dwordx4 v[4:7], v[78:79], off
	v_addc_co_u32_e32 v81, vcc, 0, v77, vcc
	v_add_co_u32_e32 v82, vcc, s19, v76
	global_load_dwordx4 v[8:11], v[80:81], off
	s_nop 0
	v_addc_co_u32_e32 v83, vcc, 0, v77, vcc
	global_load_dwordx4 v[12:15], v[82:83], off
	s_mov_b32 s11, 0x700000
	v_add_co_u32_e32 v22, vcc, s11, v72
	s_mov_b32 s11, 0x710000
	s_nop 0
	v_addc_co_u32_e32 v23, vcc, 0, v73, vcc
	global_load_dwordx4 v[16:19], v[22:23], off
	s_waitcnt vmcnt(5)
	global_load_dwordx4 v[64:67], v[22:23], off offset:1024
	global_load_dwordx4 v[56:59], v[22:23], off offset:2048
	global_load_dwordx4 v[32:35], v[22:23], off offset:3072
	v_add_co_u32_e32 v22, vcc, s11, v72
	v_mad_u64_u32 v[74:75], s[14:15], v24, s21, v[20:21]
	s_nop 0
	v_addc_co_u32_e32 v23, vcc, 0, v73, vcc
	global_load_dwordx4 v[88:91], v[22:23], off
	global_load_dwordx4 v[68:71], v[22:23], off offset:1024
	global_load_dwordx4 v[60:63], v[22:23], off offset:2048
	global_load_dwordx4 v[52:55], v[22:23], off offset:3072
	s_movk_i32 s11, 0xffe0
	s_waitcnt vmcnt(11)
	ds_write_b128 v74, v[0:3]
	s_waitcnt vmcnt(10)
	ds_write_b128 v74, v[4:7] offset:4608
	s_waitcnt vmcnt(9)
	ds_write_b128 v74, v[8:11] offset:9216
	s_waitcnt vmcnt(8)
	ds_write_b128 v74, v[12:15] offset:13824
	v_ashrrev_i32_e32 v0, 1, v21
	v_bfi_b32 v75, s11, v0, v21
	v_lshrrev_b32_e32 v0, 1, v21
	v_and_b32_e32 v0, 16, v0
	v_mad_u64_u32 v[84:85], s[14:15], v75, s21, v[0:1]
	global_load_dwordx4 v[36:39], v[76:77], off offset:128
	global_load_dwordx4 v[40:43], v[78:79], off offset:128
	global_load_dwordx4 v[44:47], v[80:81], off offset:128
	global_load_dwordx4 v[48:51], v[82:83], off offset:128
	s_waitcnt lgkmcnt(0)
	s_barrier
	ds_read_b128 v[0:3], v84
	s_mov_b32 s11, 0x701000
	v_add_co_u32_e32 v100, vcc, s11, v72
	s_mov_b32 s11, 0x711000
	s_nop 0
	v_addc_co_u32_e32 v101, vcc, 0, v73, vcc
	v_add_co_u32_e32 v102, vcc, s11, v72
	s_waitcnt vmcnt(11) lgkmcnt(0)
	v_mfma_f32_32x32x16_bf16 v[16:31], v[16:19], v[0:3], 0
	v_addc_co_u32_e32 v103, vcc, 0, v73, vcc
	global_load_dwordx4 v[92:95], v[100:101], off
	s_waitcnt vmcnt(8)
	v_mfma_f32_32x32x16_bf16 v[0:15], v[88:91], v[0:3], 0
	global_load_dwordx4 v[88:91], v[102:103], off
	ds_read_b128 v[96:99], v84 offset:32
	s_waitcnt lgkmcnt(0)
	v_mfma_f32_32x32x16_bf16 v[16:31], v[64:67], v[96:99], v[16:31]
	global_load_dwordx4 v[64:67], v[100:101], off offset:1024
	s_waitcnt vmcnt(9)
	v_mfma_f32_32x32x16_bf16 v[0:15], v[68:71], v[96:99], v[0:15]
	global_load_dwordx4 v[68:71], v[102:103], off offset:1024
	ds_read_b128 v[96:99], v84 offset:64
	s_waitcnt lgkmcnt(0)
	v_mfma_f32_32x32x16_bf16 v[16:31], v[56:59], v[96:99], v[16:31]
	global_load_dwordx4 v[56:59], v[100:101], off offset:2048
	s_waitcnt vmcnt(10)
	v_mfma_f32_32x32x16_bf16 v[0:15], v[60:63], v[96:99], v[0:15]
	global_load_dwordx4 v[60:63], v[102:103], off offset:2048
	ds_read_b128 v[96:99], v84 offset:96
	s_waitcnt lgkmcnt(0)
	v_mfma_f32_32x32x16_bf16 v[16:31], v[32:35], v[96:99], v[16:31]
	global_load_dwordx4 v[32:35], v[100:101], off offset:3072
	s_waitcnt vmcnt(11)
	v_mfma_f32_32x32x16_bf16 v[0:15], v[52:55], v[96:99], v[0:15]
	global_load_dwordx4 v[52:55], v[102:103], off offset:3072
	s_waitcnt vmcnt(11)
	ds_write_b128 v74, v[36:39] offset:18432
	s_waitcnt vmcnt(10)
	ds_write_b128 v74, v[40:43] offset:23040
	s_waitcnt vmcnt(9)
	ds_write_b128 v74, v[44:47] offset:27648
	s_waitcnt vmcnt(8)
	ds_write_b128 v74, v[48:51] offset:32256
	global_load_dwordx4 v[36:39], v[76:77], off offset:256
	global_load_dwordx4 v[40:43], v[78:79], off offset:256
	global_load_dwordx4 v[44:47], v[80:81], off offset:256
	global_load_dwordx4 v[48:51], v[82:83], off offset:256
	s_waitcnt lgkmcnt(0)
	s_barrier
	ds_read_b128 v[96:99], v84 offset:18432
	s_mov_b32 s11, 0x702000
	v_add_co_u32_e32 v100, vcc, s11, v72
	s_mov_b32 s11, 0x712000
	s_nop 0
	v_addc_co_u32_e32 v101, vcc, 0, v73, vcc
	v_add_co_u32_e32 v102, vcc, s11, v72
	s_waitcnt vmcnt(11) lgkmcnt(0)
	v_mfma_f32_32x32x16_bf16 v[16:31], v[92:95], v[96:99], v[16:31]
	v_addc_co_u32_e32 v103, vcc, 0, v73, vcc
	global_load_dwordx4 v[92:95], v[100:101], off
	s_waitcnt vmcnt(11)
	v_mfma_f32_32x32x16_bf16 v[0:15], v[88:91], v[96:99], v[0:15]
	global_load_dwordx4 v[88:91], v[102:103], off
	ds_read_b128 v[96:99], v84 offset:18464
	s_waitcnt vmcnt(11) lgkmcnt(0)
	v_mfma_f32_32x32x16_bf16 v[16:31], v[64:67], v[96:99], v[16:31]
	global_load_dwordx4 v[64:67], v[100:101], off offset:1024
	s_waitcnt vmcnt(11)
	v_mfma_f32_32x32x16_bf16 v[0:15], v[68:71], v[96:99], v[0:15]
	global_load_dwordx4 v[68:71], v[102:103], off offset:1024
	ds_read_b128 v[96:99], v84 offset:18496
	s_waitcnt vmcnt(11) lgkmcnt(0)
	v_mfma_f32_32x32x16_bf16 v[16:31], v[56:59], v[96:99], v[16:31]
	global_load_dwordx4 v[56:59], v[100:101], off offset:2048
	s_waitcnt vmcnt(11)
	v_mfma_f32_32x32x16_bf16 v[0:15], v[60:63], v[96:99], v[0:15]
	global_load_dwordx4 v[60:63], v[102:103], off offset:2048
	ds_read_b128 v[96:99], v84 offset:18528
	s_waitcnt vmcnt(11) lgkmcnt(0)
	v_mfma_f32_32x32x16_bf16 v[16:31], v[32:35], v[96:99], v[16:31]
	global_load_dwordx4 v[32:35], v[100:101], off offset:3072
	s_waitcnt vmcnt(11)
	v_mfma_f32_32x32x16_bf16 v[0:15], v[52:55], v[96:99], v[0:15]
	global_load_dwordx4 v[52:55], v[102:103], off offset:3072
	s_waitcnt vmcnt(11)
	ds_write_b128 v74, v[36:39]
	s_waitcnt vmcnt(10)
	ds_write_b128 v74, v[40:43] offset:4608
	s_waitcnt vmcnt(9)
	ds_write_b128 v74, v[44:47] offset:9216
	s_waitcnt vmcnt(8)
	ds_write_b128 v74, v[48:51] offset:13824
	global_load_dwordx4 v[36:39], v[82:83], off offset:384
	global_load_dwordx4 v[40:43], v[80:81], off offset:384
	global_load_dwordx4 v[44:47], v[78:79], off offset:384
	global_load_dwordx4 v[48:51], v[76:77], off offset:384
	s_waitcnt lgkmcnt(0)
	s_barrier
	ds_read_b128 v[96:99], v84
	s_mov_b32 s11, 0x703000
	v_add_co_u32_e32 v100, vcc, s11, v72
	s_mov_b32 s11, 0x713000
	s_nop 0
	v_addc_co_u32_e32 v101, vcc, 0, v73, vcc
	v_add_co_u32_e32 v102, vcc, s11, v72
	s_waitcnt vmcnt(11) lgkmcnt(0)
	v_mfma_f32_32x32x16_bf16 v[16:31], v[92:95], v[96:99], v[16:31]
	v_addc_co_u32_e32 v103, vcc, 0, v73, vcc
	global_load_dwordx4 v[92:95], v[100:101], off
	s_waitcnt vmcnt(11)
	v_mfma_f32_32x32x16_bf16 v[0:15], v[88:91], v[96:99], v[0:15]
	global_load_dwordx4 v[88:91], v[102:103], off
	ds_read_b128 v[96:99], v84 offset:32
	s_waitcnt vmcnt(11) lgkmcnt(0)
	v_mfma_f32_32x32x16_bf16 v[16:31], v[64:67], v[96:99], v[16:31]
	global_load_dwordx4 v[64:67], v[100:101], off offset:1024
	s_waitcnt vmcnt(11)
	v_mfma_f32_32x32x16_bf16 v[0:15], v[68:71], v[96:99], v[0:15]
	global_load_dwordx4 v[68:71], v[102:103], off offset:1024
	ds_read_b128 v[96:99], v84 offset:64
	s_waitcnt vmcnt(11) lgkmcnt(0)
	v_mfma_f32_32x32x16_bf16 v[16:31], v[56:59], v[96:99], v[16:31]
	global_load_dwordx4 v[56:59], v[100:101], off offset:2048
	s_waitcnt vmcnt(11)
	v_mfma_f32_32x32x16_bf16 v[0:15], v[60:63], v[96:99], v[0:15]
	global_load_dwordx4 v[60:63], v[102:103], off offset:2048
	ds_read_b128 v[96:99], v84 offset:96
	s_waitcnt vmcnt(11) lgkmcnt(0)
	v_mfma_f32_32x32x16_bf16 v[16:31], v[32:35], v[96:99], v[16:31]
	global_load_dwordx4 v[32:35], v[100:101], off offset:3072
	s_waitcnt vmcnt(11)
	v_mfma_f32_32x32x16_bf16 v[0:15], v[52:55], v[96:99], v[0:15]
	global_load_dwordx4 v[52:55], v[102:103], off offset:3072
	s_waitcnt vmcnt(8)
	ds_write_b128 v74, v[48:51] offset:18432
	ds_write_b128 v74, v[44:47] offset:23040
	ds_write_b128 v74, v[40:43] offset:27648
	ds_write_b128 v74, v[36:39] offset:32256
	global_load_dwordx4 v[36:39], v[76:77], off offset:512
	global_load_dwordx4 v[40:43], v[78:79], off offset:512
	global_load_dwordx4 v[44:47], v[80:81], off offset:512
	global_load_dwordx4 v[48:51], v[82:83], off offset:512
	s_waitcnt lgkmcnt(0)
	s_barrier
	ds_read_b128 v[96:99], v84 offset:18432
	s_mov_b32 s11, 0x704000
	v_add_co_u32_e32 v100, vcc, s11, v72
	s_mov_b32 s11, 0x714000
	s_nop 0
	v_addc_co_u32_e32 v101, vcc, 0, v73, vcc
	v_add_co_u32_e32 v102, vcc, s11, v72
	s_waitcnt vmcnt(11) lgkmcnt(0)
	v_mfma_f32_32x32x16_bf16 v[16:31], v[92:95], v[96:99], v[16:31]
	v_addc_co_u32_e32 v103, vcc, 0, v73, vcc
	global_load_dwordx4 v[92:95], v[100:101], off
	s_waitcnt vmcnt(11)
	v_mfma_f32_32x32x16_bf16 v[0:15], v[88:91], v[96:99], v[0:15]
	global_load_dwordx4 v[88:91], v[102:103], off
	ds_read_b128 v[96:99], v84 offset:18464
	s_waitcnt vmcnt(11) lgkmcnt(0)
	v_mfma_f32_32x32x16_bf16 v[16:31], v[64:67], v[96:99], v[16:31]
	global_load_dwordx4 v[64:67], v[100:101], off offset:1024
	s_waitcnt vmcnt(11)
	v_mfma_f32_32x32x16_bf16 v[0:15], v[68:71], v[96:99], v[0:15]
	global_load_dwordx4 v[68:71], v[102:103], off offset:1024
	ds_read_b128 v[96:99], v84 offset:18496
	s_waitcnt vmcnt(11) lgkmcnt(0)
	v_mfma_f32_32x32x16_bf16 v[16:31], v[56:59], v[96:99], v[16:31]
	global_load_dwordx4 v[56:59], v[100:101], off offset:2048
	s_waitcnt vmcnt(11)
	v_mfma_f32_32x32x16_bf16 v[0:15], v[60:63], v[96:99], v[0:15]
	global_load_dwordx4 v[60:63], v[102:103], off offset:2048
	ds_read_b128 v[96:99], v84 offset:18528
	s_waitcnt vmcnt(11) lgkmcnt(0)
	v_mfma_f32_32x32x16_bf16 v[16:31], v[32:35], v[96:99], v[16:31]
	global_load_dwordx4 v[32:35], v[100:101], off offset:3072
	s_waitcnt vmcnt(11)
	v_mfma_f32_32x32x16_bf16 v[0:15], v[52:55], v[96:99], v[0:15]
	global_load_dwordx4 v[52:55], v[102:103], off offset:3072
	s_waitcnt vmcnt(11)
	ds_write_b128 v74, v[36:39]
	s_waitcnt vmcnt(10)
	ds_write_b128 v74, v[40:43] offset:4608
	s_waitcnt vmcnt(9)
	ds_write_b128 v74, v[44:47] offset:9216
	s_waitcnt vmcnt(8)
	ds_write_b128 v74, v[48:51] offset:13824
	global_load_dwordx4 v[36:39], v[82:83], off offset:640
	global_load_dwordx4 v[40:43], v[80:81], off offset:640
	global_load_dwordx4 v[44:47], v[78:79], off offset:640
	global_load_dwordx4 v[48:51], v[76:77], off offset:640
	s_waitcnt lgkmcnt(0)
	s_barrier
	ds_read_b128 v[96:99], v84
	s_mov_b32 s11, 0x705000
	v_add_co_u32_e32 v100, vcc, s11, v72
	s_mov_b32 s11, 0x715000
	s_nop 0
	v_addc_co_u32_e32 v101, vcc, 0, v73, vcc
	v_add_co_u32_e32 v102, vcc, s11, v72
	s_waitcnt vmcnt(11) lgkmcnt(0)
	v_mfma_f32_32x32x16_bf16 v[16:31], v[92:95], v[96:99], v[16:31]
	v_addc_co_u32_e32 v103, vcc, 0, v73, vcc
	global_load_dwordx4 v[92:95], v[100:101], off
	s_waitcnt vmcnt(11)
	v_mfma_f32_32x32x16_bf16 v[0:15], v[88:91], v[96:99], v[0:15]
	global_load_dwordx4 v[88:91], v[102:103], off
	ds_read_b128 v[96:99], v84 offset:32
	s_waitcnt vmcnt(11) lgkmcnt(0)
	v_mfma_f32_32x32x16_bf16 v[16:31], v[64:67], v[96:99], v[16:31]
	global_load_dwordx4 v[64:67], v[100:101], off offset:1024
	s_waitcnt vmcnt(11)
	v_mfma_f32_32x32x16_bf16 v[0:15], v[68:71], v[96:99], v[0:15]
	global_load_dwordx4 v[68:71], v[102:103], off offset:1024
	ds_read_b128 v[96:99], v84 offset:64
	s_waitcnt vmcnt(11) lgkmcnt(0)
	v_mfma_f32_32x32x16_bf16 v[16:31], v[56:59], v[96:99], v[16:31]
	global_load_dwordx4 v[56:59], v[100:101], off offset:2048
	s_waitcnt vmcnt(11)
	v_mfma_f32_32x32x16_bf16 v[0:15], v[60:63], v[96:99], v[0:15]
	global_load_dwordx4 v[60:63], v[102:103], off offset:2048
	ds_read_b128 v[96:99], v84 offset:96
	s_waitcnt vmcnt(11) lgkmcnt(0)
	v_mfma_f32_32x32x16_bf16 v[16:31], v[32:35], v[96:99], v[16:31]
	global_load_dwordx4 v[32:35], v[100:101], off offset:3072
	s_waitcnt vmcnt(11)
	v_mfma_f32_32x32x16_bf16 v[0:15], v[52:55], v[96:99], v[0:15]
	global_load_dwordx4 v[52:55], v[102:103], off offset:3072
	s_waitcnt vmcnt(8)
	ds_write_b128 v74, v[48:51] offset:18432
	ds_write_b128 v74, v[44:47] offset:23040
	ds_write_b128 v74, v[40:43] offset:27648
	ds_write_b128 v74, v[36:39] offset:32256
	global_load_dwordx4 v[36:39], v[76:77], off offset:768
	global_load_dwordx4 v[40:43], v[78:79], off offset:768
	global_load_dwordx4 v[44:47], v[80:81], off offset:768
	global_load_dwordx4 v[48:51], v[82:83], off offset:768
	s_waitcnt lgkmcnt(0)
	s_barrier
	ds_read_b128 v[96:99], v84 offset:18432
	s_mov_b32 s11, 0x706000
	v_add_co_u32_e32 v100, vcc, s11, v72
	s_mov_b32 s11, 0x716000
	s_nop 0
	v_addc_co_u32_e32 v101, vcc, 0, v73, vcc
	v_add_co_u32_e32 v102, vcc, s11, v72
	s_waitcnt vmcnt(11) lgkmcnt(0)
	v_mfma_f32_32x32x16_bf16 v[16:31], v[92:95], v[96:99], v[16:31]
	v_addc_co_u32_e32 v103, vcc, 0, v73, vcc
	global_load_dwordx4 v[92:95], v[100:101], off
	s_waitcnt vmcnt(11)
	v_mfma_f32_32x32x16_bf16 v[0:15], v[88:91], v[96:99], v[0:15]
	global_load_dwordx4 v[88:91], v[102:103], off
	ds_read_b128 v[96:99], v84 offset:18464
	s_waitcnt vmcnt(11) lgkmcnt(0)
	v_mfma_f32_32x32x16_bf16 v[16:31], v[64:67], v[96:99], v[16:31]
	global_load_dwordx4 v[64:67], v[100:101], off offset:1024
	s_waitcnt vmcnt(11)
	v_mfma_f32_32x32x16_bf16 v[0:15], v[68:71], v[96:99], v[0:15]
	global_load_dwordx4 v[68:71], v[102:103], off offset:1024
	ds_read_b128 v[96:99], v84 offset:18496
	s_waitcnt vmcnt(11) lgkmcnt(0)
	v_mfma_f32_32x32x16_bf16 v[16:31], v[56:59], v[96:99], v[16:31]
	global_load_dwordx4 v[56:59], v[100:101], off offset:2048
	s_waitcnt vmcnt(11)
	v_mfma_f32_32x32x16_bf16 v[0:15], v[60:63], v[96:99], v[0:15]
	global_load_dwordx4 v[60:63], v[102:103], off offset:2048
	ds_read_b128 v[96:99], v84 offset:18528
	s_waitcnt vmcnt(11) lgkmcnt(0)
	v_mfma_f32_32x32x16_bf16 v[16:31], v[32:35], v[96:99], v[16:31]
	global_load_dwordx4 v[32:35], v[100:101], off offset:3072
	s_waitcnt vmcnt(11)
	v_mfma_f32_32x32x16_bf16 v[0:15], v[52:55], v[96:99], v[0:15]
	global_load_dwordx4 v[52:55], v[102:103], off offset:3072
	s_waitcnt vmcnt(11)
	ds_write_b128 v74, v[36:39]
	s_waitcnt vmcnt(10)
	ds_write_b128 v74, v[40:43] offset:4608
	s_waitcnt vmcnt(9)
	ds_write_b128 v74, v[44:47] offset:9216
	s_waitcnt vmcnt(8)
	ds_write_b128 v74, v[48:51] offset:13824
	global_load_dwordx4 v[36:39], v[82:83], off offset:896
	global_load_dwordx4 v[40:43], v[80:81], off offset:896
	global_load_dwordx4 v[44:47], v[78:79], off offset:896
	global_load_dwordx4 v[48:51], v[76:77], off offset:896
	s_waitcnt lgkmcnt(0)
	s_barrier
	ds_read_b128 v[96:99], v84
	s_mov_b32 s11, 0x707000
	v_add_co_u32_e32 v100, vcc, s11, v72
	s_mov_b32 s11, 0x717000
	s_nop 0
	v_addc_co_u32_e32 v101, vcc, 0, v73, vcc
	v_add_co_u32_e32 v102, vcc, s11, v72
	s_waitcnt vmcnt(11) lgkmcnt(0)
	v_mfma_f32_32x32x16_bf16 v[16:31], v[92:95], v[96:99], v[16:31]
	v_addc_co_u32_e32 v103, vcc, 0, v73, vcc
	global_load_dwordx4 v[92:95], v[100:101], off
	s_waitcnt vmcnt(11)
	v_mfma_f32_32x32x16_bf16 v[0:15], v[88:91], v[96:99], v[0:15]
	global_load_dwordx4 v[88:91], v[102:103], off
	ds_read_b128 v[96:99], v84 offset:32
	s_waitcnt vmcnt(11) lgkmcnt(0)
	v_mfma_f32_32x32x16_bf16 v[16:31], v[64:67], v[96:99], v[16:31]
	global_load_dwordx4 v[64:67], v[100:101], off offset:1024
	s_waitcnt vmcnt(11)
	v_mfma_f32_32x32x16_bf16 v[0:15], v[68:71], v[96:99], v[0:15]
	global_load_dwordx4 v[68:71], v[102:103], off offset:1024
	ds_read_b128 v[96:99], v84 offset:64
	s_waitcnt vmcnt(11) lgkmcnt(0)
	v_mfma_f32_32x32x16_bf16 v[16:31], v[56:59], v[96:99], v[16:31]
	global_load_dwordx4 v[56:59], v[100:101], off offset:2048
	s_waitcnt vmcnt(11)
	v_mfma_f32_32x32x16_bf16 v[0:15], v[60:63], v[96:99], v[0:15]
	global_load_dwordx4 v[60:63], v[102:103], off offset:2048
	ds_read_b128 v[96:99], v84 offset:96
	s_waitcnt vmcnt(11) lgkmcnt(0)
	v_mfma_f32_32x32x16_bf16 v[16:31], v[32:35], v[96:99], v[16:31]
	global_load_dwordx4 v[32:35], v[100:101], off offset:3072
	s_waitcnt vmcnt(11)
	v_mfma_f32_32x32x16_bf16 v[0:15], v[52:55], v[96:99], v[0:15]
	global_load_dwordx4 v[52:55], v[102:103], off offset:3072
	s_waitcnt vmcnt(8)
	ds_write_b128 v74, v[48:51] offset:18432
	ds_write_b128 v74, v[44:47] offset:23040
	ds_write_b128 v74, v[40:43] offset:27648
	ds_write_b128 v74, v[36:39] offset:32256
	global_load_dwordx4 v[36:39], v[76:77], off offset:1024
	global_load_dwordx4 v[40:43], v[78:79], off offset:1024
	global_load_dwordx4 v[44:47], v[80:81], off offset:1024
	global_load_dwordx4 v[48:51], v[82:83], off offset:1024
	s_waitcnt lgkmcnt(0)
	s_barrier
	ds_read_b128 v[96:99], v84 offset:18432
	s_mov_b32 s11, 0x708000
	v_add_co_u32_e32 v100, vcc, s11, v72
	s_mov_b32 s11, 0x718000
	s_nop 0
	v_addc_co_u32_e32 v101, vcc, 0, v73, vcc
	v_add_co_u32_e32 v102, vcc, s11, v72
	s_waitcnt vmcnt(11) lgkmcnt(0)
	v_mfma_f32_32x32x16_bf16 v[16:31], v[92:95], v[96:99], v[16:31]
	v_addc_co_u32_e32 v103, vcc, 0, v73, vcc
	global_load_dwordx4 v[92:95], v[100:101], off
	s_waitcnt vmcnt(11)
	v_mfma_f32_32x32x16_bf16 v[0:15], v[88:91], v[96:99], v[0:15]
	global_load_dwordx4 v[88:91], v[102:103], off
	ds_read_b128 v[96:99], v84 offset:18464
	s_waitcnt vmcnt(11) lgkmcnt(0)
	v_mfma_f32_32x32x16_bf16 v[16:31], v[64:67], v[96:99], v[16:31]
	global_load_dwordx4 v[64:67], v[100:101], off offset:1024
	s_waitcnt vmcnt(11)
	v_mfma_f32_32x32x16_bf16 v[0:15], v[68:71], v[96:99], v[0:15]
	global_load_dwordx4 v[68:71], v[102:103], off offset:1024
	ds_read_b128 v[96:99], v84 offset:18496
	s_waitcnt vmcnt(11) lgkmcnt(0)
	v_mfma_f32_32x32x16_bf16 v[16:31], v[56:59], v[96:99], v[16:31]
	global_load_dwordx4 v[56:59], v[100:101], off offset:2048
	s_waitcnt vmcnt(11)
	v_mfma_f32_32x32x16_bf16 v[0:15], v[60:63], v[96:99], v[0:15]
	global_load_dwordx4 v[60:63], v[102:103], off offset:2048
	ds_read_b128 v[96:99], v84 offset:18528
	s_waitcnt vmcnt(11) lgkmcnt(0)
	v_mfma_f32_32x32x16_bf16 v[16:31], v[32:35], v[96:99], v[16:31]
	global_load_dwordx4 v[32:35], v[100:101], off offset:3072
	s_waitcnt vmcnt(11)
	v_mfma_f32_32x32x16_bf16 v[0:15], v[52:55], v[96:99], v[0:15]
	global_load_dwordx4 v[52:55], v[102:103], off offset:3072
	s_waitcnt vmcnt(11)
	ds_write_b128 v74, v[36:39]
	s_waitcnt vmcnt(10)
	ds_write_b128 v74, v[40:43] offset:4608
	s_waitcnt vmcnt(9)
	ds_write_b128 v74, v[44:47] offset:9216
	s_waitcnt vmcnt(8)
	ds_write_b128 v74, v[48:51] offset:13824
	global_load_dwordx4 v[36:39], v[82:83], off offset:1152
	global_load_dwordx4 v[40:43], v[80:81], off offset:1152
	global_load_dwordx4 v[44:47], v[78:79], off offset:1152
	global_load_dwordx4 v[48:51], v[76:77], off offset:1152
	s_waitcnt lgkmcnt(0)
	s_barrier
	ds_read_b128 v[96:99], v84
	s_mov_b32 s11, 0x709000
	v_add_co_u32_e32 v100, vcc, s11, v72
	s_mov_b32 s11, 0x719000
	s_nop 0
	v_addc_co_u32_e32 v101, vcc, 0, v73, vcc
	v_add_co_u32_e32 v102, vcc, s11, v72
	s_waitcnt vmcnt(11) lgkmcnt(0)
	v_mfma_f32_32x32x16_bf16 v[16:31], v[92:95], v[96:99], v[16:31]
	v_addc_co_u32_e32 v103, vcc, 0, v73, vcc
	global_load_dwordx4 v[92:95], v[100:101], off
	s_waitcnt vmcnt(11)
	v_mfma_f32_32x32x16_bf16 v[0:15], v[88:91], v[96:99], v[0:15]
	global_load_dwordx4 v[88:91], v[102:103], off
	ds_read_b128 v[96:99], v84 offset:32
	s_waitcnt vmcnt(11) lgkmcnt(0)
	v_mfma_f32_32x32x16_bf16 v[16:31], v[64:67], v[96:99], v[16:31]
	global_load_dwordx4 v[64:67], v[100:101], off offset:1024
	s_waitcnt vmcnt(11)
	v_mfma_f32_32x32x16_bf16 v[0:15], v[68:71], v[96:99], v[0:15]
	global_load_dwordx4 v[68:71], v[102:103], off offset:1024
	ds_read_b128 v[96:99], v84 offset:64
	s_waitcnt vmcnt(11) lgkmcnt(0)
	v_mfma_f32_32x32x16_bf16 v[16:31], v[56:59], v[96:99], v[16:31]
	global_load_dwordx4 v[56:59], v[100:101], off offset:2048
	s_waitcnt vmcnt(11)
	v_mfma_f32_32x32x16_bf16 v[0:15], v[60:63], v[96:99], v[0:15]
	global_load_dwordx4 v[60:63], v[102:103], off offset:2048
	ds_read_b128 v[96:99], v84 offset:96
	s_waitcnt vmcnt(11) lgkmcnt(0)
	v_mfma_f32_32x32x16_bf16 v[16:31], v[32:35], v[96:99], v[16:31]
	global_load_dwordx4 v[32:35], v[100:101], off offset:3072
	s_waitcnt vmcnt(11)
	v_mfma_f32_32x32x16_bf16 v[0:15], v[52:55], v[96:99], v[0:15]
	global_load_dwordx4 v[52:55], v[102:103], off offset:3072
	s_waitcnt vmcnt(8)
	ds_write_b128 v74, v[48:51] offset:18432
	ds_write_b128 v74, v[44:47] offset:23040
	ds_write_b128 v74, v[40:43] offset:27648
	ds_write_b128 v74, v[36:39] offset:32256
	global_load_dwordx4 v[36:39], v[76:77], off offset:1280
	global_load_dwordx4 v[40:43], v[78:79], off offset:1280
	global_load_dwordx4 v[44:47], v[80:81], off offset:1280
	global_load_dwordx4 v[48:51], v[82:83], off offset:1280
	s_waitcnt lgkmcnt(0)
	s_barrier
	ds_read_b128 v[96:99], v84 offset:18432
	s_mov_b32 s11, 0x70a000
	v_add_co_u32_e32 v100, vcc, s11, v72
	s_mov_b32 s11, 0x71a000
	s_nop 0
	v_addc_co_u32_e32 v101, vcc, 0, v73, vcc
	v_add_co_u32_e32 v102, vcc, s11, v72
	s_waitcnt vmcnt(11) lgkmcnt(0)
	v_mfma_f32_32x32x16_bf16 v[16:31], v[92:95], v[96:99], v[16:31]
	v_addc_co_u32_e32 v103, vcc, 0, v73, vcc
	global_load_dwordx4 v[92:95], v[100:101], off
	s_waitcnt vmcnt(11)
	v_mfma_f32_32x32x16_bf16 v[0:15], v[88:91], v[96:99], v[0:15]
	global_load_dwordx4 v[88:91], v[102:103], off
	ds_read_b128 v[96:99], v84 offset:18464
	s_waitcnt vmcnt(11) lgkmcnt(0)
	v_mfma_f32_32x32x16_bf16 v[16:31], v[64:67], v[96:99], v[16:31]
	global_load_dwordx4 v[64:67], v[100:101], off offset:1024
	s_waitcnt vmcnt(11)
	v_mfma_f32_32x32x16_bf16 v[0:15], v[68:71], v[96:99], v[0:15]
	global_load_dwordx4 v[68:71], v[102:103], off offset:1024
	ds_read_b128 v[96:99], v84 offset:18496
	s_waitcnt vmcnt(11) lgkmcnt(0)
	v_mfma_f32_32x32x16_bf16 v[16:31], v[56:59], v[96:99], v[16:31]
	global_load_dwordx4 v[56:59], v[100:101], off offset:2048
	s_waitcnt vmcnt(11)
	v_mfma_f32_32x32x16_bf16 v[0:15], v[60:63], v[96:99], v[0:15]
	global_load_dwordx4 v[60:63], v[102:103], off offset:2048
	ds_read_b128 v[96:99], v84 offset:18528
	s_waitcnt vmcnt(11) lgkmcnt(0)
	v_mfma_f32_32x32x16_bf16 v[16:31], v[32:35], v[96:99], v[16:31]
	global_load_dwordx4 v[32:35], v[100:101], off offset:3072
	s_waitcnt vmcnt(11)
	v_mfma_f32_32x32x16_bf16 v[0:15], v[52:55], v[96:99], v[0:15]
	global_load_dwordx4 v[52:55], v[102:103], off offset:3072
	s_waitcnt vmcnt(11)
	ds_write_b128 v74, v[36:39]
	s_waitcnt vmcnt(10)
	ds_write_b128 v74, v[40:43] offset:4608
	s_waitcnt vmcnt(9)
	ds_write_b128 v74, v[44:47] offset:9216
	s_waitcnt vmcnt(8)
	ds_write_b128 v74, v[48:51] offset:13824
	global_load_dwordx4 v[36:39], v[82:83], off offset:1408
	global_load_dwordx4 v[40:43], v[80:81], off offset:1408
	global_load_dwordx4 v[44:47], v[78:79], off offset:1408
	global_load_dwordx4 v[48:51], v[76:77], off offset:1408
	s_waitcnt lgkmcnt(0)
	s_barrier
	ds_read_b128 v[96:99], v84
	s_mov_b32 s11, 0x70b000
	v_add_co_u32_e32 v100, vcc, s11, v72
	s_mov_b32 s11, 0x71b000
	s_nop 0
	v_addc_co_u32_e32 v101, vcc, 0, v73, vcc
	v_add_co_u32_e32 v102, vcc, s11, v72
	s_waitcnt vmcnt(11) lgkmcnt(0)
	v_mfma_f32_32x32x16_bf16 v[16:31], v[92:95], v[96:99], v[16:31]
	v_addc_co_u32_e32 v103, vcc, 0, v73, vcc
	global_load_dwordx4 v[92:95], v[100:101], off
	s_waitcnt vmcnt(11)
	v_mfma_f32_32x32x16_bf16 v[0:15], v[88:91], v[96:99], v[0:15]
	global_load_dwordx4 v[88:91], v[102:103], off
	ds_read_b128 v[96:99], v84 offset:32
	s_waitcnt vmcnt(11) lgkmcnt(0)
	v_mfma_f32_32x32x16_bf16 v[16:31], v[64:67], v[96:99], v[16:31]
	global_load_dwordx4 v[64:67], v[100:101], off offset:1024
	s_waitcnt vmcnt(11)
	v_mfma_f32_32x32x16_bf16 v[0:15], v[68:71], v[96:99], v[0:15]
	global_load_dwordx4 v[68:71], v[102:103], off offset:1024
	ds_read_b128 v[96:99], v84 offset:64
	s_waitcnt vmcnt(11) lgkmcnt(0)
	v_mfma_f32_32x32x16_bf16 v[16:31], v[56:59], v[96:99], v[16:31]
	global_load_dwordx4 v[56:59], v[100:101], off offset:2048
	s_waitcnt vmcnt(11)
	v_mfma_f32_32x32x16_bf16 v[0:15], v[60:63], v[96:99], v[0:15]
	global_load_dwordx4 v[60:63], v[102:103], off offset:2048
	ds_read_b128 v[96:99], v84 offset:96
	s_waitcnt vmcnt(11) lgkmcnt(0)
	v_mfma_f32_32x32x16_bf16 v[16:31], v[32:35], v[96:99], v[16:31]
	global_load_dwordx4 v[32:35], v[100:101], off offset:3072
	s_waitcnt vmcnt(11)
	v_mfma_f32_32x32x16_bf16 v[0:15], v[52:55], v[96:99], v[0:15]
	global_load_dwordx4 v[52:55], v[102:103], off offset:3072
	s_waitcnt vmcnt(8)
	ds_write_b128 v74, v[48:51] offset:18432
	ds_write_b128 v74, v[44:47] offset:23040
	ds_write_b128 v74, v[40:43] offset:27648
	ds_write_b128 v74, v[36:39] offset:32256
	global_load_dwordx4 v[36:39], v[76:77], off offset:1536
	global_load_dwordx4 v[40:43], v[78:79], off offset:1536
	global_load_dwordx4 v[44:47], v[80:81], off offset:1536
	global_load_dwordx4 v[48:51], v[82:83], off offset:1536
	s_waitcnt lgkmcnt(0)
	s_barrier
	ds_read_b128 v[96:99], v84 offset:18432
	s_mov_b32 s11, 0x70c000
	v_add_co_u32_e32 v100, vcc, s11, v72
	s_mov_b32 s11, 0x71c000
	s_nop 0
	v_addc_co_u32_e32 v101, vcc, 0, v73, vcc
	v_add_co_u32_e32 v102, vcc, s11, v72
	s_waitcnt vmcnt(11) lgkmcnt(0)
	v_mfma_f32_32x32x16_bf16 v[16:31], v[92:95], v[96:99], v[16:31]
	v_addc_co_u32_e32 v103, vcc, 0, v73, vcc
	global_load_dwordx4 v[92:95], v[100:101], off
	s_waitcnt vmcnt(11)
	v_mfma_f32_32x32x16_bf16 v[0:15], v[88:91], v[96:99], v[0:15]
	global_load_dwordx4 v[88:91], v[102:103], off
	ds_read_b128 v[96:99], v84 offset:18464
	s_waitcnt vmcnt(11) lgkmcnt(0)
	v_mfma_f32_32x32x16_bf16 v[16:31], v[64:67], v[96:99], v[16:31]
	global_load_dwordx4 v[64:67], v[100:101], off offset:1024
	s_waitcnt vmcnt(11)
	v_mfma_f32_32x32x16_bf16 v[0:15], v[68:71], v[96:99], v[0:15]
	global_load_dwordx4 v[68:71], v[102:103], off offset:1024
	ds_read_b128 v[96:99], v84 offset:18496
	s_waitcnt vmcnt(11) lgkmcnt(0)
	v_mfma_f32_32x32x16_bf16 v[16:31], v[56:59], v[96:99], v[16:31]
	global_load_dwordx4 v[56:59], v[100:101], off offset:2048
	s_waitcnt vmcnt(11)
	v_mfma_f32_32x32x16_bf16 v[0:15], v[60:63], v[96:99], v[0:15]
	global_load_dwordx4 v[60:63], v[102:103], off offset:2048
	ds_read_b128 v[96:99], v84 offset:18528
	s_waitcnt vmcnt(11) lgkmcnt(0)
	v_mfma_f32_32x32x16_bf16 v[16:31], v[32:35], v[96:99], v[16:31]
	global_load_dwordx4 v[32:35], v[100:101], off offset:3072
	s_waitcnt vmcnt(11)
	v_mfma_f32_32x32x16_bf16 v[0:15], v[52:55], v[96:99], v[0:15]
	global_load_dwordx4 v[52:55], v[102:103], off offset:3072
	s_waitcnt vmcnt(11)
	ds_write_b128 v74, v[36:39]
	s_waitcnt vmcnt(10)
	ds_write_b128 v74, v[40:43] offset:4608
	s_waitcnt vmcnt(9)
	ds_write_b128 v74, v[44:47] offset:9216
	s_waitcnt vmcnt(8)
	ds_write_b128 v74, v[48:51] offset:13824
	global_load_dwordx4 v[36:39], v[82:83], off offset:1664
	global_load_dwordx4 v[40:43], v[80:81], off offset:1664
	global_load_dwordx4 v[44:47], v[78:79], off offset:1664
	global_load_dwordx4 v[48:51], v[76:77], off offset:1664
	s_waitcnt lgkmcnt(0)
	s_barrier
	ds_read_b128 v[96:99], v84
	s_mov_b32 s11, 0x70d000
	v_add_co_u32_e32 v100, vcc, s11, v72
	s_mov_b32 s11, 0x71d000
	s_nop 0
	v_addc_co_u32_e32 v101, vcc, 0, v73, vcc
	v_add_co_u32_e32 v102, vcc, s11, v72
	s_waitcnt vmcnt(11) lgkmcnt(0)
	v_mfma_f32_32x32x16_bf16 v[16:31], v[92:95], v[96:99], v[16:31]
	v_addc_co_u32_e32 v103, vcc, 0, v73, vcc
	global_load_dwordx4 v[92:95], v[100:101], off
	s_waitcnt vmcnt(11)
	v_mfma_f32_32x32x16_bf16 v[0:15], v[88:91], v[96:99], v[0:15]
	global_load_dwordx4 v[88:91], v[102:103], off
	ds_read_b128 v[96:99], v84 offset:32
	s_waitcnt vmcnt(11) lgkmcnt(0)
	v_mfma_f32_32x32x16_bf16 v[16:31], v[64:67], v[96:99], v[16:31]
	global_load_dwordx4 v[64:67], v[100:101], off offset:1024
	s_waitcnt vmcnt(11)
	v_mfma_f32_32x32x16_bf16 v[0:15], v[68:71], v[96:99], v[0:15]
	global_load_dwordx4 v[68:71], v[102:103], off offset:1024
	ds_read_b128 v[96:99], v84 offset:64
	s_waitcnt vmcnt(11) lgkmcnt(0)
	v_mfma_f32_32x32x16_bf16 v[16:31], v[56:59], v[96:99], v[16:31]
	global_load_dwordx4 v[56:59], v[100:101], off offset:2048
	s_waitcnt vmcnt(11)
	v_mfma_f32_32x32x16_bf16 v[0:15], v[60:63], v[96:99], v[0:15]
	global_load_dwordx4 v[60:63], v[102:103], off offset:2048
	ds_read_b128 v[96:99], v84 offset:96
	s_waitcnt vmcnt(11) lgkmcnt(0)
	v_mfma_f32_32x32x16_bf16 v[16:31], v[32:35], v[96:99], v[16:31]
	global_load_dwordx4 v[32:35], v[100:101], off offset:3072
	s_waitcnt vmcnt(11)
	v_mfma_f32_32x32x16_bf16 v[0:15], v[52:55], v[96:99], v[0:15]
	global_load_dwordx4 v[52:55], v[102:103], off offset:3072
	s_waitcnt vmcnt(8)
	ds_write_b128 v74, v[48:51] offset:18432
	ds_write_b128 v74, v[44:47] offset:23040
	ds_write_b128 v74, v[40:43] offset:27648
	ds_write_b128 v74, v[36:39] offset:32256
	global_load_dwordx4 v[36:39], v[76:77], off offset:1792
	global_load_dwordx4 v[40:43], v[78:79], off offset:1792
	global_load_dwordx4 v[44:47], v[80:81], off offset:1792
	global_load_dwordx4 v[48:51], v[82:83], off offset:1792
	s_waitcnt lgkmcnt(0)
	s_barrier
	ds_read_b128 v[96:99], v84 offset:18432
	s_mov_b32 s11, 0x70e000
	v_add_co_u32_e32 v100, vcc, s11, v72
	s_mov_b32 s11, 0x71e000
	s_nop 0
	v_addc_co_u32_e32 v101, vcc, 0, v73, vcc
	v_add_co_u32_e32 v102, vcc, s11, v72
	s_waitcnt vmcnt(11) lgkmcnt(0)
	v_mfma_f32_32x32x16_bf16 v[16:31], v[92:95], v[96:99], v[16:31]
	v_addc_co_u32_e32 v103, vcc, 0, v73, vcc
	global_load_dwordx4 v[92:95], v[100:101], off
	s_waitcnt vmcnt(11)
	v_mfma_f32_32x32x16_bf16 v[0:15], v[88:91], v[96:99], v[0:15]
	global_load_dwordx4 v[88:91], v[102:103], off
	ds_read_b128 v[96:99], v84 offset:18464
	s_waitcnt vmcnt(11) lgkmcnt(0)
	v_mfma_f32_32x32x16_bf16 v[16:31], v[64:67], v[96:99], v[16:31]
	global_load_dwordx4 v[64:67], v[100:101], off offset:1024
	s_waitcnt vmcnt(11)
	v_mfma_f32_32x32x16_bf16 v[0:15], v[68:71], v[96:99], v[0:15]
	global_load_dwordx4 v[68:71], v[102:103], off offset:1024
	ds_read_b128 v[96:99], v84 offset:18496
	s_waitcnt vmcnt(11) lgkmcnt(0)
	v_mfma_f32_32x32x16_bf16 v[16:31], v[56:59], v[96:99], v[16:31]
	global_load_dwordx4 v[56:59], v[100:101], off offset:2048
	s_waitcnt vmcnt(11)
	v_mfma_f32_32x32x16_bf16 v[0:15], v[60:63], v[96:99], v[0:15]
	global_load_dwordx4 v[60:63], v[102:103], off offset:2048
	ds_read_b128 v[96:99], v84 offset:18528
	s_waitcnt vmcnt(11) lgkmcnt(0)
	v_mfma_f32_32x32x16_bf16 v[16:31], v[32:35], v[96:99], v[16:31]
	global_load_dwordx4 v[32:35], v[100:101], off offset:3072
	s_waitcnt vmcnt(11)
	v_mfma_f32_32x32x16_bf16 v[0:15], v[52:55], v[96:99], v[0:15]
	global_load_dwordx4 v[52:55], v[102:103], off offset:3072
	s_waitcnt vmcnt(11)
	ds_write_b128 v74, v[36:39]
	s_waitcnt vmcnt(10)
	ds_write_b128 v74, v[40:43] offset:4608
	s_waitcnt vmcnt(9)
	ds_write_b128 v74, v[44:47] offset:9216
	s_waitcnt vmcnt(8)
	ds_write_b128 v74, v[48:51] offset:13824
	global_load_dwordx4 v[36:39], v[82:83], off offset:1920
	global_load_dwordx4 v[40:43], v[80:81], off offset:1920
	global_load_dwordx4 v[44:47], v[78:79], off offset:1920
	global_load_dwordx4 v[48:51], v[76:77], off offset:1920
	s_waitcnt lgkmcnt(0)
	s_barrier
	ds_read_b128 v[76:79], v84
	s_mov_b32 s11, 0x70f000
	s_waitcnt vmcnt(11) lgkmcnt(0)
	v_mfma_f32_32x32x16_bf16 v[16:31], v[92:95], v[76:79], v[16:31]
	v_add_co_u32_e32 v92, vcc, s11, v72
	s_mov_b32 s11, 0x71f000
	s_nop 0
	v_addc_co_u32_e32 v93, vcc, 0, v73, vcc
	v_add_co_u32_e32 v72, vcc, s11, v72
	global_load_dwordx4 v[80:83], v[92:93], off
	s_nop 0
	v_addc_co_u32_e32 v73, vcc, 0, v73, vcc
	s_waitcnt vmcnt(11)
	v_mfma_f32_32x32x16_bf16 v[0:15], v[88:91], v[76:79], v[0:15]
	global_load_dwordx4 v[76:79], v[72:73], off
	ds_read_b128 v[88:91], v84 offset:32
	s_waitcnt vmcnt(11) lgkmcnt(0)
	v_mfma_f32_32x32x16_bf16 v[16:31], v[64:67], v[88:91], v[16:31]
	global_load_dwordx4 v[64:67], v[92:93], off offset:1024
	s_waitcnt vmcnt(11)
	v_mfma_f32_32x32x16_bf16 v[0:15], v[68:71], v[88:91], v[0:15]
	global_load_dwordx4 v[68:71], v[72:73], off offset:1024
	ds_read_b128 v[88:91], v84 offset:64
	s_waitcnt vmcnt(11) lgkmcnt(0)
	v_mfma_f32_32x32x16_bf16 v[16:31], v[56:59], v[88:91], v[16:31]
	global_load_dwordx4 v[56:59], v[92:93], off offset:2048
	s_waitcnt vmcnt(11)
	v_mfma_f32_32x32x16_bf16 v[0:15], v[60:63], v[88:91], v[0:15]
	global_load_dwordx4 v[60:63], v[72:73], off offset:2048
	ds_read_b128 v[88:91], v84 offset:96
	s_waitcnt vmcnt(11) lgkmcnt(0)
	v_mfma_f32_32x32x16_bf16 v[16:31], v[32:35], v[88:91], v[16:31]
	global_load_dwordx4 v[32:35], v[92:93], off offset:3072
	s_waitcnt vmcnt(11)
	v_mfma_f32_32x32x16_bf16 v[0:15], v[52:55], v[88:91], v[0:15]
	global_load_dwordx4 v[52:55], v[72:73], off offset:3072
	s_waitcnt vmcnt(8)
	ds_write_b128 v74, v[48:51] offset:18432
	ds_write_b128 v74, v[44:47] offset:23040
	ds_write_b128 v74, v[40:43] offset:27648
	ds_write_b128 v74, v[36:39] offset:32256
	s_waitcnt lgkmcnt(0)
	s_barrier
	ds_read_b128 v[36:39], v84 offset:18432
	s_waitcnt vmcnt(7) lgkmcnt(0)
	v_mfma_f32_32x32x16_bf16 v[16:31], v[80:83], v[36:39], v[16:31]
	s_waitcnt vmcnt(6)
	v_mfma_f32_32x32x16_bf16 v[0:15], v[76:79], v[36:39], v[0:15]
	ds_read_b128 v[36:39], v84 offset:18464
	s_waitcnt vmcnt(5) lgkmcnt(0)
	v_mfma_f32_32x32x16_bf16 v[16:31], v[64:67], v[36:39], v[16:31]
	s_waitcnt vmcnt(4)
	v_mfma_f32_32x32x16_bf16 v[0:15], v[68:71], v[36:39], v[0:15]
	ds_read_b128 v[36:39], v84 offset:18496
	s_waitcnt vmcnt(3) lgkmcnt(0)
	v_mfma_f32_32x32x16_bf16 v[16:31], v[56:59], v[36:39], v[16:31]
	s_waitcnt vmcnt(2)
	v_mfma_f32_32x32x16_bf16 v[0:15], v[60:63], v[36:39], v[0:15]
	ds_read_b128 v[36:39], v84 offset:18528
	s_waitcnt vmcnt(1) lgkmcnt(0)
	v_mfma_f32_32x32x16_bf16 v[16:31], v[32:35], v[36:39], v[16:31]
	s_waitcnt vmcnt(0)
	v_mfma_f32_32x32x16_bf16 v[0:15], v[52:55], v[36:39], v[0:15]
	v_add_u32_e32 v32, s10, v75
	v_ashrrev_i32_e32 v33, 31, v32
	v_lshl_add_u64 v[34:35], v[32:33], 2, s[8:9]
	s_barrier
	global_load_dword v34, v[34:35], off
	v_mov_b64_e32 v[36:37], s[2:3]
	v_cmp_gt_u32_e32 vcc, 32, v86
	v_mad_i64_i32 v[32:33], s[14:15], v32, s23, v[36:37]
	s_nop 0
	v_cndmask_b32_e64 v192, 16, 0, vcc
	v_lshl_add_u64 v[32:33], v[32:33], 0, v[192:193]
	s_mov_b32 s11, 0x3dd1000
	s_mov_b64 s[14:15], 0x3dd1c00
	v_lshl_add_u64 v[36:37], v[32:33], 0, s[14:15]
	s_add_i32 s20, s20, s22
	s_add_i32 s10, s10, s16
	s_cmpk_lt_i32 s20, 0x180
	s_waitcnt vmcnt(0)
	v_pk_mul_f32 v[16:17], v[16:17], v[34:35] op_sel_hi:[1,0]
	v_pk_mul_f32 v[18:19], v[18:19], v[34:35] op_sel_hi:[1,0]
	v_pk_mul_f32 v[20:21], v[20:21], v[34:35] op_sel_hi:[1,0]
	v_pk_mul_f32 v[22:23], v[22:23], v[34:35] op_sel_hi:[1,0]
	v_pk_mul_f32 v[0:1], v[0:1], v[34:35] op_sel_hi:[1,0]
	v_pk_mul_f32 v[2:3], v[2:3], v[34:35] op_sel_hi:[1,0]
	v_pk_mul_f32 v[4:5], v[4:5], v[34:35] op_sel_hi:[1,0]
	v_pk_mul_f32 v[6:7], v[6:7], v[34:35] op_sel_hi:[1,0]
	v_cvt_pk_bf16_f32 v16, v16, v17
	v_cvt_pk_bf16_f32 v17, v18, v19
	v_cvt_pk_bf16_f32 v18, v20, v21
	v_cvt_pk_bf16_f32 v19, v22, v23
	v_add_co_u32_e32 v20, vcc, s11, v32
	v_cvt_pk_bf16_f32 v0, v0, v1
	v_cvt_pk_bf16_f32 v1, v2, v3
	v_cvt_pk_bf16_f32 v2, v4, v5
	v_cvt_pk_bf16_f32 v3, v6, v7
	v_permlane32_swap_b32_e32 v16, v18
	v_permlane32_swap_b32_e32 v17, v19
	v_addc_co_u32_e32 v21, vcc, 0, v33, vcc
	v_permlane32_swap_b32_e32 v0, v2
	v_permlane32_swap_b32_e32 v1, v3
	global_store_dwordx4 v[20:21], v[16:19], off offset:3072
	v_pk_mul_f32 v[20:21], v[28:29], v[34:35] op_sel_hi:[1,0]
	v_pk_mul_f32 v[22:23], v[30:31], v[34:35] op_sel_hi:[1,0]
	v_pk_mul_f32 v[16:17], v[24:25], v[34:35] op_sel_hi:[1,0]
	v_pk_mul_f32 v[18:19], v[26:27], v[34:35] op_sel_hi:[1,0]
	global_store_dwordx4 v[36:37], v[0:3], off offset:64
	v_pk_mul_f32 v[4:5], v[12:13], v[34:35] op_sel_hi:[1,0]
	v_pk_mul_f32 v[6:7], v[14:15], v[34:35] op_sel_hi:[1,0]
	v_pk_mul_f32 v[0:1], v[8:9], v[34:35] op_sel_hi:[1,0]
	v_pk_mul_f32 v[2:3], v[10:11], v[34:35] op_sel_hi:[1,0]
	v_cvt_pk_bf16_f32 v16, v16, v17
	v_cvt_pk_bf16_f32 v17, v18, v19
	v_cvt_pk_bf16_f32 v18, v20, v21
	v_cvt_pk_bf16_f32 v19, v22, v23
	v_cvt_pk_bf16_f32 v0, v0, v1
	v_cvt_pk_bf16_f32 v1, v2, v3
	v_cvt_pk_bf16_f32 v2, v4, v5
	v_cvt_pk_bf16_f32 v3, v6, v7
	v_permlane32_swap_b32_e32 v16, v18
	v_permlane32_swap_b32_e32 v17, v19
	v_permlane32_swap_b32_e32 v0, v2
	v_permlane32_swap_b32_e32 v1, v3
	global_store_dwordx4 v[36:37], v[16:19], off offset:32
	global_store_dwordx4 v[36:37], v[0:3], off offset:96
	s_cbranch_scc1 .LBB0_316

.LBB0_815:
	s_ashr_i32 s8, s60, 31
	s_lshr_b32 s8, s8, 25
	s_add_i32 s8, s60, s8
	s_ashr_i32 s61, s8, 7
	s_and_b32 s8, s8, 0xffffff80
	v_mov_b32_e32 v152, v166
	s_sub_i32 s34, s60, s8
	s_lshl_b32 s8, s61, 3
	v_ashrrev_i32_e32 v168, 6, v152
	v_lshl_add_u32 v0, v168, 1, s8
	s_lshl_b32 s30, s34, 7
	v_ashrrev_i32_e32 v1, 31, v0
	v_lshlrev_b64 v[0:1], 16, v[0:1]
	s_ashr_i32 s31, s30, 31
	v_lshl_add_u64 v[16:17], s[20:21], 0, v[0:1]
	s_lshl_b64 s[8:9], s[30:31], 11
	v_lshlrev_b32_e32 v0, 4, v152
	v_ashrrev_i32_e32 v21, 3, v152
	s_add_u32 s8, s54, s8
	v_and_b32_e32 v20, 0x70, v0
	s_addc_u32 s9, s55, s9
	v_lshl_or_b32 v192, v21, 11, v20
	v_lshl_add_u64 v[158:159], s[8:9], 0, v[192:193]
	s_mov_b32 s8, 0x10000
	v_add_co_u32_e32 v160, vcc, s8, v158
	s_mov_b32 s9, 0x20000
	s_nop 0
	v_addc_co_u32_e32 v161, vcc, 0, v159, vcc
	v_add_co_u32_e32 v162, vcc, s9, v158
	s_barrier
	global_load_dwordx4 v[0:3], v[158:159], off
	global_load_dwordx4 v[4:7], v[160:161], off
	v_addc_co_u32_e32 v163, vcc, 0, v159, vcc
	s_mov_b32 s9, 0x30000
	v_add_co_u32_e32 v164, vcc, s9, v158
	global_load_dwordx4 v[8:11], v[162:163], off
	s_nop 0
	v_addc_co_u32_e32 v165, vcc, 0, v159, vcc
	global_load_dwordx4 v[12:15], v[164:165], off
	v_and_b32_e32 v153, 63, v152
	v_lshlrev_b32_e32 v192, 4, v153
	v_lshl_add_u64 v[156:157], v[16:17], 0, v[192:193]
	v_add_co_u32_e32 v22, vcc, s8, v156
	s_movk_i32 s10, 0x90
	s_nop 0
	v_addc_co_u32_e32 v23, vcc, 0, v157, vcc
	v_mad_u64_u32 v[154:155], s[8:9], v21, s10, v[20:21]
	global_load_dwordx4 v[16:19], v[156:157], off
	global_load_dwordx4 v[148:151], v[156:157], off offset:1024
	global_load_dwordx4 v[140:143], v[156:157], off offset:2048
	global_load_dwordx4 v[132:135], v[156:157], off offset:3072
	global_load_dwordx4 v[170:173], v[22:23], off
	global_load_dwordx4 v[144:147], v[22:23], off offset:1024
	global_load_dwordx4 v[136:139], v[22:23], off offset:2048
	global_load_dwordx4 v[128:131], v[22:23], off offset:3072
	v_bfe_u32 v169, v152, 5, 1
	v_and_b32_e32 v167, 31, v152
	s_waitcnt vmcnt(11) lgkmcnt(0)
	ds_write_b128 v154, v[0:3]
	s_waitcnt vmcnt(10)
	ds_write_b128 v154, v[4:7] offset:4608
	s_waitcnt vmcnt(9)
	ds_write_b128 v154, v[8:11] offset:9216
	s_waitcnt vmcnt(8)
	ds_write_b128 v154, v[12:15] offset:13824
	global_load_dwordx4 v[174:177], v[158:159], off offset:128
	global_load_dwordx4 v[178:181], v[160:161], off offset:128
	global_load_dwordx4 v[182:185], v[162:163], off offset:128
	global_load_dwordx4 v[186:189], v[164:165], off offset:128
	v_lshlrev_b32_e32 v0, 4, v169
	v_mad_u32_u24 v155, v167, s10, v0
	s_waitcnt lgkmcnt(0)
	s_barrier
	ds_read_b128 v[0:3], v155 offset:4608
	ds_read_b128 v[4:7], v155 offset:9216
	ds_read_b128 v[8:11], v155 offset:13824
	ds_read_b128 v[12:15], v155
	ds_read_b128 v[198:201], v155 offset:32
	ds_read_b128 v[202:205], v155 offset:4640
	ds_read_b128 v[206:209], v155 offset:9248
	ds_read_b128 v[210:213], v155 offset:13856
	s_setprio 2
	s_movk_i32 s8, 0x1000
	v_add_co_u32_e32 v190, vcc, s8, v156
	s_mov_b32 s8, 0x11000
	s_nop 0
	v_addc_co_u32_e32 v191, vcc, 0, v157, vcc
	v_add_co_u32_e32 v242, vcc, s8, v156
	s_waitcnt vmcnt(11) lgkmcnt(4)
	v_mfma_f32_32x32x16_bf16 v[112:127], v[16:19], v[12:15], 0
	v_addc_co_u32_e32 v243, vcc, 0, v157, vcc
	global_load_dwordx4 v[214:217], v[190:191], off
	v_mfma_f32_32x32x16_bf16 v[80:95], v[16:19], v[0:3], 0
	v_mfma_f32_32x32x16_bf16 v[48:63], v[16:19], v[4:7], 0
	v_mfma_f32_32x32x16_bf16 v[16:31], v[16:19], v[8:11], 0
	s_waitcnt vmcnt(8)
	v_mfma_f32_32x32x16_bf16 v[96:111], v[170:173], v[12:15], 0
	v_mfma_f32_32x32x16_bf16 v[64:79], v[170:173], v[0:3], 0
	v_mfma_f32_32x32x16_bf16 v[32:47], v[170:173], v[4:7], 0
	v_mfma_f32_32x32x16_bf16 v[0:15], v[170:173], v[8:11], 0
	global_load_dwordx4 v[170:173], v[242:243], off
	s_setprio 0
	ds_read_b128 v[218:221], v155 offset:64
	ds_read_b128 v[228:231], v155 offset:4672
	ds_read_b128 v[234:237], v155 offset:9280
	ds_read_b128 v[238:241], v155 offset:13888
	s_setprio 2
	s_waitcnt lgkmcnt(7)
	v_mfma_f32_32x32x16_bf16 v[112:127], v[148:151], v[198:201], v[112:127]
	s_waitcnt lgkmcnt(6)
	v_mfma_f32_32x32x16_bf16 v[80:95], v[148:151], v[202:205], v[80:95]
	s_waitcnt lgkmcnt(5)
	v_mfma_f32_32x32x16_bf16 v[48:63], v[148:151], v[206:209], v[48:63]
	s_waitcnt lgkmcnt(4)
	v_mfma_f32_32x32x16_bf16 v[16:31], v[148:151], v[210:213], v[16:31]
	s_waitcnt vmcnt(8)
	v_mfma_f32_32x32x16_bf16 v[96:111], v[144:147], v[198:201], v[96:111]
	global_load_dwordx4 v[148:151], v[190:191], off offset:1024
	global_load_dwordx4 v[198:201], v[242:243], off offset:1024
	v_mfma_f32_32x32x16_bf16 v[64:79], v[144:147], v[202:205], v[64:79]
	v_mfma_f32_32x32x16_bf16 v[32:47], v[144:147], v[206:209], v[32:47]
	v_mfma_f32_32x32x16_bf16 v[0:15], v[144:147], v[210:213], v[0:15]
	s_setprio 0
	ds_read_b128 v[144:147], v155 offset:96
	ds_read_b128 v[202:205], v155 offset:4704
	ds_read_b128 v[206:209], v155 offset:9312
	ds_read_b128 v[210:213], v155 offset:13920
	s_setprio 2
	s_waitcnt lgkmcnt(7)
	v_mfma_f32_32x32x16_bf16 v[112:127], v[140:143], v[218:221], v[112:127]
	s_waitcnt lgkmcnt(6)
	v_mfma_f32_32x32x16_bf16 v[80:95], v[140:143], v[228:231], v[80:95]
	s_waitcnt lgkmcnt(5)
	v_mfma_f32_32x32x16_bf16 v[48:63], v[140:143], v[234:237], v[48:63]
	s_waitcnt lgkmcnt(4)
	v_mfma_f32_32x32x16_bf16 v[16:31], v[140:143], v[238:241], v[16:31]
	s_waitcnt vmcnt(9)
	v_mfma_f32_32x32x16_bf16 v[96:111], v[136:139], v[218:221], v[96:111]
	global_load_dwordx4 v[140:143], v[190:191], off offset:2048
	global_load_dwordx4 v[218:221], v[242:243], off offset:2048
	v_mfma_f32_32x32x16_bf16 v[64:79], v[136:139], v[228:231], v[64:79]
	v_mfma_f32_32x32x16_bf16 v[32:47], v[136:139], v[234:237], v[32:47]
	v_mfma_f32_32x32x16_bf16 v[0:15], v[136:139], v[238:241], v[0:15]
	s_setprio 0
	s_setprio 2
	s_waitcnt lgkmcnt(3)
	v_mfma_f32_32x32x16_bf16 v[112:127], v[132:135], v[144:147], v[112:127]
	s_waitcnt lgkmcnt(2)
	v_mfma_f32_32x32x16_bf16 v[80:95], v[132:135], v[202:205], v[80:95]
	s_waitcnt lgkmcnt(1)
	v_mfma_f32_32x32x16_bf16 v[48:63], v[132:135], v[206:209], v[48:63]
	s_waitcnt lgkmcnt(0)
	v_mfma_f32_32x32x16_bf16 v[16:31], v[132:135], v[210:213], v[16:31]
	global_load_dwordx4 v[132:135], v[190:191], off offset:3072
	global_load_dwordx4 v[136:139], v[242:243], off offset:3072
	s_waitcnt vmcnt(12)
	v_mfma_f32_32x32x16_bf16 v[96:111], v[128:131], v[144:147], v[96:111]
	v_mfma_f32_32x32x16_bf16 v[64:79], v[128:131], v[202:205], v[64:79]
	v_mfma_f32_32x32x16_bf16 v[32:47], v[128:131], v[206:209], v[32:47]
	v_mfma_f32_32x32x16_bf16 v[0:15], v[128:131], v[210:213], v[0:15]
	s_setprio 0
	s_waitcnt vmcnt(11)
	ds_write_b128 v154, v[174:177] offset:18432
	s_waitcnt vmcnt(10)
	ds_write_b128 v154, v[178:181] offset:23040
	s_waitcnt vmcnt(9)
	ds_write_b128 v154, v[182:185] offset:27648
	s_waitcnt vmcnt(8)
	ds_write_b128 v154, v[186:189] offset:32256
	global_load_dwordx4 v[128:131], v[158:159], off offset:256
	global_load_dwordx4 v[144:147], v[160:161], off offset:256
	global_load_dwordx4 v[174:177], v[162:163], off offset:256
	global_load_dwordx4 v[178:181], v[164:165], off offset:256
	s_waitcnt lgkmcnt(0)
	s_barrier
	ds_read_b128 v[182:185], v155 offset:18432
	ds_read_b128 v[186:189], v155 offset:18464
	ds_read_b128 v[202:205], v155 offset:23040
	ds_read_b128 v[206:209], v155 offset:23072
	ds_read_b128 v[210:213], v155 offset:27648
	ds_read_b128 v[228:231], v155 offset:27680
	ds_read_b128 v[234:237], v155 offset:32256
	ds_read_b128 v[238:241], v155 offset:32288
	s_setprio 2
	s_movk_i32 s8, 0x2000
	v_add_co_u32_e32 v190, vcc, s8, v156
	s_mov_b32 s8, 0x12000
	s_nop 0
	v_addc_co_u32_e32 v191, vcc, 0, v157, vcc
	v_add_co_u32_e32 v242, vcc, s8, v156
	s_waitcnt vmcnt(11) lgkmcnt(7)
	v_mfma_f32_32x32x16_bf16 v[112:127], v[214:217], v[182:185], v[112:127]
	v_addc_co_u32_e32 v243, vcc, 0, v157, vcc
	s_waitcnt lgkmcnt(5)
	v_mfma_f32_32x32x16_bf16 v[80:95], v[214:217], v[202:205], v[80:95]
	s_waitcnt vmcnt(10)
	v_mfma_f32_32x32x16_bf16 v[96:111], v[170:173], v[182:185], v[96:111]
	v_mfma_f32_32x32x16_bf16 v[64:79], v[170:173], v[202:205], v[64:79]
	global_load_dwordx4 v[182:185], v[190:191], off
	global_load_dwordx4 v[202:205], v[242:243], off
	s_waitcnt lgkmcnt(3)
	v_mfma_f32_32x32x16_bf16 v[48:63], v[214:217], v[210:213], v[48:63]
	s_waitcnt lgkmcnt(1)
	v_mfma_f32_32x32x16_bf16 v[16:31], v[214:217], v[234:237], v[16:31]
	v_mfma_f32_32x32x16_bf16 v[32:47], v[170:173], v[210:213], v[32:47]
	v_mfma_f32_32x32x16_bf16 v[0:15], v[170:173], v[234:237], v[0:15]
	s_setprio 0
	ds_read_b128 v[170:173], v155 offset:18496
	ds_read_b128 v[210:213], v155 offset:23104
	ds_read_b128 v[214:217], v155 offset:27712
	ds_read_b128 v[234:237], v155 offset:32320
	s_setprio 2
	s_waitcnt vmcnt(11)
	v_mfma_f32_32x32x16_bf16 v[112:127], v[148:151], v[186:189], v[112:127]
	v_mfma_f32_32x32x16_bf16 v[80:95], v[148:151], v[206:209], v[80:95]
	v_mfma_f32_32x32x16_bf16 v[48:63], v[148:151], v[228:231], v[48:63]
	s_waitcnt lgkmcnt(4)
	v_mfma_f32_32x32x16_bf16 v[16:31], v[148:151], v[238:241], v[16:31]
	s_waitcnt vmcnt(10)
	v_mfma_f32_32x32x16_bf16 v[96:111], v[198:201], v[186:189], v[96:111]
	global_load_dwordx4 v[148:151], v[190:191], off offset:1024
	global_load_dwordx4 v[186:189], v[242:243], off offset:1024
	v_mfma_f32_32x32x16_bf16 v[64:79], v[198:201], v[206:209], v[64:79]
	v_mfma_f32_32x32x16_bf16 v[32:47], v[198:201], v[228:231], v[32:47]
	v_mfma_f32_32x32x16_bf16 v[0:15], v[198:201], v[238:241], v[0:15]
	s_setprio 0
	ds_read_b128 v[198:201], v155 offset:18528
	ds_read_b128 v[206:209], v155 offset:23136
	ds_read_b128 v[228:231], v155 offset:27744
	ds_read_b128 v[238:241], v155 offset:32352
	s_setprio 2
	s_waitcnt vmcnt(11) lgkmcnt(7)
	v_mfma_f32_32x32x16_bf16 v[112:127], v[140:143], v[170:173], v[112:127]
	s_waitcnt lgkmcnt(6)
	v_mfma_f32_32x32x16_bf16 v[80:95], v[140:143], v[210:213], v[80:95]
	s_waitcnt lgkmcnt(5)
	v_mfma_f32_32x32x16_bf16 v[48:63], v[140:143], v[214:217], v[48:63]
	s_waitcnt lgkmcnt(4)
	v_mfma_f32_32x32x16_bf16 v[16:31], v[140:143], v[234:237], v[16:31]
	s_waitcnt vmcnt(10)
	v_mfma_f32_32x32x16_bf16 v[96:111], v[218:221], v[170:173], v[96:111]
	global_load_dwordx4 v[140:143], v[190:191], off offset:2048
	global_load_dwordx4 v[170:173], v[242:243], off offset:2048
	v_mfma_f32_32x32x16_bf16 v[64:79], v[218:221], v[210:213], v[64:79]
	v_mfma_f32_32x32x16_bf16 v[32:47], v[218:221], v[214:217], v[32:47]
	v_mfma_f32_32x32x16_bf16 v[0:15], v[218:221], v[234:237], v[0:15]
	s_setprio 0
	s_setprio 2
	s_waitcnt vmcnt(11) lgkmcnt(3)
	v_mfma_f32_32x32x16_bf16 v[112:127], v[132:135], v[198:201], v[112:127]
	s_waitcnt lgkmcnt(2)
	v_mfma_f32_32x32x16_bf16 v[80:95], v[132:135], v[206:209], v[80:95]
	s_waitcnt lgkmcnt(1)
	v_mfma_f32_32x32x16_bf16 v[48:63], v[132:135], v[228:231], v[48:63]
	s_waitcnt lgkmcnt(0)
	v_mfma_f32_32x32x16_bf16 v[16:31], v[132:135], v[238:241], v[16:31]
	s_waitcnt vmcnt(10)
	v_mfma_f32_32x32x16_bf16 v[96:111], v[136:139], v[198:201], v[96:111]
	global_load_dwordx4 v[132:135], v[190:191], off offset:3072
	global_load_dwordx4 v[198:201], v[242:243], off offset:3072
	v_mfma_f32_32x32x16_bf16 v[64:79], v[136:139], v[206:209], v[64:79]
	v_mfma_f32_32x32x16_bf16 v[32:47], v[136:139], v[228:231], v[32:47]
	v_mfma_f32_32x32x16_bf16 v[0:15], v[136:139], v[238:241], v[0:15]
	s_setprio 0
	s_waitcnt vmcnt(11)
	ds_write_b128 v154, v[128:131]
	s_waitcnt vmcnt(10)
	ds_write_b128 v154, v[144:147] offset:4608
	s_waitcnt vmcnt(9)
	ds_write_b128 v154, v[174:177] offset:9216
	s_waitcnt vmcnt(8)
	ds_write_b128 v154, v[178:181] offset:13824
	global_load_dwordx4 v[128:131], v[164:165], off offset:384
	global_load_dwordx4 v[136:139], v[162:163], off offset:384
	global_load_dwordx4 v[144:147], v[160:161], off offset:384
	global_load_dwordx4 v[174:177], v[158:159], off offset:384
	s_waitcnt lgkmcnt(0)
	s_barrier
	ds_read_b128 v[178:181], v155
	ds_read_b128 v[206:209], v155 offset:32
	ds_read_b128 v[210:213], v155 offset:4608
	ds_read_b128 v[214:217], v155 offset:4640
	ds_read_b128 v[218:221], v155 offset:9216
	ds_read_b128 v[228:231], v155 offset:9248
	ds_read_b128 v[234:237], v155 offset:13824
	ds_read_b128 v[238:241], v155 offset:13856
	s_setprio 2
	s_movk_i32 s8, 0x3000
	v_add_co_u32_e32 v190, vcc, s8, v156
	s_mov_b32 s8, 0x13000
	s_nop 0
	v_addc_co_u32_e32 v191, vcc, 0, v157, vcc
	v_add_co_u32_e32 v242, vcc, s8, v156
	s_waitcnt vmcnt(11) lgkmcnt(7)
	v_mfma_f32_32x32x16_bf16 v[112:127], v[182:185], v[178:181], v[112:127]
	v_addc_co_u32_e32 v243, vcc, 0, v157, vcc
	s_waitcnt lgkmcnt(5)
	v_mfma_f32_32x32x16_bf16 v[80:95], v[182:185], v[210:213], v[80:95]
	s_waitcnt lgkmcnt(3)
	v_mfma_f32_32x32x16_bf16 v[48:63], v[182:185], v[218:221], v[48:63]
	s_waitcnt lgkmcnt(1)
	v_mfma_f32_32x32x16_bf16 v[16:31], v[182:185], v[234:237], v[16:31]
	s_waitcnt vmcnt(10)
	v_mfma_f32_32x32x16_bf16 v[96:111], v[202:205], v[178:181], v[96:111]
	global_load_dwordx4 v[178:181], v[190:191], off
	global_load_dwordx4 v[182:185], v[242:243], off
	v_mfma_f32_32x32x16_bf16 v[64:79], v[202:205], v[210:213], v[64:79]
	v_mfma_f32_32x32x16_bf16 v[32:47], v[202:205], v[218:221], v[32:47]
	v_mfma_f32_32x32x16_bf16 v[0:15], v[202:205], v[234:237], v[0:15]
	s_setprio 0
	ds_read_b128 v[202:205], v155 offset:64
	ds_read_b128 v[210:213], v155 offset:4672
	ds_read_b128 v[218:221], v155 offset:9280
	ds_read_b128 v[234:237], v155 offset:13888
	s_setprio 2
	s_waitcnt vmcnt(11)
	v_mfma_f32_32x32x16_bf16 v[112:127], v[148:151], v[206:209], v[112:127]
	v_mfma_f32_32x32x16_bf16 v[80:95], v[148:151], v[214:217], v[80:95]
	v_mfma_f32_32x32x16_bf16 v[48:63], v[148:151], v[228:231], v[48:63]
	s_waitcnt lgkmcnt(4)
	v_mfma_f32_32x32x16_bf16 v[16:31], v[148:151], v[238:241], v[16:31]
	s_waitcnt vmcnt(10)
	v_mfma_f32_32x32x16_bf16 v[96:111], v[186:189], v[206:209], v[96:111]
	global_load_dwordx4 v[148:151], v[190:191], off offset:1024
	global_load_dwordx4 v[206:209], v[242:243], off offset:1024
	v_mfma_f32_32x32x16_bf16 v[64:79], v[186:189], v[214:217], v[64:79]
	v_mfma_f32_32x32x16_bf16 v[32:47], v[186:189], v[228:231], v[32:47]
	v_mfma_f32_32x32x16_bf16 v[0:15], v[186:189], v[238:241], v[0:15]
	s_setprio 0
	ds_read_b128 v[186:189], v155 offset:96
	ds_read_b128 v[214:217], v155 offset:4704
	ds_read_b128 v[228:231], v155 offset:9312
	ds_read_b128 v[238:241], v155 offset:13920
	s_setprio 2
	s_waitcnt vmcnt(11) lgkmcnt(7)
	v_mfma_f32_32x32x16_bf16 v[112:127], v[140:143], v[202:205], v[112:127]
	s_waitcnt lgkmcnt(6)
	v_mfma_f32_32x32x16_bf16 v[80:95], v[140:143], v[210:213], v[80:95]
	s_waitcnt lgkmcnt(5)
	v_mfma_f32_32x32x16_bf16 v[48:63], v[140:143], v[218:221], v[48:63]
	s_waitcnt lgkmcnt(4)
	v_mfma_f32_32x32x16_bf16 v[16:31], v[140:143], v[234:237], v[16:31]
	s_waitcnt vmcnt(10)
	v_mfma_f32_32x32x16_bf16 v[96:111], v[170:173], v[202:205], v[96:111]
	global_load_dwordx4 v[140:143], v[190:191], off offset:2048
	global_load_dwordx4 v[202:205], v[242:243], off offset:2048
	v_mfma_f32_32x32x16_bf16 v[64:79], v[170:173], v[210:213], v[64:79]
	v_mfma_f32_32x32x16_bf16 v[32:47], v[170:173], v[218:221], v[32:47]
	v_mfma_f32_32x32x16_bf16 v[0:15], v[170:173], v[234:237], v[0:15]
	s_setprio 0
	s_setprio 2
	s_waitcnt vmcnt(11) lgkmcnt(3)
	v_mfma_f32_32x32x16_bf16 v[112:127], v[132:135], v[186:189], v[112:127]
	s_waitcnt lgkmcnt(2)
	v_mfma_f32_32x32x16_bf16 v[80:95], v[132:135], v[214:217], v[80:95]
	s_waitcnt lgkmcnt(1)
	v_mfma_f32_32x32x16_bf16 v[48:63], v[132:135], v[228:231], v[48:63]
	s_waitcnt lgkmcnt(0)
	v_mfma_f32_32x32x16_bf16 v[16:31], v[132:135], v[238:241], v[16:31]
	global_load_dwordx4 v[132:135], v[190:191], off offset:3072
	global_load_dwordx4 v[170:173], v[242:243], off offset:3072
	s_waitcnt vmcnt(12)
	v_mfma_f32_32x32x16_bf16 v[96:111], v[198:201], v[186:189], v[96:111]
	v_mfma_f32_32x32x16_bf16 v[64:79], v[198:201], v[214:217], v[64:79]
	v_mfma_f32_32x32x16_bf16 v[32:47], v[198:201], v[228:231], v[32:47]
	v_mfma_f32_32x32x16_bf16 v[0:15], v[198:201], v[238:241], v[0:15]
	s_setprio 0
	s_waitcnt vmcnt(8)
	ds_write_b128 v154, v[174:177] offset:18432
	ds_write_b128 v154, v[144:147] offset:23040
	ds_write_b128 v154, v[136:139] offset:27648
	ds_write_b128 v154, v[128:131] offset:32256
	global_load_dwordx4 v[128:131], v[158:159], off offset:512
	global_load_dwordx4 v[136:139], v[160:161], off offset:512
	global_load_dwordx4 v[144:147], v[162:163], off offset:512
	global_load_dwordx4 v[174:177], v[164:165], off offset:512
	s_waitcnt lgkmcnt(0)
	s_barrier
	ds_read_b128 v[186:189], v155 offset:18432
	ds_read_b128 v[198:201], v155 offset:18464
	ds_read_b128 v[210:213], v155 offset:23040
	ds_read_b128 v[214:217], v155 offset:23072
	ds_read_b128 v[218:221], v155 offset:27648
	ds_read_b128 v[228:231], v155 offset:27680
	ds_read_b128 v[234:237], v155 offset:32256
	ds_read_b128 v[238:241], v155 offset:32288
	s_setprio 2
	s_movk_i32 s8, 0x4000
	v_add_co_u32_e32 v190, vcc, s8, v156
	s_mov_b32 s8, 0x14000
	s_nop 0
	v_addc_co_u32_e32 v191, vcc, 0, v157, vcc
	v_add_co_u32_e32 v242, vcc, s8, v156
	s_waitcnt vmcnt(11) lgkmcnt(7)
	v_mfma_f32_32x32x16_bf16 v[112:127], v[178:181], v[186:189], v[112:127]
	v_addc_co_u32_e32 v243, vcc, 0, v157, vcc
	s_waitcnt lgkmcnt(5)
	v_mfma_f32_32x32x16_bf16 v[80:95], v[178:181], v[210:213], v[80:95]
	s_waitcnt lgkmcnt(3)
	v_mfma_f32_32x32x16_bf16 v[48:63], v[178:181], v[218:221], v[48:63]
	s_waitcnt lgkmcnt(1)
	v_mfma_f32_32x32x16_bf16 v[16:31], v[178:181], v[234:237], v[16:31]
	s_waitcnt vmcnt(10)
	v_mfma_f32_32x32x16_bf16 v[96:111], v[182:185], v[186:189], v[96:111]
	global_load_dwordx4 v[178:181], v[190:191], off
	global_load_dwordx4 v[186:189], v[242:243], off
	v_mfma_f32_32x32x16_bf16 v[64:79], v[182:185], v[210:213], v[64:79]
	v_mfma_f32_32x32x16_bf16 v[32:47], v[182:185], v[218:221], v[32:47]
	v_mfma_f32_32x32x16_bf16 v[0:15], v[182:185], v[234:237], v[0:15]
	s_setprio 0
	ds_read_b128 v[182:185], v155 offset:18496
	ds_read_b128 v[210:213], v155 offset:23104
	ds_read_b128 v[218:221], v155 offset:27712
	ds_read_b128 v[234:237], v155 offset:32320
	s_setprio 2
	s_waitcnt vmcnt(11)
	v_mfma_f32_32x32x16_bf16 v[112:127], v[148:151], v[198:201], v[112:127]
	v_mfma_f32_32x32x16_bf16 v[80:95], v[148:151], v[214:217], v[80:95]
	v_mfma_f32_32x32x16_bf16 v[48:63], v[148:151], v[228:231], v[48:63]
	s_waitcnt lgkmcnt(4)
	v_mfma_f32_32x32x16_bf16 v[16:31], v[148:151], v[238:241], v[16:31]
	s_waitcnt vmcnt(10)
	v_mfma_f32_32x32x16_bf16 v[96:111], v[206:209], v[198:201], v[96:111]
	global_load_dwordx4 v[148:151], v[190:191], off offset:1024
	global_load_dwordx4 v[198:201], v[242:243], off offset:1024
	v_mfma_f32_32x32x16_bf16 v[64:79], v[206:209], v[214:217], v[64:79]
	v_mfma_f32_32x32x16_bf16 v[32:47], v[206:209], v[228:231], v[32:47]
	v_mfma_f32_32x32x16_bf16 v[0:15], v[206:209], v[238:241], v[0:15]
	s_setprio 0
	ds_read_b128 v[206:209], v155 offset:18528
	ds_read_b128 v[214:217], v155 offset:23136
	ds_read_b128 v[228:231], v155 offset:27744
	ds_read_b128 v[238:241], v155 offset:32352
	s_setprio 2
	s_waitcnt vmcnt(11) lgkmcnt(7)
	v_mfma_f32_32x32x16_bf16 v[112:127], v[140:143], v[182:185], v[112:127]
	s_waitcnt lgkmcnt(6)
	v_mfma_f32_32x32x16_bf16 v[80:95], v[140:143], v[210:213], v[80:95]
	s_waitcnt lgkmcnt(5)
	v_mfma_f32_32x32x16_bf16 v[48:63], v[140:143], v[218:221], v[48:63]
	s_waitcnt lgkmcnt(4)
	v_mfma_f32_32x32x16_bf16 v[16:31], v[140:143], v[234:237], v[16:31]
	s_waitcnt vmcnt(10)
	v_mfma_f32_32x32x16_bf16 v[96:111], v[202:205], v[182:185], v[96:111]
	global_load_dwordx4 v[140:143], v[190:191], off offset:2048
	global_load_dwordx4 v[182:185], v[242:243], off offset:2048
	v_mfma_f32_32x32x16_bf16 v[64:79], v[202:205], v[210:213], v[64:79]
	v_mfma_f32_32x32x16_bf16 v[32:47], v[202:205], v[218:221], v[32:47]
	v_mfma_f32_32x32x16_bf16 v[0:15], v[202:205], v[234:237], v[0:15]
	s_setprio 0
	s_setprio 2
	s_waitcnt vmcnt(11) lgkmcnt(3)
	v_mfma_f32_32x32x16_bf16 v[112:127], v[132:135], v[206:209], v[112:127]
	s_waitcnt lgkmcnt(2)
	v_mfma_f32_32x32x16_bf16 v[80:95], v[132:135], v[214:217], v[80:95]
	s_waitcnt lgkmcnt(1)
	v_mfma_f32_32x32x16_bf16 v[48:63], v[132:135], v[228:231], v[48:63]
	s_waitcnt lgkmcnt(0)
	v_mfma_f32_32x32x16_bf16 v[16:31], v[132:135], v[238:241], v[16:31]
	global_load_dwordx4 v[132:135], v[190:191], off offset:3072
	global_load_dwordx4 v[202:205], v[242:243], off offset:3072
	s_waitcnt vmcnt(12)
	v_mfma_f32_32x32x16_bf16 v[96:111], v[170:173], v[206:209], v[96:111]
	v_mfma_f32_32x32x16_bf16 v[64:79], v[170:173], v[214:217], v[64:79]
	v_mfma_f32_32x32x16_bf16 v[32:47], v[170:173], v[228:231], v[32:47]
	v_mfma_f32_32x32x16_bf16 v[0:15], v[170:173], v[238:241], v[0:15]
	s_setprio 0
	s_waitcnt vmcnt(11)
	ds_write_b128 v154, v[128:131]
	s_waitcnt vmcnt(10)
	ds_write_b128 v154, v[136:139] offset:4608
	s_waitcnt vmcnt(9)
	ds_write_b128 v154, v[144:147] offset:9216
	s_waitcnt vmcnt(8)
	ds_write_b128 v154, v[174:177] offset:13824
	global_load_dwordx4 v[128:131], v[164:165], off offset:640
	global_load_dwordx4 v[136:139], v[162:163], off offset:640
	global_load_dwordx4 v[144:147], v[160:161], off offset:640
	global_load_dwordx4 v[170:173], v[158:159], off offset:640
	s_waitcnt lgkmcnt(0)
	s_barrier
	ds_read_b128 v[174:177], v155
	ds_read_b128 v[206:209], v155 offset:32
	ds_read_b128 v[210:213], v155 offset:4608
	ds_read_b128 v[214:217], v155 offset:4640
	ds_read_b128 v[218:221], v155 offset:9216
	ds_read_b128 v[228:231], v155 offset:9248
	ds_read_b128 v[234:237], v155 offset:13824
	ds_read_b128 v[238:241], v155 offset:13856
	s_setprio 2
	s_movk_i32 s8, 0x5000
	v_add_co_u32_e32 v190, vcc, s8, v156
	s_mov_b32 s8, 0x15000
	s_nop 0
	v_addc_co_u32_e32 v191, vcc, 0, v157, vcc
	v_add_co_u32_e32 v242, vcc, s8, v156
	s_waitcnt vmcnt(11) lgkmcnt(7)
	v_mfma_f32_32x32x16_bf16 v[112:127], v[178:181], v[174:177], v[112:127]
	v_addc_co_u32_e32 v243, vcc, 0, v157, vcc
	s_waitcnt lgkmcnt(5)
	v_mfma_f32_32x32x16_bf16 v[80:95], v[178:181], v[210:213], v[80:95]
	s_waitcnt lgkmcnt(3)
	v_mfma_f32_32x32x16_bf16 v[48:63], v[178:181], v[218:221], v[48:63]
	s_waitcnt lgkmcnt(1)
	v_mfma_f32_32x32x16_bf16 v[16:31], v[178:181], v[234:237], v[16:31]
	s_waitcnt vmcnt(10)
	v_mfma_f32_32x32x16_bf16 v[96:111], v[186:189], v[174:177], v[96:111]
	global_load_dwordx4 v[174:177], v[190:191], off
	global_load_dwordx4 v[178:181], v[242:243], off
	v_mfma_f32_32x32x16_bf16 v[64:79], v[186:189], v[210:213], v[64:79]
	v_mfma_f32_32x32x16_bf16 v[32:47], v[186:189], v[218:221], v[32:47]
	v_mfma_f32_32x32x16_bf16 v[0:15], v[186:189], v[234:237], v[0:15]
	s_setprio 0
	ds_read_b128 v[186:189], v155 offset:64
	ds_read_b128 v[210:213], v155 offset:4672
	ds_read_b128 v[218:221], v155 offset:9280
	ds_read_b128 v[234:237], v155 offset:13888
	s_setprio 2
	s_waitcnt vmcnt(11)
	v_mfma_f32_32x32x16_bf16 v[112:127], v[148:151], v[206:209], v[112:127]
	v_mfma_f32_32x32x16_bf16 v[80:95], v[148:151], v[214:217], v[80:95]
	v_mfma_f32_32x32x16_bf16 v[48:63], v[148:151], v[228:231], v[48:63]
	s_waitcnt lgkmcnt(4)
	v_mfma_f32_32x32x16_bf16 v[16:31], v[148:151], v[238:241], v[16:31]
	s_waitcnt vmcnt(10)
	v_mfma_f32_32x32x16_bf16 v[96:111], v[198:201], v[206:209], v[96:111]
	global_load_dwordx4 v[148:151], v[190:191], off offset:1024
	global_load_dwordx4 v[206:209], v[242:243], off offset:1024
	v_mfma_f32_32x32x16_bf16 v[64:79], v[198:201], v[214:217], v[64:79]
	v_mfma_f32_32x32x16_bf16 v[32:47], v[198:201], v[228:231], v[32:47]
	v_mfma_f32_32x32x16_bf16 v[0:15], v[198:201], v[238:241], v[0:15]
	s_setprio 0
	ds_read_b128 v[198:201], v155 offset:96
	ds_read_b128 v[214:217], v155 offset:4704
	ds_read_b128 v[228:231], v155 offset:9312
	ds_read_b128 v[238:241], v155 offset:13920
	s_setprio 2
	s_waitcnt vmcnt(11) lgkmcnt(7)
	v_mfma_f32_32x32x16_bf16 v[112:127], v[140:143], v[186:189], v[112:127]
	s_waitcnt lgkmcnt(6)
	v_mfma_f32_32x32x16_bf16 v[80:95], v[140:143], v[210:213], v[80:95]
	s_waitcnt lgkmcnt(5)
	v_mfma_f32_32x32x16_bf16 v[48:63], v[140:143], v[218:221], v[48:63]
	s_waitcnt lgkmcnt(4)
	v_mfma_f32_32x32x16_bf16 v[16:31], v[140:143], v[234:237], v[16:31]
	s_waitcnt vmcnt(10)
	v_mfma_f32_32x32x16_bf16 v[96:111], v[182:185], v[186:189], v[96:111]
	global_load_dwordx4 v[140:143], v[190:191], off offset:2048
	global_load_dwordx4 v[186:189], v[242:243], off offset:2048
	v_mfma_f32_32x32x16_bf16 v[64:79], v[182:185], v[210:213], v[64:79]
	v_mfma_f32_32x32x16_bf16 v[32:47], v[182:185], v[218:221], v[32:47]
	v_mfma_f32_32x32x16_bf16 v[0:15], v[182:185], v[234:237], v[0:15]
	s_setprio 0
	s_setprio 2
	s_waitcnt vmcnt(11) lgkmcnt(3)
	v_mfma_f32_32x32x16_bf16 v[112:127], v[132:135], v[198:201], v[112:127]
	s_waitcnt lgkmcnt(2)
	v_mfma_f32_32x32x16_bf16 v[80:95], v[132:135], v[214:217], v[80:95]
	s_waitcnt lgkmcnt(1)
	v_mfma_f32_32x32x16_bf16 v[48:63], v[132:135], v[228:231], v[48:63]
	s_waitcnt lgkmcnt(0)
	v_mfma_f32_32x32x16_bf16 v[16:31], v[132:135], v[238:241], v[16:31]
	global_load_dwordx4 v[132:135], v[190:191], off offset:3072
	global_load_dwordx4 v[182:185], v[242:243], off offset:3072
	s_waitcnt vmcnt(12)
	v_mfma_f32_32x32x16_bf16 v[96:111], v[202:205], v[198:201], v[96:111]
	v_mfma_f32_32x32x16_bf16 v[64:79], v[202:205], v[214:217], v[64:79]
	v_mfma_f32_32x32x16_bf16 v[32:47], v[202:205], v[228:231], v[32:47]
	v_mfma_f32_32x32x16_bf16 v[0:15], v[202:205], v[238:241], v[0:15]
	s_setprio 0
	s_waitcnt vmcnt(8)
	ds_write_b128 v154, v[170:173] offset:18432
	ds_write_b128 v154, v[144:147] offset:23040
	ds_write_b128 v154, v[136:139] offset:27648
	ds_write_b128 v154, v[128:131] offset:32256
	global_load_dwordx4 v[128:131], v[158:159], off offset:768
	global_load_dwordx4 v[136:139], v[160:161], off offset:768
	global_load_dwordx4 v[144:147], v[162:163], off offset:768
	global_load_dwordx4 v[170:173], v[164:165], off offset:768
	s_waitcnt lgkmcnt(0)
	s_barrier
	ds_read_b128 v[198:201], v155 offset:18432
	ds_read_b128 v[202:205], v155 offset:18464
	ds_read_b128 v[210:213], v155 offset:23040
	ds_read_b128 v[214:217], v155 offset:23072
	ds_read_b128 v[218:221], v155 offset:27648
	ds_read_b128 v[228:231], v155 offset:27680
	ds_read_b128 v[234:237], v155 offset:32256
	ds_read_b128 v[238:241], v155 offset:32288
	s_setprio 2
	s_movk_i32 s8, 0x6000
	v_add_co_u32_e32 v190, vcc, s8, v156
	s_mov_b32 s8, 0x16000
	s_nop 0
	v_addc_co_u32_e32 v191, vcc, 0, v157, vcc
	v_add_co_u32_e32 v242, vcc, s8, v156
	s_waitcnt vmcnt(11) lgkmcnt(7)
	v_mfma_f32_32x32x16_bf16 v[112:127], v[174:177], v[198:201], v[112:127]
	v_addc_co_u32_e32 v243, vcc, 0, v157, vcc
	s_waitcnt lgkmcnt(5)
	v_mfma_f32_32x32x16_bf16 v[80:95], v[174:177], v[210:213], v[80:95]
	s_waitcnt lgkmcnt(3)
	v_mfma_f32_32x32x16_bf16 v[48:63], v[174:177], v[218:221], v[48:63]
	s_waitcnt lgkmcnt(1)
	v_mfma_f32_32x32x16_bf16 v[16:31], v[174:177], v[234:237], v[16:31]
	s_waitcnt vmcnt(10)
	v_mfma_f32_32x32x16_bf16 v[96:111], v[178:181], v[198:201], v[96:111]
	global_load_dwordx4 v[174:177], v[190:191], off
	global_load_dwordx4 v[198:201], v[242:243], off
	v_mfma_f32_32x32x16_bf16 v[64:79], v[178:181], v[210:213], v[64:79]
	v_mfma_f32_32x32x16_bf16 v[32:47], v[178:181], v[218:221], v[32:47]
	v_mfma_f32_32x32x16_bf16 v[0:15], v[178:181], v[234:237], v[0:15]
	s_setprio 0
	ds_read_b128 v[178:181], v155 offset:18496
	ds_read_b128 v[210:213], v155 offset:23104
	ds_read_b128 v[218:221], v155 offset:27712
	ds_read_b128 v[234:237], v155 offset:32320
	s_setprio 2
	s_waitcnt vmcnt(11)
	v_mfma_f32_32x32x16_bf16 v[112:127], v[148:151], v[202:205], v[112:127]
	v_mfma_f32_32x32x16_bf16 v[80:95], v[148:151], v[214:217], v[80:95]
	v_mfma_f32_32x32x16_bf16 v[48:63], v[148:151], v[228:231], v[48:63]
	s_waitcnt lgkmcnt(4)
	v_mfma_f32_32x32x16_bf16 v[16:31], v[148:151], v[238:241], v[16:31]
	s_waitcnt vmcnt(10)
	v_mfma_f32_32x32x16_bf16 v[96:111], v[206:209], v[202:205], v[96:111]
	global_load_dwordx4 v[148:151], v[190:191], off offset:1024
	global_load_dwordx4 v[202:205], v[242:243], off offset:1024
	v_mfma_f32_32x32x16_bf16 v[64:79], v[206:209], v[214:217], v[64:79]
	v_mfma_f32_32x32x16_bf16 v[32:47], v[206:209], v[228:231], v[32:47]
	v_mfma_f32_32x32x16_bf16 v[0:15], v[206:209], v[238:241], v[0:15]
	s_setprio 0
	ds_read_b128 v[206:209], v155 offset:18528
	ds_read_b128 v[214:217], v155 offset:23136
	ds_read_b128 v[228:231], v155 offset:27744
	ds_read_b128 v[238:241], v155 offset:32352
	s_setprio 2
	s_waitcnt vmcnt(11) lgkmcnt(7)
	v_mfma_f32_32x32x16_bf16 v[112:127], v[140:143], v[178:181], v[112:127]
	s_waitcnt lgkmcnt(6)
	v_mfma_f32_32x32x16_bf16 v[80:95], v[140:143], v[210:213], v[80:95]
	s_waitcnt lgkmcnt(5)
	v_mfma_f32_32x32x16_bf16 v[48:63], v[140:143], v[218:221], v[48:63]
	s_waitcnt lgkmcnt(4)
	v_mfma_f32_32x32x16_bf16 v[16:31], v[140:143], v[234:237], v[16:31]
	s_waitcnt vmcnt(10)
	v_mfma_f32_32x32x16_bf16 v[96:111], v[186:189], v[178:181], v[96:111]
	global_load_dwordx4 v[140:143], v[190:191], off offset:2048
	global_load_dwordx4 v[178:181], v[242:243], off offset:2048
	v_mfma_f32_32x32x16_bf16 v[64:79], v[186:189], v[210:213], v[64:79]
	v_mfma_f32_32x32x16_bf16 v[32:47], v[186:189], v[218:221], v[32:47]
	v_mfma_f32_32x32x16_bf16 v[0:15], v[186:189], v[234:237], v[0:15]
	s_setprio 0
	s_setprio 2
	s_waitcnt vmcnt(11) lgkmcnt(3)
	v_mfma_f32_32x32x16_bf16 v[112:127], v[132:135], v[206:209], v[112:127]
	s_waitcnt lgkmcnt(2)
	v_mfma_f32_32x32x16_bf16 v[80:95], v[132:135], v[214:217], v[80:95]
	s_waitcnt lgkmcnt(1)
	v_mfma_f32_32x32x16_bf16 v[48:63], v[132:135], v[228:231], v[48:63]
	s_waitcnt lgkmcnt(0)
	v_mfma_f32_32x32x16_bf16 v[16:31], v[132:135], v[238:241], v[16:31]
	global_load_dwordx4 v[132:135], v[190:191], off offset:3072
	global_load_dwordx4 v[186:189], v[242:243], off offset:3072
	s_waitcnt vmcnt(12)
	v_mfma_f32_32x32x16_bf16 v[96:111], v[182:185], v[206:209], v[96:111]
	v_mfma_f32_32x32x16_bf16 v[64:79], v[182:185], v[214:217], v[64:79]
	v_mfma_f32_32x32x16_bf16 v[32:47], v[182:185], v[228:231], v[32:47]
	v_mfma_f32_32x32x16_bf16 v[0:15], v[182:185], v[238:241], v[0:15]
	s_setprio 0
	s_waitcnt vmcnt(11)
	ds_write_b128 v154, v[128:131]
	s_waitcnt vmcnt(10)
	ds_write_b128 v154, v[136:139] offset:4608
	s_waitcnt vmcnt(9)
	ds_write_b128 v154, v[144:147] offset:9216
	s_waitcnt vmcnt(8)
	ds_write_b128 v154, v[170:173] offset:13824
	global_load_dwordx4 v[128:131], v[164:165], off offset:896
	global_load_dwordx4 v[136:139], v[162:163], off offset:896
	global_load_dwordx4 v[144:147], v[160:161], off offset:896
	global_load_dwordx4 v[170:173], v[158:159], off offset:896
	s_waitcnt lgkmcnt(0)
	s_barrier
	ds_read_b128 v[182:185], v155
	ds_read_b128 v[206:209], v155 offset:32
	ds_read_b128 v[210:213], v155 offset:4608
	ds_read_b128 v[214:217], v155 offset:4640
	ds_read_b128 v[218:221], v155 offset:9216
	ds_read_b128 v[228:231], v155 offset:9248
	ds_read_b128 v[234:237], v155 offset:13824
	ds_read_b128 v[238:241], v155 offset:13856
	s_setprio 2
	s_movk_i32 s8, 0x7000
	v_add_co_u32_e32 v190, vcc, s8, v156
	s_mov_b32 s8, 0x17000
	s_nop 0
	v_addc_co_u32_e32 v191, vcc, 0, v157, vcc
	v_add_co_u32_e32 v242, vcc, s8, v156
	s_waitcnt vmcnt(11) lgkmcnt(7)
	v_mfma_f32_32x32x16_bf16 v[112:127], v[174:177], v[182:185], v[112:127]
	v_addc_co_u32_e32 v243, vcc, 0, v157, vcc
	s_waitcnt lgkmcnt(5)
	v_mfma_f32_32x32x16_bf16 v[80:95], v[174:177], v[210:213], v[80:95]
	s_waitcnt lgkmcnt(3)
	v_mfma_f32_32x32x16_bf16 v[48:63], v[174:177], v[218:221], v[48:63]
	s_waitcnt lgkmcnt(1)
	v_mfma_f32_32x32x16_bf16 v[16:31], v[174:177], v[234:237], v[16:31]
	s_waitcnt vmcnt(10)
	v_mfma_f32_32x32x16_bf16 v[96:111], v[198:201], v[182:185], v[96:111]
	global_load_dwordx4 v[174:177], v[190:191], off
	global_load_dwordx4 v[182:185], v[242:243], off
	v_mfma_f32_32x32x16_bf16 v[64:79], v[198:201], v[210:213], v[64:79]
	v_mfma_f32_32x32x16_bf16 v[32:47], v[198:201], v[218:221], v[32:47]
	v_mfma_f32_32x32x16_bf16 v[0:15], v[198:201], v[234:237], v[0:15]
	s_setprio 0
	ds_read_b128 v[198:201], v155 offset:64
	ds_read_b128 v[210:213], v155 offset:4672
	ds_read_b128 v[218:221], v155 offset:9280
	ds_read_b128 v[234:237], v155 offset:13888
	s_setprio 2
	s_waitcnt vmcnt(11)
	v_mfma_f32_32x32x16_bf16 v[112:127], v[148:151], v[206:209], v[112:127]
	v_mfma_f32_32x32x16_bf16 v[80:95], v[148:151], v[214:217], v[80:95]
	v_mfma_f32_32x32x16_bf16 v[48:63], v[148:151], v[228:231], v[48:63]
	s_waitcnt lgkmcnt(4)
	v_mfma_f32_32x32x16_bf16 v[16:31], v[148:151], v[238:241], v[16:31]
	s_waitcnt vmcnt(10)
	v_mfma_f32_32x32x16_bf16 v[96:111], v[202:205], v[206:209], v[96:111]
	global_load_dwordx4 v[148:151], v[190:191], off offset:1024
	global_load_dwordx4 v[206:209], v[242:243], off offset:1024
	v_mfma_f32_32x32x16_bf16 v[64:79], v[202:205], v[214:217], v[64:79]
	v_mfma_f32_32x32x16_bf16 v[32:47], v[202:205], v[228:231], v[32:47]
	v_mfma_f32_32x32x16_bf16 v[0:15], v[202:205], v[238:241], v[0:15]
	s_setprio 0
	ds_read_b128 v[202:205], v155 offset:96
	ds_read_b128 v[214:217], v155 offset:4704
	ds_read_b128 v[228:231], v155 offset:9312
	ds_read_b128 v[238:241], v155 offset:13920
	s_setprio 2
	s_waitcnt vmcnt(11) lgkmcnt(7)
	v_mfma_f32_32x32x16_bf16 v[112:127], v[140:143], v[198:201], v[112:127]
	s_waitcnt lgkmcnt(6)
	v_mfma_f32_32x32x16_bf16 v[80:95], v[140:143], v[210:213], v[80:95]
	s_waitcnt lgkmcnt(5)
	v_mfma_f32_32x32x16_bf16 v[48:63], v[140:143], v[218:221], v[48:63]
	s_waitcnt lgkmcnt(4)
	v_mfma_f32_32x32x16_bf16 v[16:31], v[140:143], v[234:237], v[16:31]
	s_waitcnt vmcnt(10)
	v_mfma_f32_32x32x16_bf16 v[96:111], v[178:181], v[198:201], v[96:111]
	global_load_dwordx4 v[140:143], v[190:191], off offset:2048
	global_load_dwordx4 v[198:201], v[242:243], off offset:2048
	v_mfma_f32_32x32x16_bf16 v[64:79], v[178:181], v[210:213], v[64:79]
	v_mfma_f32_32x32x16_bf16 v[32:47], v[178:181], v[218:221], v[32:47]
	v_mfma_f32_32x32x16_bf16 v[0:15], v[178:181], v[234:237], v[0:15]
	s_setprio 0
	s_setprio 2
	s_waitcnt vmcnt(11) lgkmcnt(3)
	v_mfma_f32_32x32x16_bf16 v[112:127], v[132:135], v[202:205], v[112:127]
	s_waitcnt lgkmcnt(2)
	v_mfma_f32_32x32x16_bf16 v[80:95], v[132:135], v[214:217], v[80:95]
	s_waitcnt lgkmcnt(1)
	v_mfma_f32_32x32x16_bf16 v[48:63], v[132:135], v[228:231], v[48:63]
	s_waitcnt lgkmcnt(0)
	v_mfma_f32_32x32x16_bf16 v[16:31], v[132:135], v[238:241], v[16:31]
	global_load_dwordx4 v[132:135], v[190:191], off offset:3072
	global_load_dwordx4 v[178:181], v[242:243], off offset:3072
	s_waitcnt vmcnt(12)
	v_mfma_f32_32x32x16_bf16 v[96:111], v[186:189], v[202:205], v[96:111]
	v_mfma_f32_32x32x16_bf16 v[64:79], v[186:189], v[214:217], v[64:79]
	v_mfma_f32_32x32x16_bf16 v[32:47], v[186:189], v[228:231], v[32:47]
	v_mfma_f32_32x32x16_bf16 v[0:15], v[186:189], v[238:241], v[0:15]
	s_setprio 0
	s_waitcnt vmcnt(8)
	ds_write_b128 v154, v[170:173] offset:18432
	ds_write_b128 v154, v[144:147] offset:23040
	ds_write_b128 v154, v[136:139] offset:27648
	ds_write_b128 v154, v[128:131] offset:32256
	global_load_dwordx4 v[128:131], v[158:159], off offset:1024
	global_load_dwordx4 v[136:139], v[160:161], off offset:1024
	global_load_dwordx4 v[144:147], v[162:163], off offset:1024
	global_load_dwordx4 v[170:173], v[164:165], off offset:1024
	s_waitcnt lgkmcnt(0)
	s_barrier
	ds_read_b128 v[186:189], v155 offset:18432
	ds_read_b128 v[202:205], v155 offset:18464
	ds_read_b128 v[210:213], v155 offset:23040
	ds_read_b128 v[214:217], v155 offset:23072
	ds_read_b128 v[218:221], v155 offset:27648
	ds_read_b128 v[228:231], v155 offset:27680
	ds_read_b128 v[234:237], v155 offset:32256
	ds_read_b128 v[238:241], v155 offset:32288
	s_setprio 2
	s_mov_b32 s8, 0x8000
	v_add_co_u32_e32 v190, vcc, s8, v156
	s_mov_b32 s8, 0x18000
	s_nop 0
	v_addc_co_u32_e32 v191, vcc, 0, v157, vcc
	v_add_co_u32_e32 v242, vcc, s8, v156
	s_waitcnt vmcnt(11) lgkmcnt(7)
	v_mfma_f32_32x32x16_bf16 v[112:127], v[174:177], v[186:189], v[112:127]
	v_addc_co_u32_e32 v243, vcc, 0, v157, vcc
	s_waitcnt lgkmcnt(5)
	v_mfma_f32_32x32x16_bf16 v[80:95], v[174:177], v[210:213], v[80:95]
	s_waitcnt lgkmcnt(3)
	v_mfma_f32_32x32x16_bf16 v[48:63], v[174:177], v[218:221], v[48:63]
	s_waitcnt lgkmcnt(1)
	v_mfma_f32_32x32x16_bf16 v[16:31], v[174:177], v[234:237], v[16:31]
	s_waitcnt vmcnt(10)
	v_mfma_f32_32x32x16_bf16 v[96:111], v[182:185], v[186:189], v[96:111]
	global_load_dwordx4 v[174:177], v[190:191], off
	global_load_dwordx4 v[186:189], v[242:243], off
	v_mfma_f32_32x32x16_bf16 v[64:79], v[182:185], v[210:213], v[64:79]
	v_mfma_f32_32x32x16_bf16 v[32:47], v[182:185], v[218:221], v[32:47]
	v_mfma_f32_32x32x16_bf16 v[0:15], v[182:185], v[234:237], v[0:15]
	s_setprio 0
	ds_read_b128 v[182:185], v155 offset:18496
	ds_read_b128 v[210:213], v155 offset:23104
	ds_read_b128 v[218:221], v155 offset:27712
	ds_read_b128 v[234:237], v155 offset:32320
	s_setprio 2
	s_waitcnt vmcnt(11)
	v_mfma_f32_32x32x16_bf16 v[112:127], v[148:151], v[202:205], v[112:127]
	v_mfma_f32_32x32x16_bf16 v[80:95], v[148:151], v[214:217], v[80:95]
	v_mfma_f32_32x32x16_bf16 v[48:63], v[148:151], v[228:231], v[48:63]
	s_waitcnt lgkmcnt(4)
	v_mfma_f32_32x32x16_bf16 v[16:31], v[148:151], v[238:241], v[16:31]
	s_waitcnt vmcnt(10)
	v_mfma_f32_32x32x16_bf16 v[96:111], v[206:209], v[202:205], v[96:111]
	global_load_dwordx4 v[148:151], v[190:191], off offset:1024
	global_load_dwordx4 v[202:205], v[242:243], off offset:1024
	v_mfma_f32_32x32x16_bf16 v[64:79], v[206:209], v[214:217], v[64:79]
	v_mfma_f32_32x32x16_bf16 v[32:47], v[206:209], v[228:231], v[32:47]
	v_mfma_f32_32x32x16_bf16 v[0:15], v[206:209], v[238:241], v[0:15]
	s_setprio 0
	ds_read_b128 v[206:209], v155 offset:18528
	ds_read_b128 v[214:217], v155 offset:23136
	ds_read_b128 v[228:231], v155 offset:27744
	ds_read_b128 v[238:241], v155 offset:32352
	s_setprio 2
	s_waitcnt vmcnt(11) lgkmcnt(7)
	v_mfma_f32_32x32x16_bf16 v[112:127], v[140:143], v[182:185], v[112:127]
	s_waitcnt lgkmcnt(6)
	v_mfma_f32_32x32x16_bf16 v[80:95], v[140:143], v[210:213], v[80:95]
	s_waitcnt lgkmcnt(5)
	v_mfma_f32_32x32x16_bf16 v[48:63], v[140:143], v[218:221], v[48:63]
	s_waitcnt lgkmcnt(4)
	v_mfma_f32_32x32x16_bf16 v[16:31], v[140:143], v[234:237], v[16:31]
	s_waitcnt vmcnt(10)
	v_mfma_f32_32x32x16_bf16 v[96:111], v[198:201], v[182:185], v[96:111]
	global_load_dwordx4 v[140:143], v[190:191], off offset:2048
	global_load_dwordx4 v[182:185], v[242:243], off offset:2048
	v_mfma_f32_32x32x16_bf16 v[64:79], v[198:201], v[210:213], v[64:79]
	v_mfma_f32_32x32x16_bf16 v[32:47], v[198:201], v[218:221], v[32:47]
	v_mfma_f32_32x32x16_bf16 v[0:15], v[198:201], v[234:237], v[0:15]
	s_setprio 0
	s_setprio 2
	s_waitcnt vmcnt(11) lgkmcnt(3)
	v_mfma_f32_32x32x16_bf16 v[112:127], v[132:135], v[206:209], v[112:127]
	s_waitcnt lgkmcnt(2)
	v_mfma_f32_32x32x16_bf16 v[80:95], v[132:135], v[214:217], v[80:95]
	s_waitcnt lgkmcnt(1)
	v_mfma_f32_32x32x16_bf16 v[48:63], v[132:135], v[228:231], v[48:63]
	s_waitcnt lgkmcnt(0)
	v_mfma_f32_32x32x16_bf16 v[16:31], v[132:135], v[238:241], v[16:31]
	global_load_dwordx4 v[132:135], v[190:191], off offset:3072
	global_load_dwordx4 v[198:201], v[242:243], off offset:3072
	s_waitcnt vmcnt(12)
	v_mfma_f32_32x32x16_bf16 v[96:111], v[178:181], v[206:209], v[96:111]
	v_mfma_f32_32x32x16_bf16 v[64:79], v[178:181], v[214:217], v[64:79]
	v_mfma_f32_32x32x16_bf16 v[32:47], v[178:181], v[228:231], v[32:47]
	v_mfma_f32_32x32x16_bf16 v[0:15], v[178:181], v[238:241], v[0:15]
	s_setprio 0
	s_waitcnt vmcnt(11)
	ds_write_b128 v154, v[128:131]
	s_waitcnt vmcnt(10)
	ds_write_b128 v154, v[136:139] offset:4608
	s_waitcnt vmcnt(9)
	ds_write_b128 v154, v[144:147] offset:9216
	s_waitcnt vmcnt(8)
	ds_write_b128 v154, v[170:173] offset:13824
	global_load_dwordx4 v[128:131], v[164:165], off offset:1152
	global_load_dwordx4 v[136:139], v[162:163], off offset:1152
	global_load_dwordx4 v[144:147], v[160:161], off offset:1152
	global_load_dwordx4 v[170:173], v[158:159], off offset:1152
	s_waitcnt lgkmcnt(0)
	s_barrier
	ds_read_b128 v[178:181], v155
	ds_read_b128 v[206:209], v155 offset:32
	ds_read_b128 v[210:213], v155 offset:4608
	ds_read_b128 v[214:217], v155 offset:4640
	ds_read_b128 v[218:221], v155 offset:9216
	ds_read_b128 v[228:231], v155 offset:9248
	ds_read_b128 v[234:237], v155 offset:13824
	ds_read_b128 v[238:241], v155 offset:13856
	s_setprio 2
	s_mov_b32 s8, 0x9000
	v_add_co_u32_e32 v190, vcc, s8, v156
	s_mov_b32 s8, 0x19000
	s_nop 0
	v_addc_co_u32_e32 v191, vcc, 0, v157, vcc
	v_add_co_u32_e32 v242, vcc, s8, v156
	s_waitcnt vmcnt(11) lgkmcnt(7)
	v_mfma_f32_32x32x16_bf16 v[112:127], v[174:177], v[178:181], v[112:127]
	v_addc_co_u32_e32 v243, vcc, 0, v157, vcc
	s_waitcnt lgkmcnt(5)
	v_mfma_f32_32x32x16_bf16 v[80:95], v[174:177], v[210:213], v[80:95]
	s_waitcnt lgkmcnt(3)
	v_mfma_f32_32x32x16_bf16 v[48:63], v[174:177], v[218:221], v[48:63]
	s_waitcnt lgkmcnt(1)
	v_mfma_f32_32x32x16_bf16 v[16:31], v[174:177], v[234:237], v[16:31]
	s_waitcnt vmcnt(10)
	v_mfma_f32_32x32x16_bf16 v[96:111], v[186:189], v[178:181], v[96:111]
	global_load_dwordx4 v[174:177], v[190:191], off
	global_load_dwordx4 v[178:181], v[242:243], off
	v_mfma_f32_32x32x16_bf16 v[64:79], v[186:189], v[210:213], v[64:79]
	v_mfma_f32_32x32x16_bf16 v[32:47], v[186:189], v[218:221], v[32:47]
	v_mfma_f32_32x32x16_bf16 v[0:15], v[186:189], v[234:237], v[0:15]
	s_setprio 0
	ds_read_b128 v[186:189], v155 offset:64
	ds_read_b128 v[210:213], v155 offset:4672
	ds_read_b128 v[218:221], v155 offset:9280
	ds_read_b128 v[234:237], v155 offset:13888
	s_setprio 2
	s_waitcnt vmcnt(11)
	v_mfma_f32_32x32x16_bf16 v[112:127], v[148:151], v[206:209], v[112:127]
	v_mfma_f32_32x32x16_bf16 v[80:95], v[148:151], v[214:217], v[80:95]
	v_mfma_f32_32x32x16_bf16 v[48:63], v[148:151], v[228:231], v[48:63]
	s_waitcnt lgkmcnt(4)
	v_mfma_f32_32x32x16_bf16 v[16:31], v[148:151], v[238:241], v[16:31]
	s_waitcnt vmcnt(10)
	v_mfma_f32_32x32x16_bf16 v[96:111], v[202:205], v[206:209], v[96:111]
	global_load_dwordx4 v[148:151], v[190:191], off offset:1024
	global_load_dwordx4 v[206:209], v[242:243], off offset:1024
	v_mfma_f32_32x32x16_bf16 v[64:79], v[202:205], v[214:217], v[64:79]
	v_mfma_f32_32x32x16_bf16 v[32:47], v[202:205], v[228:231], v[32:47]
	v_mfma_f32_32x32x16_bf16 v[0:15], v[202:205], v[238:241], v[0:15]
	s_setprio 0
	ds_read_b128 v[202:205], v155 offset:96
	ds_read_b128 v[214:217], v155 offset:4704
	ds_read_b128 v[228:231], v155 offset:9312
	ds_read_b128 v[238:241], v155 offset:13920
	s_setprio 2
	s_waitcnt vmcnt(11) lgkmcnt(7)
	v_mfma_f32_32x32x16_bf16 v[112:127], v[140:143], v[186:189], v[112:127]
	s_waitcnt lgkmcnt(6)
	v_mfma_f32_32x32x16_bf16 v[80:95], v[140:143], v[210:213], v[80:95]
	s_waitcnt lgkmcnt(5)
	v_mfma_f32_32x32x16_bf16 v[48:63], v[140:143], v[218:221], v[48:63]
	s_waitcnt lgkmcnt(4)
	v_mfma_f32_32x32x16_bf16 v[16:31], v[140:143], v[234:237], v[16:31]
	s_waitcnt vmcnt(10)
	v_mfma_f32_32x32x16_bf16 v[96:111], v[182:185], v[186:189], v[96:111]
	global_load_dwordx4 v[140:143], v[190:191], off offset:2048
	global_load_dwordx4 v[186:189], v[242:243], off offset:2048
	v_mfma_f32_32x32x16_bf16 v[64:79], v[182:185], v[210:213], v[64:79]
	v_mfma_f32_32x32x16_bf16 v[32:47], v[182:185], v[218:221], v[32:47]
	v_mfma_f32_32x32x16_bf16 v[0:15], v[182:185], v[234:237], v[0:15]
	s_setprio 0
	s_setprio 2
	s_waitcnt vmcnt(11) lgkmcnt(3)
	v_mfma_f32_32x32x16_bf16 v[112:127], v[132:135], v[202:205], v[112:127]
	s_waitcnt lgkmcnt(2)
	v_mfma_f32_32x32x16_bf16 v[80:95], v[132:135], v[214:217], v[80:95]
	s_waitcnt lgkmcnt(1)
	v_mfma_f32_32x32x16_bf16 v[48:63], v[132:135], v[228:231], v[48:63]
	s_waitcnt lgkmcnt(0)
	v_mfma_f32_32x32x16_bf16 v[16:31], v[132:135], v[238:241], v[16:31]
	global_load_dwordx4 v[132:135], v[190:191], off offset:3072
	global_load_dwordx4 v[182:185], v[242:243], off offset:3072
	s_waitcnt vmcnt(12)
	v_mfma_f32_32x32x16_bf16 v[96:111], v[198:201], v[202:205], v[96:111]
	v_mfma_f32_32x32x16_bf16 v[64:79], v[198:201], v[214:217], v[64:79]
	v_mfma_f32_32x32x16_bf16 v[32:47], v[198:201], v[228:231], v[32:47]
	v_mfma_f32_32x32x16_bf16 v[0:15], v[198:201], v[238:241], v[0:15]
	s_setprio 0
	s_waitcnt vmcnt(8)
	ds_write_b128 v154, v[170:173] offset:18432
	ds_write_b128 v154, v[144:147] offset:23040
	ds_write_b128 v154, v[136:139] offset:27648
	ds_write_b128 v154, v[128:131] offset:32256
	global_load_dwordx4 v[128:131], v[158:159], off offset:1280
	global_load_dwordx4 v[136:139], v[160:161], off offset:1280
	global_load_dwordx4 v[144:147], v[162:163], off offset:1280
	global_load_dwordx4 v[170:173], v[164:165], off offset:1280
	s_waitcnt lgkmcnt(0)
	s_barrier
	ds_read_b128 v[198:201], v155 offset:18432
	ds_read_b128 v[202:205], v155 offset:18464
	ds_read_b128 v[210:213], v155 offset:23040
	ds_read_b128 v[214:217], v155 offset:23072
	ds_read_b128 v[218:221], v155 offset:27648
	ds_read_b128 v[228:231], v155 offset:27680
	ds_read_b128 v[234:237], v155 offset:32256
	ds_read_b128 v[238:241], v155 offset:32288
	s_setprio 2
	s_mov_b32 s8, 0xa000
	v_add_co_u32_e32 v190, vcc, s8, v156
	s_mov_b32 s8, 0x1a000
	s_nop 0
	v_addc_co_u32_e32 v191, vcc, 0, v157, vcc
	v_add_co_u32_e32 v242, vcc, s8, v156
	s_waitcnt vmcnt(11) lgkmcnt(7)
	v_mfma_f32_32x32x16_bf16 v[112:127], v[174:177], v[198:201], v[112:127]
	v_addc_co_u32_e32 v243, vcc, 0, v157, vcc
	s_waitcnt lgkmcnt(5)
	v_mfma_f32_32x32x16_bf16 v[80:95], v[174:177], v[210:213], v[80:95]
	s_waitcnt lgkmcnt(3)
	v_mfma_f32_32x32x16_bf16 v[48:63], v[174:177], v[218:221], v[48:63]
	s_waitcnt lgkmcnt(1)
	v_mfma_f32_32x32x16_bf16 v[16:31], v[174:177], v[234:237], v[16:31]
	s_waitcnt vmcnt(10)
	v_mfma_f32_32x32x16_bf16 v[96:111], v[178:181], v[198:201], v[96:111]
	global_load_dwordx4 v[174:177], v[190:191], off
	global_load_dwordx4 v[198:201], v[242:243], off
	v_mfma_f32_32x32x16_bf16 v[64:79], v[178:181], v[210:213], v[64:79]
	v_mfma_f32_32x32x16_bf16 v[32:47], v[178:181], v[218:221], v[32:47]
	v_mfma_f32_32x32x16_bf16 v[0:15], v[178:181], v[234:237], v[0:15]
	s_setprio 0
	ds_read_b128 v[178:181], v155 offset:18496
	ds_read_b128 v[210:213], v155 offset:23104
	ds_read_b128 v[218:221], v155 offset:27712
	ds_read_b128 v[234:237], v155 offset:32320
	s_setprio 2
	s_waitcnt vmcnt(11)
	v_mfma_f32_32x32x16_bf16 v[112:127], v[148:151], v[202:205], v[112:127]
	v_mfma_f32_32x32x16_bf16 v[80:95], v[148:151], v[214:217], v[80:95]
	v_mfma_f32_32x32x16_bf16 v[48:63], v[148:151], v[228:231], v[48:63]
	s_waitcnt lgkmcnt(4)
	v_mfma_f32_32x32x16_bf16 v[16:31], v[148:151], v[238:241], v[16:31]
	s_waitcnt vmcnt(10)
	v_mfma_f32_32x32x16_bf16 v[96:111], v[206:209], v[202:205], v[96:111]
	global_load_dwordx4 v[148:151], v[190:191], off offset:1024
	global_load_dwordx4 v[202:205], v[242:243], off offset:1024
	v_mfma_f32_32x32x16_bf16 v[64:79], v[206:209], v[214:217], v[64:79]
	v_mfma_f32_32x32x16_bf16 v[32:47], v[206:209], v[228:231], v[32:47]
	v_mfma_f32_32x32x16_bf16 v[0:15], v[206:209], v[238:241], v[0:15]
	s_setprio 0
	ds_read_b128 v[206:209], v155 offset:18528
	ds_read_b128 v[214:217], v155 offset:23136
	ds_read_b128 v[228:231], v155 offset:27744
	ds_read_b128 v[238:241], v155 offset:32352
	s_setprio 2
	s_waitcnt vmcnt(11) lgkmcnt(7)
	v_mfma_f32_32x32x16_bf16 v[112:127], v[140:143], v[178:181], v[112:127]
	s_waitcnt lgkmcnt(6)
	v_mfma_f32_32x32x16_bf16 v[80:95], v[140:143], v[210:213], v[80:95]
	s_waitcnt lgkmcnt(5)
	v_mfma_f32_32x32x16_bf16 v[48:63], v[140:143], v[218:221], v[48:63]
	s_waitcnt lgkmcnt(4)
	v_mfma_f32_32x32x16_bf16 v[16:31], v[140:143], v[234:237], v[16:31]
	s_waitcnt vmcnt(10)
	v_mfma_f32_32x32x16_bf16 v[96:111], v[186:189], v[178:181], v[96:111]
	global_load_dwordx4 v[140:143], v[190:191], off offset:2048
	global_load_dwordx4 v[178:181], v[242:243], off offset:2048
	v_mfma_f32_32x32x16_bf16 v[64:79], v[186:189], v[210:213], v[64:79]
	v_mfma_f32_32x32x16_bf16 v[32:47], v[186:189], v[218:221], v[32:47]
	v_mfma_f32_32x32x16_bf16 v[0:15], v[186:189], v[234:237], v[0:15]
	s_setprio 0
	s_setprio 2
	s_waitcnt vmcnt(11) lgkmcnt(3)
	v_mfma_f32_32x32x16_bf16 v[112:127], v[132:135], v[206:209], v[112:127]
	s_waitcnt lgkmcnt(2)
	v_mfma_f32_32x32x16_bf16 v[80:95], v[132:135], v[214:217], v[80:95]
	s_waitcnt lgkmcnt(1)
	v_mfma_f32_32x32x16_bf16 v[48:63], v[132:135], v[228:231], v[48:63]
	s_waitcnt lgkmcnt(0)
	v_mfma_f32_32x32x16_bf16 v[16:31], v[132:135], v[238:241], v[16:31]
	global_load_dwordx4 v[132:135], v[190:191], off offset:3072
	global_load_dwordx4 v[186:189], v[242:243], off offset:3072
	s_waitcnt vmcnt(12)
	v_mfma_f32_32x32x16_bf16 v[96:111], v[182:185], v[206:209], v[96:111]
	v_mfma_f32_32x32x16_bf16 v[64:79], v[182:185], v[214:217], v[64:79]
	v_mfma_f32_32x32x16_bf16 v[32:47], v[182:185], v[228:231], v[32:47]
	v_mfma_f32_32x32x16_bf16 v[0:15], v[182:185], v[238:241], v[0:15]
	s_setprio 0
	s_waitcnt vmcnt(11)
	ds_write_b128 v154, v[128:131]
	s_waitcnt vmcnt(10)
	ds_write_b128 v154, v[136:139] offset:4608
	s_waitcnt vmcnt(9)
	ds_write_b128 v154, v[144:147] offset:9216
	s_waitcnt vmcnt(8)
	ds_write_b128 v154, v[170:173] offset:13824
	global_load_dwordx4 v[128:131], v[164:165], off offset:1408
	global_load_dwordx4 v[136:139], v[162:163], off offset:1408
	global_load_dwordx4 v[144:147], v[160:161], off offset:1408
	global_load_dwordx4 v[170:173], v[158:159], off offset:1408
	s_waitcnt lgkmcnt(0)
	s_barrier
	ds_read_b128 v[182:185], v155
	ds_read_b128 v[206:209], v155 offset:32
	ds_read_b128 v[210:213], v155 offset:4608
	ds_read_b128 v[214:217], v155 offset:4640
	ds_read_b128 v[218:221], v155 offset:9216
	ds_read_b128 v[228:231], v155 offset:9248
	ds_read_b128 v[234:237], v155 offset:13824
	ds_read_b128 v[238:241], v155 offset:13856
	s_setprio 2
	s_mov_b32 s8, 0xb000
	v_add_co_u32_e32 v190, vcc, s8, v156
	s_mov_b32 s8, 0x1b000
	s_nop 0
	v_addc_co_u32_e32 v191, vcc, 0, v157, vcc
	v_add_co_u32_e32 v242, vcc, s8, v156
	s_waitcnt vmcnt(11) lgkmcnt(7)
	v_mfma_f32_32x32x16_bf16 v[112:127], v[174:177], v[182:185], v[112:127]
	v_addc_co_u32_e32 v243, vcc, 0, v157, vcc
	s_waitcnt lgkmcnt(5)
	v_mfma_f32_32x32x16_bf16 v[80:95], v[174:177], v[210:213], v[80:95]
	s_waitcnt lgkmcnt(3)
	v_mfma_f32_32x32x16_bf16 v[48:63], v[174:177], v[218:221], v[48:63]
	s_waitcnt lgkmcnt(1)
	v_mfma_f32_32x32x16_bf16 v[16:31], v[174:177], v[234:237], v[16:31]
	s_waitcnt vmcnt(10)
	v_mfma_f32_32x32x16_bf16 v[96:111], v[198:201], v[182:185], v[96:111]
	global_load_dwordx4 v[174:177], v[190:191], off
	global_load_dwordx4 v[182:185], v[242:243], off
	v_mfma_f32_32x32x16_bf16 v[64:79], v[198:201], v[210:213], v[64:79]
	v_mfma_f32_32x32x16_bf16 v[32:47], v[198:201], v[218:221], v[32:47]
	v_mfma_f32_32x32x16_bf16 v[0:15], v[198:201], v[234:237], v[0:15]
	s_setprio 0
	ds_read_b128 v[198:201], v155 offset:64
	ds_read_b128 v[210:213], v155 offset:4672
	ds_read_b128 v[218:221], v155 offset:9280
	ds_read_b128 v[234:237], v155 offset:13888
	s_setprio 2
	s_waitcnt vmcnt(11)
	v_mfma_f32_32x32x16_bf16 v[112:127], v[148:151], v[206:209], v[112:127]
	v_mfma_f32_32x32x16_bf16 v[80:95], v[148:151], v[214:217], v[80:95]
	v_mfma_f32_32x32x16_bf16 v[48:63], v[148:151], v[228:231], v[48:63]
	s_waitcnt lgkmcnt(4)
	v_mfma_f32_32x32x16_bf16 v[16:31], v[148:151], v[238:241], v[16:31]
	s_waitcnt vmcnt(10)
	v_mfma_f32_32x32x16_bf16 v[96:111], v[202:205], v[206:209], v[96:111]
	global_load_dwordx4 v[148:151], v[190:191], off offset:1024
	global_load_dwordx4 v[206:209], v[242:243], off offset:1024
	v_mfma_f32_32x32x16_bf16 v[64:79], v[202:205], v[214:217], v[64:79]
	v_mfma_f32_32x32x16_bf16 v[32:47], v[202:205], v[228:231], v[32:47]
	v_mfma_f32_32x32x16_bf16 v[0:15], v[202:205], v[238:241], v[0:15]
	s_setprio 0
	ds_read_b128 v[202:205], v155 offset:96
	ds_read_b128 v[214:217], v155 offset:4704
	ds_read_b128 v[228:231], v155 offset:9312
	ds_read_b128 v[238:241], v155 offset:13920
	s_setprio 2
	s_waitcnt vmcnt(11) lgkmcnt(7)
	v_mfma_f32_32x32x16_bf16 v[112:127], v[140:143], v[198:201], v[112:127]
	s_waitcnt lgkmcnt(6)
	v_mfma_f32_32x32x16_bf16 v[80:95], v[140:143], v[210:213], v[80:95]
	s_waitcnt lgkmcnt(5)
	v_mfma_f32_32x32x16_bf16 v[48:63], v[140:143], v[218:221], v[48:63]
	s_waitcnt lgkmcnt(4)
	v_mfma_f32_32x32x16_bf16 v[16:31], v[140:143], v[234:237], v[16:31]
	s_waitcnt vmcnt(10)
	v_mfma_f32_32x32x16_bf16 v[96:111], v[178:181], v[198:201], v[96:111]
	global_load_dwordx4 v[140:143], v[190:191], off offset:2048
	global_load_dwordx4 v[198:201], v[242:243], off offset:2048
	v_mfma_f32_32x32x16_bf16 v[64:79], v[178:181], v[210:213], v[64:79]
	v_mfma_f32_32x32x16_bf16 v[32:47], v[178:181], v[218:221], v[32:47]
	v_mfma_f32_32x32x16_bf16 v[0:15], v[178:181], v[234:237], v[0:15]
	s_setprio 0
	s_setprio 2
	s_waitcnt vmcnt(11) lgkmcnt(3)
	v_mfma_f32_32x32x16_bf16 v[112:127], v[132:135], v[202:205], v[112:127]
	s_waitcnt lgkmcnt(2)
	v_mfma_f32_32x32x16_bf16 v[80:95], v[132:135], v[214:217], v[80:95]
	s_waitcnt lgkmcnt(1)
	v_mfma_f32_32x32x16_bf16 v[48:63], v[132:135], v[228:231], v[48:63]
	s_waitcnt lgkmcnt(0)
	v_mfma_f32_32x32x16_bf16 v[16:31], v[132:135], v[238:241], v[16:31]
	global_load_dwordx4 v[132:135], v[190:191], off offset:3072
	global_load_dwordx4 v[178:181], v[242:243], off offset:3072
	s_waitcnt vmcnt(12)
	v_mfma_f32_32x32x16_bf16 v[96:111], v[186:189], v[202:205], v[96:111]
	v_mfma_f32_32x32x16_bf16 v[64:79], v[186:189], v[214:217], v[64:79]
	v_mfma_f32_32x32x16_bf16 v[32:47], v[186:189], v[228:231], v[32:47]
	v_mfma_f32_32x32x16_bf16 v[0:15], v[186:189], v[238:241], v[0:15]
	s_setprio 0
	s_waitcnt vmcnt(8)
	ds_write_b128 v154, v[170:173] offset:18432
	ds_write_b128 v154, v[144:147] offset:23040
	ds_write_b128 v154, v[136:139] offset:27648
	ds_write_b128 v154, v[128:131] offset:32256
	global_load_dwordx4 v[128:131], v[158:159], off offset:1536
	global_load_dwordx4 v[136:139], v[160:161], off offset:1536
	global_load_dwordx4 v[144:147], v[162:163], off offset:1536
	global_load_dwordx4 v[170:173], v[164:165], off offset:1536
	s_waitcnt lgkmcnt(0)
	s_barrier
	ds_read_b128 v[186:189], v155 offset:18432
	ds_read_b128 v[202:205], v155 offset:18464
	ds_read_b128 v[210:213], v155 offset:23040
	ds_read_b128 v[214:217], v155 offset:23072
	ds_read_b128 v[218:221], v155 offset:27648
	ds_read_b128 v[228:231], v155 offset:27680
	ds_read_b128 v[234:237], v155 offset:32256
	ds_read_b128 v[238:241], v155 offset:32288
	s_setprio 2
	s_mov_b32 s8, 0xc000
	v_add_co_u32_e32 v190, vcc, s8, v156
	s_mov_b32 s8, 0x1c000
	s_nop 0
	v_addc_co_u32_e32 v191, vcc, 0, v157, vcc
	v_add_co_u32_e32 v242, vcc, s8, v156
	s_waitcnt vmcnt(11) lgkmcnt(7)
	v_mfma_f32_32x32x16_bf16 v[112:127], v[174:177], v[186:189], v[112:127]
	v_addc_co_u32_e32 v243, vcc, 0, v157, vcc
	s_waitcnt lgkmcnt(5)
	v_mfma_f32_32x32x16_bf16 v[80:95], v[174:177], v[210:213], v[80:95]
	s_waitcnt lgkmcnt(3)
	v_mfma_f32_32x32x16_bf16 v[48:63], v[174:177], v[218:221], v[48:63]
	s_waitcnt lgkmcnt(1)
	v_mfma_f32_32x32x16_bf16 v[16:31], v[174:177], v[234:237], v[16:31]
	s_waitcnt vmcnt(10)
	v_mfma_f32_32x32x16_bf16 v[96:111], v[182:185], v[186:189], v[96:111]
	global_load_dwordx4 v[174:177], v[190:191], off
	global_load_dwordx4 v[186:189], v[242:243], off
	v_mfma_f32_32x32x16_bf16 v[64:79], v[182:185], v[210:213], v[64:79]
	v_mfma_f32_32x32x16_bf16 v[32:47], v[182:185], v[218:221], v[32:47]
	v_mfma_f32_32x32x16_bf16 v[0:15], v[182:185], v[234:237], v[0:15]
	s_setprio 0
	ds_read_b128 v[182:185], v155 offset:18496
	ds_read_b128 v[210:213], v155 offset:23104
	ds_read_b128 v[218:221], v155 offset:27712
	ds_read_b128 v[234:237], v155 offset:32320
	s_setprio 2
	s_waitcnt vmcnt(11)
	v_mfma_f32_32x32x16_bf16 v[112:127], v[148:151], v[202:205], v[112:127]
	v_mfma_f32_32x32x16_bf16 v[80:95], v[148:151], v[214:217], v[80:95]
	v_mfma_f32_32x32x16_bf16 v[48:63], v[148:151], v[228:231], v[48:63]
	s_waitcnt lgkmcnt(4)
	v_mfma_f32_32x32x16_bf16 v[16:31], v[148:151], v[238:241], v[16:31]
	s_waitcnt vmcnt(10)
	v_mfma_f32_32x32x16_bf16 v[96:111], v[206:209], v[202:205], v[96:111]
	global_load_dwordx4 v[148:151], v[190:191], off offset:1024
	global_load_dwordx4 v[202:205], v[242:243], off offset:1024
	v_mfma_f32_32x32x16_bf16 v[64:79], v[206:209], v[214:217], v[64:79]
	v_mfma_f32_32x32x16_bf16 v[32:47], v[206:209], v[228:231], v[32:47]
	v_mfma_f32_32x32x16_bf16 v[0:15], v[206:209], v[238:241], v[0:15]
	s_setprio 0
	ds_read_b128 v[206:209], v155 offset:18528
	ds_read_b128 v[214:217], v155 offset:23136
	ds_read_b128 v[228:231], v155 offset:27744
	ds_read_b128 v[238:241], v155 offset:32352
	s_setprio 2
	s_waitcnt vmcnt(11) lgkmcnt(7)
	v_mfma_f32_32x32x16_bf16 v[112:127], v[140:143], v[182:185], v[112:127]
	s_waitcnt lgkmcnt(6)
	v_mfma_f32_32x32x16_bf16 v[80:95], v[140:143], v[210:213], v[80:95]
	s_waitcnt lgkmcnt(5)
	v_mfma_f32_32x32x16_bf16 v[48:63], v[140:143], v[218:221], v[48:63]
	s_waitcnt lgkmcnt(4)
	v_mfma_f32_32x32x16_bf16 v[16:31], v[140:143], v[234:237], v[16:31]
	s_waitcnt vmcnt(10)
	v_mfma_f32_32x32x16_bf16 v[96:111], v[198:201], v[182:185], v[96:111]
	global_load_dwordx4 v[140:143], v[190:191], off offset:2048
	global_load_dwordx4 v[182:185], v[242:243], off offset:2048
	v_mfma_f32_32x32x16_bf16 v[64:79], v[198:201], v[210:213], v[64:79]
	v_mfma_f32_32x32x16_bf16 v[32:47], v[198:201], v[218:221], v[32:47]
	v_mfma_f32_32x32x16_bf16 v[0:15], v[198:201], v[234:237], v[0:15]
	s_setprio 0
	s_setprio 2
	s_waitcnt vmcnt(11) lgkmcnt(3)
	v_mfma_f32_32x32x16_bf16 v[112:127], v[132:135], v[206:209], v[112:127]
	s_waitcnt lgkmcnt(2)
	v_mfma_f32_32x32x16_bf16 v[80:95], v[132:135], v[214:217], v[80:95]
	s_waitcnt lgkmcnt(1)
	v_mfma_f32_32x32x16_bf16 v[48:63], v[132:135], v[228:231], v[48:63]
	s_waitcnt lgkmcnt(0)
	v_mfma_f32_32x32x16_bf16 v[16:31], v[132:135], v[238:241], v[16:31]
	global_load_dwordx4 v[132:135], v[190:191], off offset:3072
	global_load_dwordx4 v[198:201], v[242:243], off offset:3072
	s_waitcnt vmcnt(12)
	v_mfma_f32_32x32x16_bf16 v[96:111], v[178:181], v[206:209], v[96:111]
	v_mfma_f32_32x32x16_bf16 v[64:79], v[178:181], v[214:217], v[64:79]
	v_mfma_f32_32x32x16_bf16 v[32:47], v[178:181], v[228:231], v[32:47]
	v_mfma_f32_32x32x16_bf16 v[0:15], v[178:181], v[238:241], v[0:15]
	s_setprio 0
	s_waitcnt vmcnt(11)
	ds_write_b128 v154, v[128:131]
	s_waitcnt vmcnt(10)
	ds_write_b128 v154, v[136:139] offset:4608
	s_waitcnt vmcnt(9)
	ds_write_b128 v154, v[144:147] offset:9216
	s_waitcnt vmcnt(8)
	ds_write_b128 v154, v[170:173] offset:13824
	global_load_dwordx4 v[128:131], v[164:165], off offset:1664
	global_load_dwordx4 v[136:139], v[162:163], off offset:1664
	global_load_dwordx4 v[144:147], v[160:161], off offset:1664
	global_load_dwordx4 v[170:173], v[158:159], off offset:1664
	s_waitcnt lgkmcnt(0)
	s_barrier
	ds_read_b128 v[178:181], v155
	ds_read_b128 v[206:209], v155 offset:32
	ds_read_b128 v[210:213], v155 offset:4608
	ds_read_b128 v[214:217], v155 offset:4640
	ds_read_b128 v[218:221], v155 offset:9216
	ds_read_b128 v[228:231], v155 offset:9248
	ds_read_b128 v[234:237], v155 offset:13824
	ds_read_b128 v[238:241], v155 offset:13856
	s_setprio 2
	s_mov_b32 s8, 0xd000
	v_add_co_u32_e32 v190, vcc, s8, v156
	s_mov_b32 s8, 0x1d000
	s_nop 0
	v_addc_co_u32_e32 v191, vcc, 0, v157, vcc
	v_add_co_u32_e32 v242, vcc, s8, v156
	s_waitcnt vmcnt(11) lgkmcnt(7)
	v_mfma_f32_32x32x16_bf16 v[112:127], v[174:177], v[178:181], v[112:127]
	v_addc_co_u32_e32 v243, vcc, 0, v157, vcc
	s_waitcnt lgkmcnt(5)
	v_mfma_f32_32x32x16_bf16 v[80:95], v[174:177], v[210:213], v[80:95]
	s_waitcnt lgkmcnt(3)
	v_mfma_f32_32x32x16_bf16 v[48:63], v[174:177], v[218:221], v[48:63]
	s_waitcnt lgkmcnt(1)
	v_mfma_f32_32x32x16_bf16 v[16:31], v[174:177], v[234:237], v[16:31]
	s_waitcnt vmcnt(10)
	v_mfma_f32_32x32x16_bf16 v[96:111], v[186:189], v[178:181], v[96:111]
	global_load_dwordx4 v[174:177], v[190:191], off
	global_load_dwordx4 v[178:181], v[242:243], off
	v_mfma_f32_32x32x16_bf16 v[64:79], v[186:189], v[210:213], v[64:79]
	v_mfma_f32_32x32x16_bf16 v[32:47], v[186:189], v[218:221], v[32:47]
	v_mfma_f32_32x32x16_bf16 v[0:15], v[186:189], v[234:237], v[0:15]
	s_setprio 0
	ds_read_b128 v[186:189], v155 offset:64
	ds_read_b128 v[210:213], v155 offset:4672
	ds_read_b128 v[218:221], v155 offset:9280
	ds_read_b128 v[234:237], v155 offset:13888
	s_setprio 2
	s_waitcnt vmcnt(11)
	v_mfma_f32_32x32x16_bf16 v[112:127], v[148:151], v[206:209], v[112:127]
	v_mfma_f32_32x32x16_bf16 v[80:95], v[148:151], v[214:217], v[80:95]
	v_mfma_f32_32x32x16_bf16 v[48:63], v[148:151], v[228:231], v[48:63]
	s_waitcnt lgkmcnt(4)
	v_mfma_f32_32x32x16_bf16 v[16:31], v[148:151], v[238:241], v[16:31]
	s_waitcnt vmcnt(10)
	v_mfma_f32_32x32x16_bf16 v[96:111], v[202:205], v[206:209], v[96:111]
	global_load_dwordx4 v[148:151], v[190:191], off offset:1024
	global_load_dwordx4 v[206:209], v[242:243], off offset:1024
	v_mfma_f32_32x32x16_bf16 v[64:79], v[202:205], v[214:217], v[64:79]
	v_mfma_f32_32x32x16_bf16 v[32:47], v[202:205], v[228:231], v[32:47]
	v_mfma_f32_32x32x16_bf16 v[0:15], v[202:205], v[238:241], v[0:15]
	s_setprio 0
	ds_read_b128 v[202:205], v155 offset:96
	ds_read_b128 v[214:217], v155 offset:4704
	ds_read_b128 v[228:231], v155 offset:9312
	ds_read_b128 v[238:241], v155 offset:13920
	s_setprio 2
	s_waitcnt vmcnt(11) lgkmcnt(7)
	v_mfma_f32_32x32x16_bf16 v[112:127], v[140:143], v[186:189], v[112:127]
	s_waitcnt lgkmcnt(6)
	v_mfma_f32_32x32x16_bf16 v[80:95], v[140:143], v[210:213], v[80:95]
	s_waitcnt lgkmcnt(5)
	v_mfma_f32_32x32x16_bf16 v[48:63], v[140:143], v[218:221], v[48:63]
	s_waitcnt lgkmcnt(4)
	v_mfma_f32_32x32x16_bf16 v[16:31], v[140:143], v[234:237], v[16:31]
	s_waitcnt vmcnt(10)
	v_mfma_f32_32x32x16_bf16 v[96:111], v[182:185], v[186:189], v[96:111]
	global_load_dwordx4 v[140:143], v[190:191], off offset:2048
	global_load_dwordx4 v[186:189], v[242:243], off offset:2048
	v_mfma_f32_32x32x16_bf16 v[64:79], v[182:185], v[210:213], v[64:79]
	v_mfma_f32_32x32x16_bf16 v[32:47], v[182:185], v[218:221], v[32:47]
	v_mfma_f32_32x32x16_bf16 v[0:15], v[182:185], v[234:237], v[0:15]
	s_setprio 0
	s_setprio 2
	s_waitcnt vmcnt(11) lgkmcnt(3)
	v_mfma_f32_32x32x16_bf16 v[112:127], v[132:135], v[202:205], v[112:127]
	s_waitcnt lgkmcnt(2)
	v_mfma_f32_32x32x16_bf16 v[80:95], v[132:135], v[214:217], v[80:95]
	s_waitcnt lgkmcnt(1)
	v_mfma_f32_32x32x16_bf16 v[48:63], v[132:135], v[228:231], v[48:63]
	s_waitcnt lgkmcnt(0)
	v_mfma_f32_32x32x16_bf16 v[16:31], v[132:135], v[238:241], v[16:31]
	global_load_dwordx4 v[132:135], v[190:191], off offset:3072
	global_load_dwordx4 v[182:185], v[242:243], off offset:3072
	s_waitcnt vmcnt(12)
	v_mfma_f32_32x32x16_bf16 v[96:111], v[198:201], v[202:205], v[96:111]
	v_mfma_f32_32x32x16_bf16 v[64:79], v[198:201], v[214:217], v[64:79]
	v_mfma_f32_32x32x16_bf16 v[32:47], v[198:201], v[228:231], v[32:47]
	v_mfma_f32_32x32x16_bf16 v[0:15], v[198:201], v[238:241], v[0:15]
	s_setprio 0
	s_waitcnt vmcnt(8)
	ds_write_b128 v154, v[170:173] offset:18432
	ds_write_b128 v154, v[144:147] offset:23040
	ds_write_b128 v154, v[136:139] offset:27648
	ds_write_b128 v154, v[128:131] offset:32256
	global_load_dwordx4 v[128:131], v[158:159], off offset:1792
	global_load_dwordx4 v[136:139], v[160:161], off offset:1792
	global_load_dwordx4 v[144:147], v[162:163], off offset:1792
	global_load_dwordx4 v[170:173], v[164:165], off offset:1792
	s_waitcnt lgkmcnt(0)
	s_barrier
	ds_read_b128 v[198:201], v155 offset:18432
	ds_read_b128 v[202:205], v155 offset:18464
	ds_read_b128 v[210:213], v155 offset:23040
	ds_read_b128 v[214:217], v155 offset:23072
	ds_read_b128 v[218:221], v155 offset:27648
	ds_read_b128 v[228:231], v155 offset:27680
	ds_read_b128 v[234:237], v155 offset:32256
	ds_read_b128 v[238:241], v155 offset:32288
	s_setprio 2
	s_mov_b32 s8, 0xe000
	v_add_co_u32_e32 v190, vcc, s8, v156
	s_mov_b32 s8, 0x1e000
	s_nop 0
	v_addc_co_u32_e32 v191, vcc, 0, v157, vcc
	v_add_co_u32_e32 v242, vcc, s8, v156
	s_waitcnt vmcnt(11) lgkmcnt(7)
	v_mfma_f32_32x32x16_bf16 v[112:127], v[174:177], v[198:201], v[112:127]
	v_addc_co_u32_e32 v243, vcc, 0, v157, vcc
	s_waitcnt lgkmcnt(5)
	v_mfma_f32_32x32x16_bf16 v[80:95], v[174:177], v[210:213], v[80:95]
	s_waitcnt lgkmcnt(3)
	v_mfma_f32_32x32x16_bf16 v[48:63], v[174:177], v[218:221], v[48:63]
	s_waitcnt lgkmcnt(1)
	v_mfma_f32_32x32x16_bf16 v[16:31], v[174:177], v[234:237], v[16:31]
	s_waitcnt vmcnt(10)
	v_mfma_f32_32x32x16_bf16 v[96:111], v[178:181], v[198:201], v[96:111]
	global_load_dwordx4 v[174:177], v[190:191], off
	global_load_dwordx4 v[198:201], v[242:243], off
	v_mfma_f32_32x32x16_bf16 v[64:79], v[178:181], v[210:213], v[64:79]
	v_mfma_f32_32x32x16_bf16 v[32:47], v[178:181], v[218:221], v[32:47]
	v_mfma_f32_32x32x16_bf16 v[0:15], v[178:181], v[234:237], v[0:15]
	s_setprio 0
	ds_read_b128 v[178:181], v155 offset:18496
	ds_read_b128 v[210:213], v155 offset:23104
	ds_read_b128 v[218:221], v155 offset:27712
	ds_read_b128 v[234:237], v155 offset:32320
	s_setprio 2
	s_waitcnt vmcnt(11)
	v_mfma_f32_32x32x16_bf16 v[112:127], v[148:151], v[202:205], v[112:127]
	v_mfma_f32_32x32x16_bf16 v[80:95], v[148:151], v[214:217], v[80:95]
	v_mfma_f32_32x32x16_bf16 v[48:63], v[148:151], v[228:231], v[48:63]
	s_waitcnt lgkmcnt(4)
	v_mfma_f32_32x32x16_bf16 v[16:31], v[148:151], v[238:241], v[16:31]
	s_waitcnt vmcnt(10)
	v_mfma_f32_32x32x16_bf16 v[96:111], v[206:209], v[202:205], v[96:111]
	global_load_dwordx4 v[148:151], v[190:191], off offset:1024
	global_load_dwordx4 v[202:205], v[242:243], off offset:1024
	v_mfma_f32_32x32x16_bf16 v[64:79], v[206:209], v[214:217], v[64:79]
	v_mfma_f32_32x32x16_bf16 v[32:47], v[206:209], v[228:231], v[32:47]
	v_mfma_f32_32x32x16_bf16 v[0:15], v[206:209], v[238:241], v[0:15]
	s_setprio 0
	ds_read_b128 v[206:209], v155 offset:18528
	ds_read_b128 v[214:217], v155 offset:23136
	ds_read_b128 v[228:231], v155 offset:27744
	ds_read_b128 v[238:241], v155 offset:32352
	s_setprio 2
	s_waitcnt vmcnt(11) lgkmcnt(7)
	v_mfma_f32_32x32x16_bf16 v[112:127], v[140:143], v[178:181], v[112:127]
	s_waitcnt lgkmcnt(6)
	v_mfma_f32_32x32x16_bf16 v[80:95], v[140:143], v[210:213], v[80:95]
	s_waitcnt lgkmcnt(5)
	v_mfma_f32_32x32x16_bf16 v[48:63], v[140:143], v[218:221], v[48:63]
	s_waitcnt lgkmcnt(4)
	v_mfma_f32_32x32x16_bf16 v[16:31], v[140:143], v[234:237], v[16:31]
	s_waitcnt vmcnt(10)
	v_mfma_f32_32x32x16_bf16 v[96:111], v[186:189], v[178:181], v[96:111]
	global_load_dwordx4 v[140:143], v[190:191], off offset:2048
	global_load_dwordx4 v[178:181], v[242:243], off offset:2048
	v_mfma_f32_32x32x16_bf16 v[64:79], v[186:189], v[210:213], v[64:79]
	v_mfma_f32_32x32x16_bf16 v[32:47], v[186:189], v[218:221], v[32:47]
	v_mfma_f32_32x32x16_bf16 v[0:15], v[186:189], v[234:237], v[0:15]
	s_setprio 0
	s_setprio 2
	s_waitcnt vmcnt(11) lgkmcnt(3)
	v_mfma_f32_32x32x16_bf16 v[112:127], v[132:135], v[206:209], v[112:127]
	s_waitcnt lgkmcnt(2)
	v_mfma_f32_32x32x16_bf16 v[80:95], v[132:135], v[214:217], v[80:95]
	s_waitcnt lgkmcnt(1)
	v_mfma_f32_32x32x16_bf16 v[48:63], v[132:135], v[228:231], v[48:63]
	s_waitcnt lgkmcnt(0)
	v_mfma_f32_32x32x16_bf16 v[16:31], v[132:135], v[238:241], v[16:31]
	global_load_dwordx4 v[132:135], v[190:191], off offset:3072
	global_load_dwordx4 v[186:189], v[242:243], off offset:3072
	s_waitcnt vmcnt(12)
	v_mfma_f32_32x32x16_bf16 v[96:111], v[182:185], v[206:209], v[96:111]
	v_mfma_f32_32x32x16_bf16 v[64:79], v[182:185], v[214:217], v[64:79]
	v_mfma_f32_32x32x16_bf16 v[32:47], v[182:185], v[228:231], v[32:47]
	v_mfma_f32_32x32x16_bf16 v[0:15], v[182:185], v[238:241], v[0:15]
	s_setprio 0
	s_waitcnt vmcnt(11)
	ds_write_b128 v154, v[128:131]
	s_waitcnt vmcnt(10)
	ds_write_b128 v154, v[136:139] offset:4608
	s_waitcnt vmcnt(9)
	ds_write_b128 v154, v[144:147] offset:9216
	s_waitcnt vmcnt(8)
	ds_write_b128 v154, v[170:173] offset:13824
	global_load_dwordx4 v[128:131], v[164:165], off offset:1920
	global_load_dwordx4 v[136:139], v[162:163], off offset:1920
	global_load_dwordx4 v[144:147], v[160:161], off offset:1920
	s_nop 0
	global_load_dwordx4 v[158:161], v[158:159], off offset:1920
	s_waitcnt lgkmcnt(0)
	s_barrier
	ds_read_b128 v[162:165], v155
	ds_read_b128 v[170:173], v155 offset:32
	ds_read_b128 v[182:185], v155 offset:4608
	ds_read_b128 v[206:209], v155 offset:4640
	ds_read_b128 v[210:213], v155 offset:9216
	ds_read_b128 v[214:217], v155 offset:9248
	ds_read_b128 v[218:221], v155 offset:13824
	ds_read_b128 v[228:231], v155 offset:13856
	s_setprio 2
	s_mov_b32 s8, 0xf000
	v_add_co_u32_e32 v190, vcc, s8, v156
	s_mov_b32 s8, 0x1f000
	s_nop 0
	v_addc_co_u32_e32 v191, vcc, 0, v157, vcc
	v_add_co_u32_e32 v156, vcc, s8, v156
	s_waitcnt vmcnt(11) lgkmcnt(7)
	v_mfma_f32_32x32x16_bf16 v[112:127], v[174:177], v[162:165], v[112:127]
	v_addc_co_u32_e32 v157, vcc, 0, v157, vcc
	s_waitcnt lgkmcnt(5)
	v_mfma_f32_32x32x16_bf16 v[80:95], v[174:177], v[182:185], v[80:95]
	s_waitcnt lgkmcnt(3)
	v_mfma_f32_32x32x16_bf16 v[48:63], v[174:177], v[210:213], v[48:63]
	s_waitcnt lgkmcnt(1)
	v_mfma_f32_32x32x16_bf16 v[16:31], v[174:177], v[218:221], v[16:31]
	s_waitcnt vmcnt(10)
	v_mfma_f32_32x32x16_bf16 v[96:111], v[198:201], v[162:165], v[96:111]
	global_load_dwordx4 v[162:165], v[190:191], off
	global_load_dwordx4 v[174:177], v[156:157], off
	v_mfma_f32_32x32x16_bf16 v[64:79], v[198:201], v[182:185], v[64:79]
	v_mfma_f32_32x32x16_bf16 v[32:47], v[198:201], v[210:213], v[32:47]
	v_mfma_f32_32x32x16_bf16 v[0:15], v[198:201], v[218:221], v[0:15]
	s_setprio 0
	ds_read_b128 v[182:185], v155 offset:64
	ds_read_b128 v[198:201], v155 offset:4672
	ds_read_b128 v[210:213], v155 offset:9280
	ds_read_b128 v[218:221], v155 offset:13888
	s_setprio 2
	s_waitcnt vmcnt(11)
	v_mfma_f32_32x32x16_bf16 v[112:127], v[148:151], v[170:173], v[112:127]
	v_mfma_f32_32x32x16_bf16 v[80:95], v[148:151], v[206:209], v[80:95]
	v_mfma_f32_32x32x16_bf16 v[48:63], v[148:151], v[214:217], v[48:63]
	s_waitcnt lgkmcnt(4)
	v_mfma_f32_32x32x16_bf16 v[16:31], v[148:151], v[228:231], v[16:31]
	s_waitcnt vmcnt(10)
	v_mfma_f32_32x32x16_bf16 v[96:111], v[202:205], v[170:173], v[96:111]
	global_load_dwordx4 v[148:151], v[190:191], off offset:1024
	global_load_dwordx4 v[170:173], v[156:157], off offset:1024
	v_mfma_f32_32x32x16_bf16 v[64:79], v[202:205], v[206:209], v[64:79]
	v_mfma_f32_32x32x16_bf16 v[32:47], v[202:205], v[214:217], v[32:47]
	v_mfma_f32_32x32x16_bf16 v[0:15], v[202:205], v[228:231], v[0:15]
	s_setprio 0
	ds_read_b128 v[202:205], v155 offset:96
	ds_read_b128 v[206:209], v155 offset:4704
	ds_read_b128 v[214:217], v155 offset:9312
	ds_read_b128 v[228:231], v155 offset:13920
	s_setprio 2
	s_waitcnt vmcnt(11) lgkmcnt(7)
	v_mfma_f32_32x32x16_bf16 v[112:127], v[140:143], v[182:185], v[112:127]
	s_waitcnt lgkmcnt(6)
	v_mfma_f32_32x32x16_bf16 v[80:95], v[140:143], v[198:201], v[80:95]
	s_waitcnt lgkmcnt(5)
	v_mfma_f32_32x32x16_bf16 v[48:63], v[140:143], v[210:213], v[48:63]
	s_waitcnt lgkmcnt(4)
	v_mfma_f32_32x32x16_bf16 v[16:31], v[140:143], v[218:221], v[16:31]
	s_waitcnt vmcnt(10)
	v_mfma_f32_32x32x16_bf16 v[96:111], v[178:181], v[182:185], v[96:111]
	global_load_dwordx4 v[140:143], v[190:191], off offset:2048
	global_load_dwordx4 v[182:185], v[156:157], off offset:2048
	v_mfma_f32_32x32x16_bf16 v[64:79], v[178:181], v[198:201], v[64:79]
	v_mfma_f32_32x32x16_bf16 v[32:47], v[178:181], v[210:213], v[32:47]
	v_mfma_f32_32x32x16_bf16 v[0:15], v[178:181], v[218:221], v[0:15]
	s_setprio 0
	s_setprio 2
	s_waitcnt vmcnt(11) lgkmcnt(3)
	v_mfma_f32_32x32x16_bf16 v[112:127], v[132:135], v[202:205], v[112:127]
	s_waitcnt lgkmcnt(2)
	v_mfma_f32_32x32x16_bf16 v[80:95], v[132:135], v[206:209], v[80:95]
	s_waitcnt lgkmcnt(1)
	v_mfma_f32_32x32x16_bf16 v[48:63], v[132:135], v[214:217], v[48:63]
	s_waitcnt lgkmcnt(0)
	v_mfma_f32_32x32x16_bf16 v[16:31], v[132:135], v[228:231], v[16:31]
	global_load_dwordx4 v[132:135], v[190:191], off offset:3072
	global_load_dwordx4 v[178:181], v[156:157], off offset:3072
	s_waitcnt vmcnt(12)
	v_mfma_f32_32x32x16_bf16 v[96:111], v[186:189], v[202:205], v[96:111]
	v_mfma_f32_32x32x16_bf16 v[64:79], v[186:189], v[206:209], v[64:79]
	v_mfma_f32_32x32x16_bf16 v[32:47], v[186:189], v[214:217], v[32:47]
	v_mfma_f32_32x32x16_bf16 v[0:15], v[186:189], v[228:231], v[0:15]
	s_setprio 0
	s_waitcnt vmcnt(8)
	ds_write_b128 v154, v[158:161] offset:18432
	ds_write_b128 v154, v[144:147] offset:23040
	ds_write_b128 v154, v[136:139] offset:27648
	ds_write_b128 v154, v[128:131] offset:32256
	s_waitcnt lgkmcnt(0)
	s_barrier
	ds_read_b128 v[128:131], v155 offset:18432
	ds_read_b128 v[136:139], v155 offset:18464
	ds_read_b128 v[144:147], v155 offset:23040
	ds_read_b128 v[156:159], v155 offset:23072
	ds_read_b128 v[186:189], v155 offset:27648
	ds_read_b128 v[198:201], v155 offset:27680
	ds_read_b128 v[202:205], v155 offset:32256
	ds_read_b128 v[206:209], v155 offset:32288
	s_setprio 2
	s_waitcnt vmcnt(7) lgkmcnt(7)
	v_mfma_f32_32x32x16_bf16 v[112:127], v[162:165], v[128:131], v[112:127]
	s_waitcnt lgkmcnt(5)
	v_mfma_f32_32x32x16_bf16 v[80:95], v[162:165], v[144:147], v[80:95]
	s_waitcnt lgkmcnt(3)
	v_mfma_f32_32x32x16_bf16 v[48:63], v[162:165], v[186:189], v[48:63]
	s_waitcnt lgkmcnt(1)
	v_mfma_f32_32x32x16_bf16 v[16:31], v[162:165], v[202:205], v[16:31]
	s_waitcnt vmcnt(6)
	v_mfma_f32_32x32x16_bf16 v[96:111], v[174:177], v[128:131], v[96:111]
	v_mfma_f32_32x32x16_bf16 v[64:79], v[174:177], v[144:147], v[64:79]
	v_mfma_f32_32x32x16_bf16 v[32:47], v[174:177], v[186:189], v[32:47]
	v_mfma_f32_32x32x16_bf16 v[0:15], v[174:177], v[202:205], v[0:15]
	s_setprio 0
	ds_read_b128 v[128:131], v155 offset:18496
	ds_read_b128 v[144:147], v155 offset:23104
	ds_read_b128 v[160:163], v155 offset:27712
	ds_read_b128 v[174:177], v155 offset:32320
	s_setprio 2
	s_waitcnt vmcnt(5)
	v_mfma_f32_32x32x16_bf16 v[112:127], v[148:151], v[136:139], v[112:127]
	v_mfma_f32_32x32x16_bf16 v[80:95], v[148:151], v[156:159], v[80:95]
	v_mfma_f32_32x32x16_bf16 v[48:63], v[148:151], v[198:201], v[48:63]
	s_waitcnt lgkmcnt(4)
	v_mfma_f32_32x32x16_bf16 v[16:31], v[148:151], v[206:209], v[16:31]
	s_waitcnt vmcnt(4)
	v_mfma_f32_32x32x16_bf16 v[96:111], v[170:173], v[136:139], v[96:111]
	v_mfma_f32_32x32x16_bf16 v[64:79], v[170:173], v[156:159], v[64:79]
	v_mfma_f32_32x32x16_bf16 v[32:47], v[170:173], v[198:201], v[32:47]
	v_mfma_f32_32x32x16_bf16 v[0:15], v[170:173], v[206:209], v[0:15]
	s_setprio 0
	ds_read_b128 v[136:139], v155 offset:18528
	ds_read_b128 v[148:151], v155 offset:23136
	ds_read_b128 v[156:159], v155 offset:27744
	ds_read_b128 v[170:173], v155 offset:32352
	s_setprio 2
	s_waitcnt vmcnt(3) lgkmcnt(7)
	v_mfma_f32_32x32x16_bf16 v[112:127], v[140:143], v[128:131], v[112:127]
	s_waitcnt lgkmcnt(6)
	v_mfma_f32_32x32x16_bf16 v[80:95], v[140:143], v[144:147], v[80:95]
	s_waitcnt lgkmcnt(5)
	v_mfma_f32_32x32x16_bf16 v[48:63], v[140:143], v[160:163], v[48:63]
	s_waitcnt lgkmcnt(4)
	v_mfma_f32_32x32x16_bf16 v[16:31], v[140:143], v[174:177], v[16:31]
	s_waitcnt vmcnt(2)
	v_mfma_f32_32x32x16_bf16 v[96:111], v[182:185], v[128:131], v[96:111]
	v_mfma_f32_32x32x16_bf16 v[64:79], v[182:185], v[144:147], v[64:79]
	v_mfma_f32_32x32x16_bf16 v[32:47], v[182:185], v[160:163], v[32:47]
	v_mfma_f32_32x32x16_bf16 v[0:15], v[182:185], v[174:177], v[0:15]
	s_setprio 0
	s_setprio 2
	s_waitcnt vmcnt(1) lgkmcnt(3)
	v_mfma_f32_32x32x16_bf16 v[112:127], v[132:135], v[136:139], v[112:127]
	s_waitcnt lgkmcnt(2)
	v_mfma_f32_32x32x16_bf16 v[80:95], v[132:135], v[148:151], v[80:95]
	s_waitcnt lgkmcnt(1)
	v_mfma_f32_32x32x16_bf16 v[48:63], v[132:135], v[156:159], v[48:63]
	s_waitcnt lgkmcnt(0)
	v_mfma_f32_32x32x16_bf16 v[16:31], v[132:135], v[170:173], v[16:31]
	s_waitcnt vmcnt(0)
	v_mfma_f32_32x32x16_bf16 v[96:111], v[178:181], v[136:139], v[96:111]
	v_mfma_f32_32x32x16_bf16 v[64:79], v[178:181], v[148:151], v[64:79]
	v_mfma_f32_32x32x16_bf16 v[32:47], v[178:181], v[156:159], v[32:47]
	v_mfma_f32_32x32x16_bf16 v[0:15], v[178:181], v[170:173], v[0:15]
	s_setprio 0
	v_and_b32_e32 v128, 0xffffffc0, v152
	v_or_b32_e32 v130, s30, v167
	v_readlane_b32 s10, v253, 12
	v_lshl_add_u32 v128, s61, 8, v128
	v_readlane_b32 s11, v253, 13
	v_or_b32_e32 v138, 32, v130
	v_or_b32_e32 v136, 64, v130
	v_or_b32_e32 v134, 0x60, v130
	v_ashrrev_i32_e32 v129, 31, v128
	v_lshlrev_b32_e32 v141, 2, v169
	s_mov_b64 s[8:9], -1
	s_andn2_b64 vcc, exec, s[10:11]
	v_ashrrev_i32_e32 v131, 31, v130
	v_ashrrev_i32_e32 v139, 31, v138
	v_ashrrev_i32_e32 v137, 31, v136
	v_ashrrev_i32_e32 v135, 31, v134
	s_barrier
	s_cbranch_vccnz .LBB0_817
	v_lshlrev_b64 v[132:133], 11, v[130:131]
	v_lshl_add_u64 v[132:133], s[22:23], 0, v[132:133]
	v_lshlrev_b64 v[142:143], 1, v[128:129]
	v_lshl_add_u64 v[132:133], v[132:133], 0, v[142:143]
	v_lshlrev_b32_e32 v192, 1, v141
	v_lshl_add_u64 v[132:133], v[132:133], 0, v[192:193]
	v_cvt_pk_bf16_f32 v144, v112, v113
	v_cvt_pk_bf16_f32 v145, v114, v115
	global_store_dwordx2 v[132:133], v[144:145], off
	v_cvt_pk_bf16_f32 v144, v116, v117
	v_cvt_pk_bf16_f32 v145, v118, v119
	global_store_dwordx2 v[132:133], v[144:145], off offset:16
	v_cvt_pk_bf16_f32 v144, v120, v121
	v_cvt_pk_bf16_f32 v145, v122, v123
	global_store_dwordx2 v[132:133], v[144:145], off offset:32
	v_cvt_pk_bf16_f32 v144, v124, v125
	v_cvt_pk_bf16_f32 v145, v126, v127
	global_store_dwordx2 v[132:133], v[144:145], off offset:48
	v_cvt_pk_bf16_f32 v144, v96, v97
	v_cvt_pk_bf16_f32 v145, v98, v99
	global_store_dwordx2 v[132:133], v[144:145], off offset:64
	v_cvt_pk_bf16_f32 v144, v100, v101
	v_cvt_pk_bf16_f32 v145, v102, v103
	global_store_dwordx2 v[132:133], v[144:145], off offset:80
	v_cvt_pk_bf16_f32 v144, v104, v105
	v_cvt_pk_bf16_f32 v145, v106, v107
	global_store_dwordx2 v[132:133], v[144:145], off offset:96
	v_cvt_pk_bf16_f32 v144, v108, v109
	v_cvt_pk_bf16_f32 v145, v110, v111
	global_store_dwordx2 v[132:133], v[144:145], off offset:112
	v_lshlrev_b64 v[132:133], 11, v[138:139]
	v_lshl_add_u64 v[132:133], s[22:23], 0, v[132:133]
	v_lshl_add_u64 v[132:133], v[132:133], 0, v[142:143]
	v_lshl_add_u64 v[132:133], v[132:133], 0, v[192:193]
	v_cvt_pk_bf16_f32 v144, v80, v81
	v_cvt_pk_bf16_f32 v145, v82, v83
	global_store_dwordx2 v[132:133], v[144:145], off
	v_cvt_pk_bf16_f32 v144, v84, v85
	v_cvt_pk_bf16_f32 v145, v86, v87
	global_store_dwordx2 v[132:133], v[144:145], off offset:16
	v_cvt_pk_bf16_f32 v144, v88, v89
	v_cvt_pk_bf16_f32 v145, v90, v91
	global_store_dwordx2 v[132:133], v[144:145], off offset:32
	v_cvt_pk_bf16_f32 v144, v92, v93
	v_cvt_pk_bf16_f32 v145, v94, v95
	global_store_dwordx2 v[132:133], v[144:145], off offset:48
	v_cvt_pk_bf16_f32 v144, v64, v65
	v_cvt_pk_bf16_f32 v145, v66, v67
	global_store_dwordx2 v[132:133], v[144:145], off offset:64
	v_cvt_pk_bf16_f32 v144, v68, v69
	v_cvt_pk_bf16_f32 v145, v70, v71
	global_store_dwordx2 v[132:133], v[144:145], off offset:80
	v_cvt_pk_bf16_f32 v144, v72, v73
	v_cvt_pk_bf16_f32 v145, v74, v75
	global_store_dwordx2 v[132:133], v[144:145], off offset:96
	v_cvt_pk_bf16_f32 v144, v76, v77
	v_cvt_pk_bf16_f32 v145, v78, v79
	global_store_dwordx2 v[132:133], v[144:145], off offset:112
	v_lshlrev_b64 v[132:133], 11, v[136:137]
	v_lshl_add_u64 v[132:133], s[22:23], 0, v[132:133]
	v_lshl_add_u64 v[132:133], v[132:133], 0, v[142:143]
	v_lshl_add_u64 v[132:133], v[132:133], 0, v[192:193]
	v_cvt_pk_bf16_f32 v144, v48, v49
	v_cvt_pk_bf16_f32 v145, v50, v51
	global_store_dwordx2 v[132:133], v[144:145], off
	v_cvt_pk_bf16_f32 v144, v52, v53
	v_cvt_pk_bf16_f32 v145, v54, v55
	global_store_dwordx2 v[132:133], v[144:145], off offset:16
	v_cvt_pk_bf16_f32 v144, v56, v57
	v_cvt_pk_bf16_f32 v145, v58, v59
	global_store_dwordx2 v[132:133], v[144:145], off offset:32
	v_cvt_pk_bf16_f32 v144, v60, v61
	v_cvt_pk_bf16_f32 v145, v62, v63
	global_store_dwordx2 v[132:133], v[144:145], off offset:48
	v_cvt_pk_bf16_f32 v144, v32, v33
	v_cvt_pk_bf16_f32 v145, v34, v35
	global_store_dwordx2 v[132:133], v[144:145], off offset:64
	v_cvt_pk_bf16_f32 v144, v36, v37
	v_cvt_pk_bf16_f32 v145, v38, v39
	global_store_dwordx2 v[132:133], v[144:145], off offset:80
	v_cvt_pk_bf16_f32 v144, v40, v41
	v_cvt_pk_bf16_f32 v145, v42, v43
	global_store_dwordx2 v[132:133], v[144:145], off offset:96
	v_cvt_pk_bf16_f32 v144, v44, v45
	v_cvt_pk_bf16_f32 v145, v46, v47
	global_store_dwordx2 v[132:133], v[144:145], off offset:112
	v_lshlrev_b64 v[132:133], 11, v[134:135]
	v_lshl_add_u64 v[132:133], s[22:23], 0, v[132:133]
	v_lshl_add_u64 v[132:133], v[132:133], 0, v[142:143]
	v_lshl_add_u64 v[132:133], v[132:133], 0, v[192:193]
	v_cvt_pk_bf16_f32 v142, v16, v17
	v_cvt_pk_bf16_f32 v143, v18, v19
	global_store_dwordx2 v[132:133], v[142:143], off
	v_cvt_pk_bf16_f32 v142, v20, v21
	v_cvt_pk_bf16_f32 v143, v22, v23
	global_store_dwordx2 v[132:133], v[142:143], off offset:16
	v_cvt_pk_bf16_f32 v142, v24, v25
	v_cvt_pk_bf16_f32 v143, v26, v27
	global_store_dwordx2 v[132:133], v[142:143], off offset:32
	v_cvt_pk_bf16_f32 v142, v28, v29
	v_cvt_pk_bf16_f32 v143, v30, v31
	global_store_dwordx2 v[132:133], v[142:143], off offset:48
	v_cvt_pk_bf16_f32 v142, v0, v1
	v_cvt_pk_bf16_f32 v143, v2, v3
	global_store_dwordx2 v[132:133], v[142:143], off offset:64
	v_cvt_pk_bf16_f32 v142, v4, v5
	v_cvt_pk_bf16_f32 v143, v6, v7
	global_store_dwordx2 v[132:133], v[142:143], off offset:80
	v_cvt_pk_bf16_f32 v142, v8, v9
	v_cvt_pk_bf16_f32 v143, v10, v11
	global_store_dwordx2 v[132:133], v[142:143], off offset:96
	v_cvt_pk_bf16_f32 v142, v12, v13
	v_cvt_pk_bf16_f32 v143, v14, v15
	s_mov_b64 s[8:9], 0
	global_store_dwordx2 v[132:133], v[142:143], off offset:112

.LBB0_844:
	s_or_b64 exec, exec, s[16:17]
	s_waitcnt lgkmcnt(0)
	s_barrier
	ds_read_b32 v133, v154 offset:2048
	s_mov_b32 s14, 0x800000
	v_lshlrev_b64 v[144:145], 10, v[130:131]
	v_lshlrev_b64 v[130:131], 11, v[130:131]
	v_cndmask_b32_e64 v132, 8, 0, s[8:9]
	s_waitcnt lgkmcnt(0)
	v_fmamk_f32 v133, v133, 0x3a800000, v224
	v_cmp_gt_f32_e32 vcc, s14, v133
	v_mul_f32_e32 v140, 0x4b800000, v133
	v_lshl_add_u64 v[130:131], s[26:27], 0, v[130:131]
	v_cndmask_b32_e32 v133, v133, v140, vcc
	v_rsq_f32_e32 v133, v133
	v_lshl_add_u64 v[130:131], v[128:129], 1, v[130:131]
	v_lshlrev_b32_e32 v132, 1, v132
	v_lshl_add_u64 v[142:143], v[128:129], 2, s[24:25]
	v_mul_f32_e32 v140, 0x45800000, v133
	v_cndmask_b32_e32 v140, v133, v140, vcc
	v_mov_b32_e32 v133, v193
	v_lshl_add_u64 v[146:147], v[130:131], 0, v[132:133]
	v_lshlrev_b32_e32 v192, 2, v141
	v_lshl_add_u64 v[130:131], v[142:143], 0, v[192:193]
	s_mov_b64 s[100:101], 0x10000
	global_load_dwordx4 v[202:205], v[130:131], off
	global_load_dwordx4 v[206:209], v[130:131], off offset:32
	global_load_dwordx4 v[210:213], v[130:131], off offset:64
	global_load_dwordx4 v[214:217], v[130:131], off offset:96
	global_load_dwordx4 v[234:237], v[130:131], off offset:128
	global_load_dwordx4 v[238:241], v[130:131], off offset:160
	global_load_dwordx4 v[242:245], v[130:131], off offset:192
	global_load_dwordx4 v[246:249], v[130:131], off offset:224
	global_load_dwordx4 v[170:173], v[146:147], off
	global_load_dwordx4 v[174:177], v[146:147], off offset:32
	global_load_dwordx4 v[178:181], v[146:147], off offset:64
	global_load_dwordx4 v[182:185], v[146:147], off offset:96
	v_lshl_add_u64 v[164:165], v[146:147], 0, s[100:101]
	global_load_dwordx4 v[218:221], v[164:165], off
	global_load_dwordx4 v[228:231], v[164:165], off offset:32
	global_load_dwordx4 v[186:189], v[164:165], off offset:64
	global_load_dwordx4 v[198:201], v[164:165], off offset:96
	v_lshl_add_u64 v[190:191], v[164:165], 0, s[100:101]
	v_lshl_add_u64 v[164:165], v[190:191], 0, s[100:101]
	s_waitcnt vmcnt(0)
	v_mov_b64_e32 v[156:157], v[170:171]
	v_mov_b64_e32 v[158:159], v[172:173]
	v_readlane_b32 s16, v253, 47
	v_readlane_b32 s36, v252, 2
	v_pk_mul_f32 v[112:113], v[112:113], v[140:141] op_sel_hi:[1,0]
	v_pk_mul_f32 v[114:115], v[114:115], v[140:141] op_sel_hi:[1,0]
	v_readlane_b32 s17, v253, 48
	v_readlane_b32 s37, v252, 3
	s_mov_b64 s[14:15], -1
	s_and_b64 vcc, exec, s[16:17]
	v_readlane_b32 s38, v252, 4
	v_readlane_b32 s39, v252, 5
	v_readlane_b32 s40, v252, 6
	v_readlane_b32 s41, v252, 7
	v_readlane_b32 s42, v252, 8
	v_readlane_b32 s43, v252, 9
	s_waitcnt lgkmcnt(0)
	v_mov_b32_e32 v133, v158
	v_mov_b32_e32 v155, v159
	v_mov_b64_e32 v[158:159], v[202:203]
	v_mov_b64_e32 v[160:161], v[204:205]
	v_permlane32_swap_b32_e32 v156, v133
	v_permlane32_swap_b32_e32 v157, v155
	v_lshlrev_b32_e32 v142, 16, v156
	v_and_b32_e32 v143, 0xffff0000, v156
	v_lshlrev_b32_e32 v156, 16, v157
	v_and_b32_e32 v157, 0xffff0000, v157
	s_nop 0
	v_pk_fma_f32 v[112:113], v[158:159], v[112:113], v[142:143]
	v_pk_fma_f32 v[114:115], v[160:161], v[114:115], v[156:157]
	v_lshl_add_u64 v[142:143], v[144:145], 2, s[36:37]
	s_cbranch_vccz .LBB0_846
	v_lshl_add_u64 v[156:157], v[128:129], 2, v[142:143]
	v_lshl_add_u64 v[156:157], v[156:157], 0, v[192:193]
	s_mov_b64 s[14:15], 0
	global_store_dwordx4 v[156:157], v[112:115], off

.LBB0_848:
	v_mov_b64_e32 v[156:157], v[206:207]
	v_mov_b64_e32 v[158:159], v[208:209]
	v_readlane_b32 s36, v253, 47
	v_mov_b32_e32 v141, v140
	v_readlane_b32 s37, v253, 48
	v_lshlrev_b32_e32 v160, 16, v133
	v_and_b32_e32 v161, 0xffff0000, v133
	v_lshlrev_b32_e32 v162, 16, v155
	v_and_b32_e32 v163, 0xffff0000, v155
	v_pk_mul_f32 v[116:117], v[116:117], v[140:141]
	v_pk_mul_f32 v[118:119], v[118:119], v[140:141]
	v_cndmask_b32_e64 v133, 0, 1, s[36:37]
	s_mov_b64 s[14:15], -1
	v_cmp_ne_u32_e64 s[16:17], 1, v133
	s_andn2_b64 vcc, exec, s[36:37]
	s_nop 0
	v_pk_fma_f32 v[116:117], v[116:117], v[156:157], v[160:161]
	v_pk_fma_f32 v[118:119], v[118:119], v[158:159], v[162:163]
	s_cbranch_vccnz .LBB0_850
	v_lshl_add_u64 v[156:157], v[128:129], 2, v[142:143]
	v_lshl_add_u64 v[156:157], v[156:157], 0, v[192:193]
	s_mov_b64 s[14:15], 0
	global_store_dwordx4 v[156:157], v[116:119], off offset:32

.LBB0_854:
	s_nop 1
	v_lshl_add_u64 v[112:113], v[144:145], 1, s[0:1]
	v_lshl_add_u64 v[144:145], v[128:129], 1, v[112:113]
	v_mov_b32_e32 v133, v193
	v_lshl_add_u64 v[146:147], v[144:145], 0, v[132:133]
	v_add_co_u32_e32 v112, vcc, 0x1dc0000, v146
	v_mov_b64_e32 v[156:157], v[210:211]
	v_mov_b64_e32 v[158:159], v[212:213]
	s_nop 0
	v_addc_co_u32_e32 v113, vcc, 0, v147, vcc
	v_mov_b64_e32 v[112:113], v[174:175]
	v_mov_b64_e32 v[114:115], v[176:177]
	s_mov_b64 s[36:37], -1
	s_and_b64 vcc, exec, s[16:17]
	s_waitcnt lgkmcnt(0)
	v_mov_b32_e32 v116, v114
	v_mov_b32_e32 v117, v115
	s_nop 0
	v_permlane32_swap_b32_e32 v112, v116
	v_permlane32_swap_b32_e32 v113, v117
	v_lshlrev_b32_e32 v114, 16, v112
	v_and_b32_e32 v115, 0xffff0000, v112
	v_lshlrev_b32_e32 v118, 16, v113
	v_and_b32_e32 v119, 0xffff0000, v113
	v_pk_mul_f32 v[112:113], v[120:121], v[140:141]
	s_nop 0
	v_pk_fma_f32 v[112:113], v[112:113], v[156:157], v[114:115]
	v_pk_mul_f32 v[114:115], v[122:123], v[140:141]
	s_nop 0
	v_pk_fma_f32 v[114:115], v[114:115], v[158:159], v[118:119]
	s_cbranch_vccnz .LBB0_856
	v_lshl_add_u64 v[118:119], v[128:129], 2, v[142:143]
	v_lshl_add_u64 v[118:119], v[118:119], 0, v[192:193]
	s_mov_b64 s[36:37], 0
	global_store_dwordx4 v[118:119], v[112:115], off offset:64

.LBB0_858:
	v_mov_b64_e32 v[118:119], v[214:215]
	v_mov_b64_e32 v[120:121], v[216:217]
	v_lshlrev_b32_e32 v122, 16, v116
	v_and_b32_e32 v123, 0xffff0000, v116
	v_lshlrev_b32_e32 v156, 16, v117
	v_and_b32_e32 v157, 0xffff0000, v117
	v_pk_mul_f32 v[116:117], v[124:125], v[140:141]
	v_pk_mul_f32 v[124:125], v[126:127], v[140:141]
	s_and_b64 vcc, exec, s[16:17]
	s_mov_b64 s[36:37], -1
	s_nop 0
	v_pk_fma_f32 v[116:117], v[116:117], v[118:119], v[122:123]
	v_pk_fma_f32 v[118:119], v[124:125], v[120:121], v[156:157]
	s_cbranch_vccnz .LBB0_987
	v_lshl_add_u64 v[120:121], v[128:129], 2, v[142:143]
	v_lshl_add_u64 v[120:121], v[120:121], 0, v[192:193]
	global_store_dwordx4 v[120:121], v[116:119], off offset:96
	s_cbranch_execz .LBB0_988

.LBB0_862:
	v_mov_b32_e32 v133, v193
	s_nop 0
	v_lshl_add_u64 v[112:113], v[144:145], 0, v[132:133]
	v_add_co_u32_e32 v114, vcc, 0x1dc0000, v112
	v_pk_mul_f32 v[96:97], v[96:97], v[140:141]
	s_nop 0
	v_addc_co_u32_e32 v115, vcc, 0, v113, vcc
	v_mov_b64_e32 v[116:117], v[178:179]
	v_mov_b64_e32 v[118:119], v[180:181]
	v_pk_mul_f32 v[98:99], v[98:99], v[140:141]
	s_mov_b64 s[36:37], -1
	s_and_b64 vcc, exec, s[16:17]
	s_waitcnt lgkmcnt(0)
	v_mov_b32_e32 v114, v118
	v_mov_b32_e32 v115, v119
	v_mov_b64_e32 v[118:119], v[234:235]
	v_mov_b64_e32 v[120:121], v[236:237]
	v_permlane32_swap_b32_e32 v116, v114
	v_permlane32_swap_b32_e32 v117, v115
	v_lshlrev_b32_e32 v122, 16, v116
	v_and_b32_e32 v123, 0xffff0000, v116
	v_lshlrev_b32_e32 v116, 16, v117
	v_and_b32_e32 v117, 0xffff0000, v117
	s_nop 0
	v_pk_fma_f32 v[96:97], v[96:97], v[118:119], v[122:123]
	v_pk_fma_f32 v[98:99], v[98:99], v[120:121], v[116:117]
	s_cbranch_vccnz .LBB0_864
	v_lshl_add_u64 v[116:117], v[128:129], 2, v[142:143]
	v_lshl_add_u64 v[116:117], v[116:117], 0, v[192:193]
	s_mov_b64 s[36:37], 0
	global_store_dwordx4 v[116:117], v[96:99], off offset:128

.LBB0_866:
	v_mov_b64_e32 v[116:117], v[238:239]
	v_mov_b64_e32 v[118:119], v[240:241]
	v_lshlrev_b32_e32 v120, 16, v114
	v_and_b32_e32 v121, 0xffff0000, v114
	v_lshlrev_b32_e32 v114, 16, v115
	v_and_b32_e32 v115, 0xffff0000, v115
	v_pk_mul_f32 v[100:101], v[100:101], v[140:141]
	v_pk_mul_f32 v[102:103], v[102:103], v[140:141]
	s_mov_b64 s[36:37], -1
	s_and_b64 vcc, exec, s[16:17]
	s_nop 0
	v_pk_fma_f32 v[100:101], v[100:101], v[116:117], v[120:121]
	v_pk_fma_f32 v[102:103], v[102:103], v[118:119], v[114:115]
	s_cbranch_vccnz .LBB0_989
	v_lshl_add_u64 v[114:115], v[128:129], 2, v[142:143]
	v_lshl_add_u64 v[114:115], v[114:115], 0, v[192:193]
	global_store_dwordx4 v[114:115], v[100:103], off offset:160
	s_cbranch_execz .LBB0_990

.LBB0_870:
	v_mov_b32_e32 v133, v193
	v_lshl_add_u64 v[112:113], v[144:145], 0, v[132:133]
	v_add_co_u32_e32 v96, vcc, 0x1dc0000, v112
	v_mov_b64_e32 v[114:115], v[242:243]
	v_mov_b64_e32 v[116:117], v[244:245]
	s_nop 0
	v_addc_co_u32_e32 v97, vcc, 0, v113, vcc
	v_mov_b64_e32 v[96:97], v[182:183]
	v_mov_b64_e32 v[98:99], v[184:185]
	global_load_dwordx4 v[170:173], v[190:191], off
	global_load_dwordx4 v[174:177], v[190:191], off offset:32
	global_load_dwordx4 v[178:181], v[190:191], off offset:64
	global_load_dwordx4 v[182:185], v[190:191], off offset:96
	s_mov_b64 s[36:37], -1
	s_and_b64 vcc, exec, s[16:17]
	s_waitcnt lgkmcnt(0)
	v_mov_b32_e32 v100, v98
	v_mov_b32_e32 v101, v99
	s_nop 0
	v_permlane32_swap_b32_e32 v96, v100
	v_permlane32_swap_b32_e32 v97, v101
	v_lshlrev_b32_e32 v98, 16, v96
	v_and_b32_e32 v99, 0xffff0000, v96
	v_lshlrev_b32_e32 v102, 16, v97
	v_and_b32_e32 v103, 0xffff0000, v97
	v_pk_mul_f32 v[96:97], v[104:105], v[140:141]
	s_nop 0
	v_pk_fma_f32 v[96:97], v[96:97], v[114:115], v[98:99]
	v_pk_mul_f32 v[98:99], v[106:107], v[140:141]
	s_nop 0
	v_pk_fma_f32 v[98:99], v[98:99], v[116:117], v[102:103]
	s_cbranch_vccnz .LBB0_872
	v_lshl_add_u64 v[102:103], v[128:129], 2, v[142:143]
	v_lshl_add_u64 v[102:103], v[102:103], 0, v[192:193]
	s_mov_b64 s[36:37], 0
	global_store_dwordx4 v[102:103], v[96:99], off offset:192

.LBB0_874:
	v_mov_b64_e32 v[102:103], v[246:247]
	v_mov_b64_e32 v[104:105], v[248:249]
	v_lshlrev_b32_e32 v106, 16, v100
	v_and_b32_e32 v107, 0xffff0000, v100
	v_lshlrev_b32_e32 v114, 16, v101
	v_and_b32_e32 v115, 0xffff0000, v101
	v_pk_mul_f32 v[100:101], v[108:109], v[140:141]
	v_pk_mul_f32 v[108:109], v[110:111], v[140:141]
	s_and_b64 vcc, exec, s[16:17]
	s_mov_b64 s[36:37], -1
	s_nop 0
	v_pk_fma_f32 v[100:101], v[100:101], v[102:103], v[106:107]
	v_pk_fma_f32 v[102:103], v[108:109], v[104:105], v[114:115]
	s_cbranch_vccnz .LBB0_991
	v_lshl_add_u64 v[104:105], v[128:129], 2, v[142:143]
	v_lshl_add_u64 v[104:105], v[104:105], 0, v[192:193]
	global_store_dwordx4 v[104:105], v[100:103], off offset:224
	s_cbranch_execz .LBB0_992

.LBB0_878:
	s_nop 1
	v_lshlrev_b64 v[98:99], 11, v[138:139]
	v_lshl_add_u64 v[98:99], s[26:27], 0, v[98:99]
	v_lshl_add_u64 v[98:99], v[128:129], 1, v[98:99]
	v_mov_b32_e32 v133, v193
	v_lshl_add_u64 v[102:103], v[98:99], 0, v[132:133]
	v_mov_b64_e32 v[108:109], v[218:219]
	v_mov_b64_e32 v[110:111], v[220:221]
	ds_read_b32 v96, v154 offset:2176
	s_mov_b32 s31, 0x800000
	v_readlane_b32 s40, v252, 2
	v_lshlrev_b64 v[100:101], 10, v[138:139]
	v_readlane_b32 s41, v252, 3
	s_waitcnt lgkmcnt(0)
	v_fmamk_f32 v96, v96, 0x3a800000, v224
	v_cmp_gt_f32_e32 vcc, s31, v96
	v_mul_f32_e32 v97, 0x4b800000, v96
	s_mov_b64 s[36:37], -1
	v_cndmask_b32_e32 v96, v96, v97, vcc
	v_rsq_f32_e32 v96, v96
	v_readlane_b32 s42, v252, 4
	v_readlane_b32 s43, v252, 5
	v_readlane_b32 s44, v252, 6
	v_mul_f32_e32 v97, 0x45800000, v96
	v_cndmask_b32_e32 v96, v96, v97, vcc
	v_pk_mul_f32 v[80:81], v[80:81], v[96:97] op_sel_hi:[1,0]
	v_pk_mul_f32 v[82:83], v[82:83], v[96:97] op_sel_hi:[1,0]
	s_and_b64 vcc, exec, s[16:17]
	v_readlane_b32 s45, v252, 7
	v_readlane_b32 s46, v252, 8
	v_readlane_b32 s47, v252, 9
	s_nop 0
	v_mov_b32_e32 v105, v110
	v_mov_b32_e32 v106, v111
	v_mov_b64_e32 v[110:111], v[202:203]
	v_mov_b64_e32 v[112:113], v[204:205]
	v_permlane32_swap_b32_e32 v108, v105
	v_permlane32_swap_b32_e32 v109, v106
	v_lshlrev_b32_e32 v98, 16, v108
	v_and_b32_e32 v99, 0xffff0000, v108
	v_lshlrev_b32_e32 v108, 16, v109
	v_and_b32_e32 v109, 0xffff0000, v109
	s_nop 0
	v_pk_fma_f32 v[80:81], v[110:111], v[80:81], v[98:99]
	v_pk_fma_f32 v[82:83], v[112:113], v[82:83], v[108:109]
	v_lshl_add_u64 v[98:99], v[100:101], 2, s[40:41]
	s_cbranch_vccnz .LBB0_880
	v_lshl_add_u64 v[108:109], v[128:129], 2, v[98:99]
	v_lshl_add_u64 v[108:109], v[108:109], 0, v[192:193]
	s_mov_b64 s[36:37], 0
	global_store_dwordx4 v[108:109], v[80:83], off

.LBB0_882:
	v_mov_b64_e32 v[108:109], v[206:207]
	v_mov_b64_e32 v[110:111], v[208:209]
	v_mov_b32_e32 v97, v96
	v_lshlrev_b32_e32 v112, 16, v105
	v_and_b32_e32 v113, 0xffff0000, v105
	v_lshlrev_b32_e32 v114, 16, v106
	v_and_b32_e32 v115, 0xffff0000, v106
	v_pk_mul_f32 v[84:85], v[84:85], v[96:97]
	v_pk_mul_f32 v[86:87], v[86:87], v[96:97]
	s_mov_b64 s[36:37], -1
	s_and_b64 vcc, exec, s[16:17]
	s_nop 0
	v_pk_fma_f32 v[84:85], v[84:85], v[108:109], v[112:113]
	v_pk_fma_f32 v[86:87], v[86:87], v[110:111], v[114:115]
	s_cbranch_vccnz .LBB0_993
	v_lshl_add_u64 v[106:107], v[128:129], 2, v[98:99]
	v_lshl_add_u64 v[106:107], v[106:107], 0, v[192:193]
	global_store_dwordx4 v[106:107], v[84:87], off offset:32
	s_cbranch_execz .LBB0_994

.LBB0_886:
	s_nop 1
	v_lshl_add_u64 v[80:81], v[100:101], 1, s[0:1]
	v_lshl_add_u64 v[100:101], v[128:129], 1, v[80:81]
	v_mov_b32_e32 v133, v193
	v_lshl_add_u64 v[102:103], v[100:101], 0, v[132:133]
	v_add_co_u32_e32 v80, vcc, 0x1dc0000, v102
	v_mov_b64_e32 v[106:107], v[210:211]
	v_mov_b64_e32 v[108:109], v[212:213]
	s_nop 0
	v_addc_co_u32_e32 v81, vcc, 0, v103, vcc
	v_mov_b64_e32 v[80:81], v[228:229]
	v_mov_b64_e32 v[82:83], v[230:231]
	s_mov_b64 s[36:37], -1
	s_and_b64 vcc, exec, s[16:17]
	s_waitcnt lgkmcnt(0)
	v_mov_b32_e32 v84, v82
	v_mov_b32_e32 v85, v83
	s_nop 0
	v_permlane32_swap_b32_e32 v80, v84
	v_permlane32_swap_b32_e32 v81, v85
	v_lshlrev_b32_e32 v82, 16, v80
	v_and_b32_e32 v83, 0xffff0000, v80
	v_lshlrev_b32_e32 v86, 16, v81
	v_and_b32_e32 v87, 0xffff0000, v81
	v_pk_mul_f32 v[80:81], v[88:89], v[96:97]
	s_nop 0
	v_pk_fma_f32 v[80:81], v[80:81], v[106:107], v[82:83]
	v_pk_mul_f32 v[82:83], v[90:91], v[96:97]
	s_nop 0
	v_pk_fma_f32 v[82:83], v[82:83], v[108:109], v[86:87]
	s_cbranch_vccnz .LBB0_888
	v_lshl_add_u64 v[86:87], v[128:129], 2, v[98:99]
	v_lshl_add_u64 v[86:87], v[86:87], 0, v[192:193]
	s_mov_b64 s[36:37], 0
	global_store_dwordx4 v[86:87], v[80:83], off offset:64

.LBB0_890:
	v_mov_b64_e32 v[86:87], v[214:215]
	v_mov_b64_e32 v[88:89], v[216:217]
	v_lshlrev_b32_e32 v90, 16, v84
	v_and_b32_e32 v91, 0xffff0000, v84
	v_lshlrev_b32_e32 v106, 16, v85
	v_and_b32_e32 v107, 0xffff0000, v85
	v_pk_mul_f32 v[84:85], v[92:93], v[96:97]
	v_pk_mul_f32 v[92:93], v[94:95], v[96:97]
	s_and_b64 vcc, exec, s[16:17]
	s_mov_b64 s[36:37], -1
	s_nop 0
	v_pk_fma_f32 v[84:85], v[84:85], v[86:87], v[90:91]
	v_pk_fma_f32 v[86:87], v[92:93], v[88:89], v[106:107]
	s_cbranch_vccnz .LBB0_995
	v_lshl_add_u64 v[88:89], v[128:129], 2, v[98:99]
	v_lshl_add_u64 v[88:89], v[88:89], 0, v[192:193]
	global_store_dwordx4 v[88:89], v[84:87], off offset:96
	s_cbranch_execz .LBB0_996

.LBB0_894:
	v_mov_b32_e32 v133, v193
	s_nop 0
	v_lshl_add_u64 v[80:81], v[100:101], 0, v[132:133]
	v_add_co_u32_e32 v82, vcc, 0x1dc0000, v80
	v_pk_mul_f32 v[64:65], v[64:65], v[96:97]
	s_nop 0
	v_addc_co_u32_e32 v83, vcc, 0, v81, vcc
	v_mov_b64_e32 v[84:85], v[186:187]
	v_mov_b64_e32 v[86:87], v[188:189]
	v_pk_mul_f32 v[66:67], v[66:67], v[96:97]
	s_mov_b64 s[36:37], -1
	s_and_b64 vcc, exec, s[16:17]
	s_waitcnt lgkmcnt(0)
	v_mov_b32_e32 v82, v86
	v_mov_b32_e32 v83, v87
	v_mov_b64_e32 v[86:87], v[234:235]
	v_mov_b64_e32 v[88:89], v[236:237]
	v_permlane32_swap_b32_e32 v84, v82
	v_permlane32_swap_b32_e32 v85, v83
	v_lshlrev_b32_e32 v90, 16, v84
	v_and_b32_e32 v91, 0xffff0000, v84
	v_lshlrev_b32_e32 v84, 16, v85
	v_and_b32_e32 v85, 0xffff0000, v85
	s_nop 0
	v_pk_fma_f32 v[64:65], v[64:65], v[86:87], v[90:91]
	v_pk_fma_f32 v[66:67], v[66:67], v[88:89], v[84:85]
	s_cbranch_vccnz .LBB0_896
	v_lshl_add_u64 v[84:85], v[128:129], 2, v[98:99]
	v_lshl_add_u64 v[84:85], v[84:85], 0, v[192:193]
	s_mov_b64 s[36:37], 0
	global_store_dwordx4 v[84:85], v[64:67], off offset:128

.LBB0_898:
	v_mov_b64_e32 v[84:85], v[238:239]
	v_mov_b64_e32 v[86:87], v[240:241]
	v_lshlrev_b32_e32 v88, 16, v82
	v_and_b32_e32 v89, 0xffff0000, v82
	v_lshlrev_b32_e32 v82, 16, v83
	v_and_b32_e32 v83, 0xffff0000, v83
	v_pk_mul_f32 v[68:69], v[68:69], v[96:97]
	v_pk_mul_f32 v[70:71], v[70:71], v[96:97]
	s_mov_b64 s[36:37], -1
	s_and_b64 vcc, exec, s[16:17]
	s_nop 0
	v_pk_fma_f32 v[68:69], v[68:69], v[84:85], v[88:89]
	v_pk_fma_f32 v[70:71], v[70:71], v[86:87], v[82:83]
	s_cbranch_vccnz .LBB0_997
	v_lshl_add_u64 v[82:83], v[128:129], 2, v[98:99]
	v_lshl_add_u64 v[82:83], v[82:83], 0, v[192:193]
	global_store_dwordx4 v[82:83], v[68:71], off offset:160
	s_cbranch_execz .LBB0_998

.LBB0_902:
	v_mov_b32_e32 v133, v193
	v_lshl_add_u64 v[80:81], v[100:101], 0, v[132:133]
	v_add_co_u32_e32 v64, vcc, 0x1dc0000, v80
	v_mov_b64_e32 v[82:83], v[242:243]
	v_mov_b64_e32 v[84:85], v[244:245]
	s_nop 0
	v_addc_co_u32_e32 v65, vcc, 0, v81, vcc
	v_mov_b64_e32 v[64:65], v[198:199]
	v_mov_b64_e32 v[66:67], v[200:201]
	global_load_dwordx4 v[218:221], v[164:165], off
	global_load_dwordx4 v[228:231], v[164:165], off offset:32
	global_load_dwordx4 v[186:189], v[164:165], off offset:64
	global_load_dwordx4 v[198:201], v[164:165], off offset:96
	s_mov_b64 s[36:37], -1
	s_and_b64 vcc, exec, s[16:17]
	s_waitcnt lgkmcnt(0)
	v_mov_b32_e32 v68, v66
	v_mov_b32_e32 v69, v67
	s_nop 0
	v_permlane32_swap_b32_e32 v64, v68
	v_permlane32_swap_b32_e32 v65, v69
	v_lshlrev_b32_e32 v66, 16, v64
	v_and_b32_e32 v67, 0xffff0000, v64
	v_lshlrev_b32_e32 v70, 16, v65
	v_and_b32_e32 v71, 0xffff0000, v65
	v_pk_mul_f32 v[64:65], v[72:73], v[96:97]
	s_nop 0
	v_pk_fma_f32 v[64:65], v[64:65], v[82:83], v[66:67]
	v_pk_mul_f32 v[66:67], v[74:75], v[96:97]
	s_nop 0
	v_pk_fma_f32 v[66:67], v[66:67], v[84:85], v[70:71]
	s_cbranch_vccnz .LBB0_904
	v_lshl_add_u64 v[70:71], v[128:129], 2, v[98:99]
	v_lshl_add_u64 v[70:71], v[70:71], 0, v[192:193]
	s_mov_b64 s[36:37], 0
	global_store_dwordx4 v[70:71], v[64:67], off offset:192

.LBB0_906:
	v_mov_b64_e32 v[70:71], v[246:247]
	v_mov_b64_e32 v[72:73], v[248:249]
	v_lshlrev_b32_e32 v74, 16, v68
	v_and_b32_e32 v75, 0xffff0000, v68
	v_lshlrev_b32_e32 v82, 16, v69
	v_and_b32_e32 v83, 0xffff0000, v69
	v_pk_mul_f32 v[68:69], v[76:77], v[96:97]
	v_pk_mul_f32 v[76:77], v[78:79], v[96:97]
	s_and_b64 vcc, exec, s[16:17]
	s_mov_b64 s[36:37], -1
	s_nop 0
	v_pk_fma_f32 v[68:69], v[68:69], v[70:71], v[74:75]
	v_pk_fma_f32 v[70:71], v[76:77], v[72:73], v[82:83]
	s_cbranch_vccnz .LBB0_999
	v_lshl_add_u64 v[72:73], v[128:129], 2, v[98:99]
	v_lshl_add_u64 v[72:73], v[72:73], 0, v[192:193]
	global_store_dwordx4 v[72:73], v[68:71], off offset:224
	s_cbranch_execz .LBB0_1000

.LBB0_910:
	s_nop 1
	v_lshlrev_b64 v[66:67], 11, v[136:137]
	v_lshl_add_u64 v[66:67], s[26:27], 0, v[66:67]
	v_lshl_add_u64 v[66:67], v[128:129], 1, v[66:67]
	v_mov_b32_e32 v133, v193
	v_lshl_add_u64 v[70:71], v[66:67], 0, v[132:133]
	s_waitcnt vmcnt(6)
	v_mov_b64_e32 v[76:77], v[170:171]
	v_mov_b64_e32 v[78:79], v[172:173]
	ds_read_b32 v64, v154 offset:2304
	v_readlane_b32 s40, v252, 2
	v_lshlrev_b64 v[68:69], 10, v[136:137]
	v_readlane_b32 s41, v252, 3
	s_mov_b64 s[36:37], -1
	s_waitcnt lgkmcnt(0)
	v_fmamk_f32 v64, v64, 0x3a800000, v224
	v_cmp_gt_f32_e32 vcc, s31, v64
	v_mul_f32_e32 v65, 0x4b800000, v64
	v_readlane_b32 s42, v252, 4
	v_cndmask_b32_e32 v64, v64, v65, vcc
	v_rsq_f32_e32 v64, v64
	v_readlane_b32 s43, v252, 5
	v_readlane_b32 s44, v252, 6
	v_readlane_b32 s45, v252, 7
	v_mul_f32_e32 v65, 0x45800000, v64
	v_cndmask_b32_e32 v64, v64, v65, vcc
	v_pk_mul_f32 v[48:49], v[48:49], v[64:65] op_sel_hi:[1,0]
	v_pk_mul_f32 v[50:51], v[50:51], v[64:65] op_sel_hi:[1,0]
	s_and_b64 vcc, exec, s[16:17]
	v_readlane_b32 s46, v252, 8
	v_readlane_b32 s47, v252, 9
	s_nop 0
	v_mov_b32_e32 v73, v78
	v_mov_b32_e32 v74, v79
	v_mov_b64_e32 v[78:79], v[202:203]
	v_mov_b64_e32 v[80:81], v[204:205]
	v_permlane32_swap_b32_e32 v76, v73
	v_permlane32_swap_b32_e32 v77, v74
	v_lshlrev_b32_e32 v66, 16, v76
	v_and_b32_e32 v67, 0xffff0000, v76
	v_lshlrev_b32_e32 v76, 16, v77
	v_and_b32_e32 v77, 0xffff0000, v77
	s_nop 0
	v_pk_fma_f32 v[48:49], v[78:79], v[48:49], v[66:67]
	v_pk_fma_f32 v[50:51], v[80:81], v[50:51], v[76:77]
	v_lshl_add_u64 v[66:67], v[68:69], 2, s[40:41]
	s_cbranch_vccnz .LBB0_912
	v_lshl_add_u64 v[76:77], v[128:129], 2, v[66:67]
	v_lshl_add_u64 v[76:77], v[76:77], 0, v[192:193]
	s_mov_b64 s[36:37], 0
	global_store_dwordx4 v[76:77], v[48:51], off

.LBB0_914:
	v_mov_b64_e32 v[76:77], v[206:207]
	v_mov_b64_e32 v[78:79], v[208:209]
	v_mov_b32_e32 v65, v64
	v_lshlrev_b32_e32 v80, 16, v73
	v_and_b32_e32 v81, 0xffff0000, v73
	v_lshlrev_b32_e32 v82, 16, v74
	v_and_b32_e32 v83, 0xffff0000, v74
	v_pk_mul_f32 v[52:53], v[52:53], v[64:65]
	v_pk_mul_f32 v[54:55], v[54:55], v[64:65]
	s_mov_b64 s[36:37], -1
	s_and_b64 vcc, exec, s[16:17]
	s_nop 0
	v_pk_fma_f32 v[52:53], v[52:53], v[76:77], v[80:81]
	v_pk_fma_f32 v[54:55], v[54:55], v[78:79], v[82:83]
	s_cbranch_vccnz .LBB0_1001
	v_lshl_add_u64 v[74:75], v[128:129], 2, v[66:67]
	v_lshl_add_u64 v[74:75], v[74:75], 0, v[192:193]
	global_store_dwordx4 v[74:75], v[52:55], off offset:32
	s_cbranch_execz .LBB0_1002

.LBB0_918:
	s_nop 1
	v_lshl_add_u64 v[48:49], v[68:69], 1, s[0:1]
	v_lshl_add_u64 v[68:69], v[128:129], 1, v[48:49]
	v_mov_b32_e32 v133, v193
	v_lshl_add_u64 v[70:71], v[68:69], 0, v[132:133]
	v_add_co_u32_e32 v48, vcc, 0x1dc0000, v70
	v_mov_b64_e32 v[74:75], v[210:211]
	v_mov_b64_e32 v[76:77], v[212:213]
	s_nop 0
	v_addc_co_u32_e32 v49, vcc, 0, v71, vcc
	v_mov_b64_e32 v[48:49], v[174:175]
	v_mov_b64_e32 v[50:51], v[176:177]
	s_mov_b64 s[36:37], -1
	s_and_b64 vcc, exec, s[16:17]
	s_waitcnt lgkmcnt(0)
	v_mov_b32_e32 v52, v50
	v_mov_b32_e32 v53, v51
	s_nop 0
	v_permlane32_swap_b32_e32 v48, v52
	v_permlane32_swap_b32_e32 v49, v53
	v_lshlrev_b32_e32 v50, 16, v48
	v_and_b32_e32 v51, 0xffff0000, v48
	v_lshlrev_b32_e32 v54, 16, v49
	v_and_b32_e32 v55, 0xffff0000, v49
	v_pk_mul_f32 v[48:49], v[56:57], v[64:65]
	s_nop 0
	v_pk_fma_f32 v[48:49], v[48:49], v[74:75], v[50:51]
	v_pk_mul_f32 v[50:51], v[58:59], v[64:65]
	s_nop 0
	v_pk_fma_f32 v[50:51], v[50:51], v[76:77], v[54:55]
	s_cbranch_vccnz .LBB0_920
	v_lshl_add_u64 v[54:55], v[128:129], 2, v[66:67]
	v_lshl_add_u64 v[54:55], v[54:55], 0, v[192:193]
	s_mov_b64 s[36:37], 0
	global_store_dwordx4 v[54:55], v[48:51], off offset:64

.LBB0_922:
	v_mov_b64_e32 v[54:55], v[214:215]
	v_mov_b64_e32 v[56:57], v[216:217]
	v_lshlrev_b32_e32 v58, 16, v52
	v_and_b32_e32 v59, 0xffff0000, v52
	v_lshlrev_b32_e32 v74, 16, v53
	v_and_b32_e32 v75, 0xffff0000, v53
	v_pk_mul_f32 v[52:53], v[60:61], v[64:65]
	v_pk_mul_f32 v[60:61], v[62:63], v[64:65]
	s_and_b64 vcc, exec, s[16:17]
	s_mov_b64 s[36:37], -1
	s_nop 0
	v_pk_fma_f32 v[52:53], v[52:53], v[54:55], v[58:59]
	v_pk_fma_f32 v[54:55], v[60:61], v[56:57], v[74:75]
	s_cbranch_vccnz .LBB0_1003
	v_lshl_add_u64 v[56:57], v[128:129], 2, v[66:67]
	v_lshl_add_u64 v[56:57], v[56:57], 0, v[192:193]
	global_store_dwordx4 v[56:57], v[52:55], off offset:96
	s_cbranch_execz .LBB0_1004

.LBB0_926:
	v_mov_b32_e32 v133, v193
	s_nop 0
	v_lshl_add_u64 v[48:49], v[68:69], 0, v[132:133]
	v_add_co_u32_e32 v50, vcc, 0x1dc0000, v48
	v_pk_mul_f32 v[32:33], v[32:33], v[64:65]
	s_nop 0
	v_addc_co_u32_e32 v51, vcc, 0, v49, vcc
	v_mov_b64_e32 v[52:53], v[178:179]
	v_mov_b64_e32 v[54:55], v[180:181]
	v_pk_mul_f32 v[34:35], v[34:35], v[64:65]
	s_mov_b64 s[36:37], -1
	s_and_b64 vcc, exec, s[16:17]
	s_waitcnt lgkmcnt(0)
	v_mov_b32_e32 v50, v54
	v_mov_b32_e32 v51, v55
	v_mov_b64_e32 v[54:55], v[234:235]
	v_mov_b64_e32 v[56:57], v[236:237]
	v_permlane32_swap_b32_e32 v52, v50
	v_permlane32_swap_b32_e32 v53, v51
	v_lshlrev_b32_e32 v58, 16, v52
	v_and_b32_e32 v59, 0xffff0000, v52
	v_lshlrev_b32_e32 v52, 16, v53
	v_and_b32_e32 v53, 0xffff0000, v53
	s_nop 0
	v_pk_fma_f32 v[32:33], v[32:33], v[54:55], v[58:59]
	v_pk_fma_f32 v[34:35], v[34:35], v[56:57], v[52:53]
	s_cbranch_vccnz .LBB0_928
	v_lshl_add_u64 v[52:53], v[128:129], 2, v[66:67]
	v_lshl_add_u64 v[52:53], v[52:53], 0, v[192:193]
	s_mov_b64 s[36:37], 0
	global_store_dwordx4 v[52:53], v[32:35], off offset:128

.LBB0_930:
	v_mov_b64_e32 v[52:53], v[238:239]
	v_mov_b64_e32 v[54:55], v[240:241]
	v_lshlrev_b32_e32 v56, 16, v50
	v_and_b32_e32 v57, 0xffff0000, v50
	v_lshlrev_b32_e32 v50, 16, v51
	v_and_b32_e32 v51, 0xffff0000, v51
	v_pk_mul_f32 v[36:37], v[36:37], v[64:65]
	v_pk_mul_f32 v[38:39], v[38:39], v[64:65]
	s_mov_b64 s[36:37], -1
	s_and_b64 vcc, exec, s[16:17]
	s_nop 0
	v_pk_fma_f32 v[36:37], v[36:37], v[52:53], v[56:57]
	v_pk_fma_f32 v[38:39], v[38:39], v[54:55], v[50:51]
	s_cbranch_vccnz .LBB0_1005
	v_lshl_add_u64 v[50:51], v[128:129], 2, v[66:67]
	v_lshl_add_u64 v[50:51], v[50:51], 0, v[192:193]
	global_store_dwordx4 v[50:51], v[36:39], off offset:160
	s_cbranch_execz .LBB0_1006

.LBB0_934:
	v_mov_b32_e32 v133, v193
	v_lshl_add_u64 v[48:49], v[68:69], 0, v[132:133]
	v_add_co_u32_e32 v32, vcc, 0x1dc0000, v48
	v_mov_b64_e32 v[50:51], v[242:243]
	v_mov_b64_e32 v[52:53], v[244:245]
	s_nop 0
	v_addc_co_u32_e32 v33, vcc, 0, v49, vcc
	v_mov_b64_e32 v[32:33], v[182:183]
	v_mov_b64_e32 v[34:35], v[184:185]
	s_mov_b64 s[36:37], -1
	s_and_b64 vcc, exec, s[16:17]
	s_waitcnt lgkmcnt(0)
	v_mov_b32_e32 v36, v34
	v_mov_b32_e32 v37, v35
	s_nop 0
	v_permlane32_swap_b32_e32 v32, v36
	v_permlane32_swap_b32_e32 v33, v37
	v_lshlrev_b32_e32 v34, 16, v32
	v_and_b32_e32 v35, 0xffff0000, v32
	v_lshlrev_b32_e32 v38, 16, v33
	v_and_b32_e32 v39, 0xffff0000, v33
	v_pk_mul_f32 v[32:33], v[40:41], v[64:65]
	s_nop 0
	v_pk_fma_f32 v[32:33], v[32:33], v[50:51], v[34:35]
	v_pk_mul_f32 v[34:35], v[42:43], v[64:65]
	s_nop 0
	v_pk_fma_f32 v[34:35], v[34:35], v[52:53], v[38:39]
	s_cbranch_vccnz .LBB0_936
	v_lshl_add_u64 v[38:39], v[128:129], 2, v[66:67]
	v_lshl_add_u64 v[38:39], v[38:39], 0, v[192:193]
	s_mov_b64 s[36:37], 0
	global_store_dwordx4 v[38:39], v[32:35], off offset:192

.LBB0_938:
	v_mov_b64_e32 v[38:39], v[246:247]
	v_mov_b64_e32 v[40:41], v[248:249]
	v_lshlrev_b32_e32 v42, 16, v36
	v_and_b32_e32 v43, 0xffff0000, v36
	v_lshlrev_b32_e32 v50, 16, v37
	v_and_b32_e32 v51, 0xffff0000, v37
	v_pk_mul_f32 v[36:37], v[44:45], v[64:65]
	v_pk_mul_f32 v[44:45], v[46:47], v[64:65]
	s_and_b64 vcc, exec, s[16:17]
	s_mov_b64 s[36:37], -1
	s_nop 0
	v_pk_fma_f32 v[36:37], v[36:37], v[38:39], v[42:43]
	v_pk_fma_f32 v[38:39], v[44:45], v[40:41], v[50:51]
	s_cbranch_vccnz .LBB0_1007
	v_lshl_add_u64 v[40:41], v[128:129], 2, v[66:67]
	v_lshl_add_u64 v[40:41], v[40:41], 0, v[192:193]
	global_store_dwordx4 v[40:41], v[36:39], off offset:224
	s_cbranch_execz .LBB0_1008

.LBB0_942:
	s_nop 1
	v_lshlrev_b64 v[34:35], 11, v[134:135]
	v_lshl_add_u64 v[34:35], s[26:27], 0, v[34:35]
	v_lshl_add_u64 v[34:35], v[128:129], 1, v[34:35]
	v_mov_b32_e32 v133, v193
	v_lshl_add_u64 v[38:39], v[34:35], 0, v[132:133]
	s_waitcnt vmcnt(4)
	v_mov_b64_e32 v[44:45], v[218:219]
	v_mov_b64_e32 v[46:47], v[220:221]
	ds_read_b32 v32, v154 offset:2432
	v_readlane_b32 s40, v252, 2
	v_lshlrev_b64 v[36:37], 10, v[134:135]
	v_readlane_b32 s41, v252, 3
	s_mov_b64 s[36:37], -1
	s_waitcnt lgkmcnt(0)
	v_fmamk_f32 v32, v32, 0x3a800000, v224
	v_cmp_gt_f32_e32 vcc, s31, v32
	v_mul_f32_e32 v33, 0x4b800000, v32
	v_readlane_b32 s42, v252, 4
	v_cndmask_b32_e32 v32, v32, v33, vcc
	v_rsq_f32_e32 v32, v32
	v_readlane_b32 s43, v252, 5
	v_readlane_b32 s44, v252, 6
	v_readlane_b32 s45, v252, 7
	v_mul_f32_e32 v33, 0x45800000, v32
	v_cndmask_b32_e32 v32, v32, v33, vcc
	v_pk_mul_f32 v[16:17], v[16:17], v[32:33] op_sel_hi:[1,0]
	v_pk_mul_f32 v[18:19], v[18:19], v[32:33] op_sel_hi:[1,0]
	s_and_b64 vcc, exec, s[16:17]
	v_readlane_b32 s46, v252, 8
	v_readlane_b32 s47, v252, 9
	s_nop 0
	v_mov_b32_e32 v41, v46
	v_mov_b32_e32 v42, v47
	v_mov_b64_e32 v[46:47], v[202:203]
	v_mov_b64_e32 v[48:49], v[204:205]
	v_permlane32_swap_b32_e32 v44, v41
	v_permlane32_swap_b32_e32 v45, v42
	v_lshlrev_b32_e32 v34, 16, v44
	v_and_b32_e32 v35, 0xffff0000, v44
	v_lshlrev_b32_e32 v44, 16, v45
	v_and_b32_e32 v45, 0xffff0000, v45
	s_nop 0
	v_pk_fma_f32 v[16:17], v[46:47], v[16:17], v[34:35]
	v_pk_fma_f32 v[18:19], v[48:49], v[18:19], v[44:45]
	v_lshl_add_u64 v[34:35], v[36:37], 2, s[40:41]
	s_cbranch_vccnz .LBB0_944
	v_lshl_add_u64 v[44:45], v[128:129], 2, v[34:35]
	v_lshl_add_u64 v[44:45], v[44:45], 0, v[192:193]
	s_mov_b64 s[36:37], 0
	global_store_dwordx4 v[44:45], v[16:19], off

.LBB0_946:
	v_mov_b64_e32 v[44:45], v[206:207]
	v_mov_b64_e32 v[46:47], v[208:209]
	v_mov_b32_e32 v33, v32
	v_lshlrev_b32_e32 v48, 16, v41
	v_and_b32_e32 v49, 0xffff0000, v41
	v_lshlrev_b32_e32 v50, 16, v42
	v_and_b32_e32 v51, 0xffff0000, v42
	v_pk_mul_f32 v[20:21], v[20:21], v[32:33]
	v_pk_mul_f32 v[22:23], v[22:23], v[32:33]
	s_mov_b64 s[36:37], -1
	s_and_b64 vcc, exec, s[16:17]
	s_nop 0
	v_pk_fma_f32 v[20:21], v[20:21], v[44:45], v[48:49]
	v_pk_fma_f32 v[22:23], v[22:23], v[46:47], v[50:51]
	s_cbranch_vccnz .LBB0_1009
	v_lshl_add_u64 v[42:43], v[128:129], 2, v[34:35]
	v_lshl_add_u64 v[42:43], v[42:43], 0, v[192:193]
	global_store_dwordx4 v[42:43], v[20:23], off offset:32
	s_cbranch_execz .LBB0_1010

.LBB0_950:
	s_nop 1
	v_lshl_add_u64 v[16:17], v[36:37], 1, s[0:1]
	v_lshl_add_u64 v[36:37], v[128:129], 1, v[16:17]
	v_mov_b32_e32 v133, v193
	v_lshl_add_u64 v[38:39], v[36:37], 0, v[132:133]
	v_add_co_u32_e32 v16, vcc, 0x1dc0000, v38
	v_mov_b64_e32 v[42:43], v[210:211]
	v_mov_b64_e32 v[44:45], v[212:213]
	s_nop 0
	v_addc_co_u32_e32 v17, vcc, 0, v39, vcc
	v_mov_b64_e32 v[16:17], v[228:229]
	v_mov_b64_e32 v[18:19], v[230:231]
	s_mov_b64 s[36:37], -1
	s_and_b64 vcc, exec, s[16:17]
	s_waitcnt lgkmcnt(0)
	v_mov_b32_e32 v20, v18
	v_mov_b32_e32 v21, v19
	s_nop 0
	v_permlane32_swap_b32_e32 v16, v20
	v_permlane32_swap_b32_e32 v17, v21
	v_lshlrev_b32_e32 v18, 16, v16
	v_and_b32_e32 v19, 0xffff0000, v16
	v_lshlrev_b32_e32 v22, 16, v17
	v_and_b32_e32 v23, 0xffff0000, v17
	v_pk_mul_f32 v[16:17], v[24:25], v[32:33]
	s_nop 0
	v_pk_fma_f32 v[16:17], v[16:17], v[42:43], v[18:19]
	v_pk_mul_f32 v[18:19], v[26:27], v[32:33]
	s_nop 0
	v_pk_fma_f32 v[18:19], v[18:19], v[44:45], v[22:23]
	s_cbranch_vccnz .LBB0_952
	v_lshl_add_u64 v[22:23], v[128:129], 2, v[34:35]
	v_lshl_add_u64 v[22:23], v[22:23], 0, v[192:193]
	s_mov_b64 s[36:37], 0
	global_store_dwordx4 v[22:23], v[16:19], off offset:64

.LBB0_954:
	v_mov_b64_e32 v[22:23], v[214:215]
	v_mov_b64_e32 v[24:25], v[216:217]
	v_lshlrev_b32_e32 v26, 16, v20
	v_and_b32_e32 v27, 0xffff0000, v20
	v_lshlrev_b32_e32 v42, 16, v21
	v_and_b32_e32 v43, 0xffff0000, v21
	v_pk_mul_f32 v[20:21], v[28:29], v[32:33]
	v_pk_mul_f32 v[28:29], v[30:31], v[32:33]
	s_and_b64 vcc, exec, s[16:17]
	s_mov_b64 s[36:37], -1
	s_nop 0
	v_pk_fma_f32 v[20:21], v[20:21], v[22:23], v[26:27]
	v_pk_fma_f32 v[22:23], v[28:29], v[24:25], v[42:43]
	s_cbranch_vccnz .LBB0_1011
	v_lshl_add_u64 v[24:25], v[128:129], 2, v[34:35]
	v_lshl_add_u64 v[24:25], v[24:25], 0, v[192:193]
	global_store_dwordx4 v[24:25], v[20:23], off offset:96
	s_cbranch_execz .LBB0_1012

.LBB0_958:
	v_mov_b32_e32 v133, v193
	s_nop 0
	v_lshl_add_u64 v[16:17], v[36:37], 0, v[132:133]
	v_add_co_u32_e32 v18, vcc, 0x1dc0000, v16
	v_pk_mul_f32 v[0:1], v[0:1], v[32:33]
	s_nop 0
	v_addc_co_u32_e32 v19, vcc, 0, v17, vcc
	v_mov_b64_e32 v[20:21], v[186:187]
	v_mov_b64_e32 v[22:23], v[188:189]
	v_pk_mul_f32 v[2:3], v[2:3], v[32:33]
	s_mov_b64 s[36:37], -1
	s_and_b64 vcc, exec, s[16:17]
	s_waitcnt lgkmcnt(0)
	v_mov_b32_e32 v18, v22
	v_mov_b32_e32 v19, v23
	v_mov_b64_e32 v[22:23], v[234:235]
	v_mov_b64_e32 v[24:25], v[236:237]
	v_permlane32_swap_b32_e32 v20, v18
	v_permlane32_swap_b32_e32 v21, v19
	v_lshlrev_b32_e32 v26, 16, v20
	v_and_b32_e32 v27, 0xffff0000, v20
	v_lshlrev_b32_e32 v20, 16, v21
	v_and_b32_e32 v21, 0xffff0000, v21
	s_nop 0
	v_pk_fma_f32 v[0:1], v[0:1], v[22:23], v[26:27]
	v_pk_fma_f32 v[2:3], v[2:3], v[24:25], v[20:21]
	s_cbranch_vccnz .LBB0_960
	v_lshl_add_u64 v[20:21], v[128:129], 2, v[34:35]
	v_lshl_add_u64 v[20:21], v[20:21], 0, v[192:193]
	s_mov_b64 s[36:37], 0
	global_store_dwordx4 v[20:21], v[0:3], off offset:128

.LBB0_962:
	v_mov_b64_e32 v[20:21], v[238:239]
	v_mov_b64_e32 v[22:23], v[240:241]
	v_lshlrev_b32_e32 v24, 16, v18
	v_and_b32_e32 v25, 0xffff0000, v18
	v_lshlrev_b32_e32 v18, 16, v19
	v_and_b32_e32 v19, 0xffff0000, v19
	v_pk_mul_f32 v[4:5], v[4:5], v[32:33]
	v_pk_mul_f32 v[6:7], v[6:7], v[32:33]
	s_mov_b64 s[36:37], -1
	s_and_b64 vcc, exec, s[16:17]
	s_nop 0
	v_pk_fma_f32 v[4:5], v[4:5], v[20:21], v[24:25]
	v_pk_fma_f32 v[6:7], v[6:7], v[22:23], v[18:19]
	s_cbranch_vccnz .LBB0_1013
	v_lshl_add_u64 v[18:19], v[128:129], 2, v[34:35]
	v_lshl_add_u64 v[18:19], v[18:19], 0, v[192:193]
	global_store_dwordx4 v[18:19], v[4:7], off offset:160
	s_cbranch_execz .LBB0_1014

.LBB0_966:
	v_mov_b32_e32 v133, v193
	v_lshl_add_u64 v[16:17], v[36:37], 0, v[132:133]
	v_add_co_u32_e32 v0, vcc, 0x1dc0000, v16
	v_mov_b64_e32 v[18:19], v[242:243]
	v_mov_b64_e32 v[20:21], v[244:245]
	s_nop 0
	v_addc_co_u32_e32 v1, vcc, 0, v17, vcc
	v_mov_b64_e32 v[0:1], v[198:199]
	v_mov_b64_e32 v[2:3], v[200:201]
	s_mov_b64 s[36:37], -1
	s_and_b64 vcc, exec, s[16:17]
	s_waitcnt lgkmcnt(0)
	v_mov_b32_e32 v4, v2
	v_mov_b32_e32 v5, v3
	s_nop 0
	v_permlane32_swap_b32_e32 v0, v4
	v_permlane32_swap_b32_e32 v1, v5
	v_lshlrev_b32_e32 v2, 16, v0
	v_and_b32_e32 v3, 0xffff0000, v0
	v_lshlrev_b32_e32 v6, 16, v1
	v_and_b32_e32 v7, 0xffff0000, v1
	v_pk_mul_f32 v[0:1], v[8:9], v[32:33]
	s_nop 0
	v_pk_fma_f32 v[0:1], v[0:1], v[18:19], v[2:3]
	v_pk_mul_f32 v[2:3], v[10:11], v[32:33]
	s_nop 0
	v_pk_fma_f32 v[2:3], v[2:3], v[20:21], v[6:7]
	s_cbranch_vccnz .LBB0_968
	v_lshl_add_u64 v[6:7], v[128:129], 2, v[34:35]
	v_lshl_add_u64 v[6:7], v[6:7], 0, v[192:193]
	s_mov_b64 s[36:37], 0
	global_store_dwordx4 v[6:7], v[0:3], off offset:192

.LBB0_970:
	v_mov_b64_e32 v[6:7], v[246:247]
	v_mov_b64_e32 v[8:9], v[248:249]
	v_lshlrev_b32_e32 v10, 16, v4
	v_and_b32_e32 v11, 0xffff0000, v4
	v_lshlrev_b32_e32 v18, 16, v5
	v_and_b32_e32 v19, 0xffff0000, v5
	v_pk_mul_f32 v[4:5], v[12:13], v[32:33]
	v_pk_mul_f32 v[12:13], v[14:15], v[32:33]
	s_and_b64 vcc, exec, s[16:17]
	s_mov_b64 s[16:17], -1
	s_nop 0
	v_pk_fma_f32 v[4:5], v[4:5], v[6:7], v[10:11]
	v_pk_fma_f32 v[6:7], v[12:13], v[8:9], v[18:19]
	s_cbranch_vccnz .LBB0_1015
	v_lshl_add_u64 v[8:9], v[128:129], 2, v[34:35]
	v_lshl_add_u64 v[8:9], v[8:9], 0, v[192:193]
	global_store_dwordx4 v[8:9], v[4:7], off offset:224
	s_cbranch_execz .LBB0_1016

	.amdhsa_kernel _Z14fwd_megakernel6Params
		.amdhsa_group_segment_fixed_size 74768
		.amdhsa_private_segment_fixed_size 0
		.amdhsa_kernarg_size 408
		.amdhsa_user_sgpr_count 2
		.amdhsa_user_sgpr_dispatch_ptr 0
		.amdhsa_user_sgpr_queue_ptr 0
		.amdhsa_user_sgpr_kernarg_segment_ptr 1
		.amdhsa_user_sgpr_dispatch_id 0
		.amdhsa_user_sgpr_kernarg_preload_length 0
		.amdhsa_user_sgpr_kernarg_preload_offset 0
		.amdhsa_user_sgpr_private_segment_size 0
		.amdhsa_uses_dynamic_stack 0
		.amdhsa_enable_private_segment 0
		.amdhsa_system_sgpr_workgroup_id_x 1
		.amdhsa_system_sgpr_workgroup_id_y 0
		.amdhsa_system_sgpr_workgroup_id_z 0
		.amdhsa_system_sgpr_workgroup_info 0
		.amdhsa_system_vgpr_workitem_id 2
		.amdhsa_next_free_vgpr 256
		.amdhsa_next_free_sgpr 102
		.amdhsa_accum_offset 256
		.amdhsa_reserve_vcc 1
		.amdhsa_float_round_mode_32 0
		.amdhsa_float_round_mode_16_64 0
		.amdhsa_float_denorm_mode_32 3
		.amdhsa_float_denorm_mode_16_64 3
		.amdhsa_dx10_clamp 1
		.amdhsa_ieee_mode 1
		.amdhsa_fp16_overflow 0
		.amdhsa_tg_split 0
		.amdhsa_exception_fp_ieee_invalid_op 0
		.amdhsa_exception_fp_denorm_src 0
		.amdhsa_exception_fp_ieee_div_zero 0
		.amdhsa_exception_fp_ieee_overflow 0
		.amdhsa_exception_fp_ieee_underflow 0
		.amdhsa_exception_fp_ieee_inexact 0
		.amdhsa_exception_int_div_zero 0
	.end_amdhsa_kernel

amdhsa.kernels:
  - .agpr_count:     0
    .args:
      - .offset:         0
        .size:           152
        .value_kind:     by_value
      - .offset:         152
        .size:           4
        .value_kind:     hidden_block_count_x
      - .offset:         156
        .size:           4
        .value_kind:     hidden_block_count_y
      - .offset:         160
        .size:           4
        .value_kind:     hidden_block_count_z
      - .offset:         164
        .size:           2
        .value_kind:     hidden_group_size_x
      - .offset:         166
        .size:           2
        .value_kind:     hidden_group_size_y
      - .offset:         168
        .size:           2
        .value_kind:     hidden_group_size_z
      - .offset:         170
        .size:           2
        .value_kind:     hidden_remainder_x
      - .offset:         172
        .size:           2
        .value_kind:     hidden_remainder_y
      - .offset:         174
        .size:           2
        .value_kind:     hidden_remainder_z
      - .offset:         192
        .size:           8
        .value_kind:     hidden_global_offset_x
      - .offset:         200
        .size:           8
        .value_kind:     hidden_global_offset_y
      - .offset:         208
        .size:           8
        .value_kind:     hidden_global_offset_z
      - .offset:         216
        .size:           2
        .value_kind:     hidden_grid_dims
      - .offset:         240
        .size:           8
        .value_kind:     hidden_multigrid_sync_arg
    .group_segment_fixed_size: 74768
    .kernarg_segment_align: 8
    .kernarg_segment_size: 408
    .language:       OpenCL C
    .language_version:
      - 2
      - 0
    .max_flat_workgroup_size: 256
    .name:           _Z14fwd_megakernel6Params
    .private_segment_fixed_size: 0
    .sgpr_count:     108
    .sgpr_spill_count: 232
    .symbol:         _Z14fwd_megakernel6Params.kd
    .uniform_work_group_size: 1
    .uses_dynamic_stack: false
    .vgpr_count:     256
    .vgpr_spill_count: 0
    .wavefront_size: 64
